# SwiGLU and in-proj epilogues reuse cached per-row rms scales (load-free fast path for units after the first); cooperative-groups grid sync replaced by the kernel's XCD barrier; plus the scan-phase edi
# speedup vs baseline: 1.0484x; 1.0281x over previous
.LBB0_205:
	s_load_dwordx2 s[24:25], s[22:23], 0x4
	s_waitcnt lgkmcnt(0)
	s_mov_b64 s[6:7], s[0:1]
	s_getreg_b32 s3, hwreg(HW_REG_XCC_ID, 0, 4)
	s_waitcnt vmcnt(0)
	s_waitcnt vmcnt(0)
	s_barrier
	s_and_saveexec_b64 s[4:5], s[20:21]
	s_cbranch_execz .Lcgx_301
	s_add_i32 s8, 0, 0x23fc0
	v_mov_b32_e32 v0, s8
	s_load_dwordx2 s[6:7], s[6:7], 0x138
	s_waitcnt vmcnt(0) expcnt(0) lgkmcnt(0)
	ds_read_b32 v2, v0
	s_add_i32 s8, 0, 0x23fc4
	v_mov_b32_e32 v0, s8
	ds_read_b32 v0, v0
	s_and_b32 s3, s3, 15
	s_waitcnt lgkmcnt(1)
	v_cmp_ne_u32_e32 vcc, 0, v2
	s_cbranch_vccnz .Lcgx_265
	s_load_dword s8, s[22:23], 0x14
	s_mov_b32 s56, 1
	v_mov_b32_e32 v16, 0
	s_waitcnt lgkmcnt(0)
	s_lshr_b32 s10, s8, 16
	s_and_b32 s8, s8, 0xffff
	s_cmp_lg_u32 s8, 0
	s_cselect_b64 s[8:9], -1, 0
	s_cmp_lg_u64 s[8:9], 0
	s_addc_u32 s8, s24, 0
	s_cmp_lg_u32 s10, 0
	s_mul_i32 s57, s8, s33
	s_cselect_b64 s[8:9], -1, 0
	s_cmp_lg_u64 s[8:9], 0
	s_addc_u32 s8, s25, 0
	s_mul_i32 s57, s57, s8
	s_add_u32 s8, s6, 0x4200
	s_addc_u32 s9, s7, 0
	s_add_u32 s10, s6, 0x4400
	s_addc_u32 s11, s7, 0
	s_add_u32 s12, s6, 0x4500
	s_addc_u32 s13, s7, 0
	s_add_u32 s14, s6, 0x4600
	s_addc_u32 s15, s7, 0
	s_add_u32 s16, s6, 0x4700
	s_addc_u32 s17, s7, 0
	s_add_u32 s18, s6, 0x4800
	s_addc_u32 s19, s7, 0
	s_add_u32 s26, s6, 0x4900
	s_addc_u32 s27, s7, 0
	s_add_u32 s28, s6, 0x4a00
	s_addc_u32 s29, s7, 0
	s_add_u32 s30, s6, 0x4b00
	s_addc_u32 s31, s7, 0
	s_add_u32 s34, s6, 0x4c00
	s_addc_u32 s35, s7, 0
	s_add_u32 s36, s6, 0x4d00
	s_addc_u32 s37, s7, 0
	s_add_u32 s38, s6, 0x4e00
	s_addc_u32 s39, s7, 0
	s_add_u32 s40, s6, 0x4f00
	s_addc_u32 s41, s7, 0
	s_add_u32 s42, s6, 0x5000
	s_addc_u32 s43, s7, 0
	s_add_u32 s44, s6, 0x5100
	s_addc_u32 s45, s7, 0
	s_add_u32 s46, s6, 0x5200
	s_addc_u32 s47, s7, 0
	s_add_u32 s48, s6, 0x5300
	s_addc_u32 s49, s7, 0
	s_branch .Lcgx_253

.Lcgx_301:
	s_or_b64 exec, exec, s[4:5]
	s_waitcnt lgkmcnt(0)
	s_mov_b32 s100, 0
	s_mov_b64 s[4:5], s[0:1]
	s_mov_b64 s[8:9], s[0:1]
	s_mov_b32 s3, s33
	s_mov_b32 s40, s2
	s_barrier
	v_mov_b32_e32 v8, v154
	s_cmpk_lt_i32 s40, 0x2c0
	s_cselect_b64 s[10:11], -1, 0
	s_cmpk_gt_i32 s40, 0x2bf
	v_readfirstlane_b32 s12, v8
	s_cbranch_scc1 .LBB0_217
	s_ashr_i32 s6, s40, 31
	s_lshr_b32 s6, s6, 29
	s_add_i32 s6, s40, s6
	s_ashr_i32 s7, s6, 3
	s_and_b32 s6, s6, -8
	s_sub_i32 s6, s40, s6
	s_cmp_lt_i32 s6, 0
	s_movk_i32 s13, 0x59
	s_cselect_b32 s13, s13, 0x58
	s_mul_i32 s6, s13, s6
	s_add_i32 s6, s6, s7
	s_mul_hi_i32 s7, s6, 0x2e8ba2e9
	s_lshr_b32 s13, s7, 31
	s_ashr_i32 s7, s7, 4
	s_add_i32 s7, s7, s13
	s_lshl_b32 s13, s7, 3
	s_mulk_i32 s7, 0x58
	s_sub_i32 s6, s6, s7
	s_bfe_i32 s7, s6, 0x80000
	s_bfe_u32 s7, s7, 0x3000c
	s_add_i32 s7, s6, s7
	s_bfe_i32 s14, s7, 0x80000
	s_and_b32 s7, s7, 0xf8
	s_sub_i32 s6, s6, s7
	s_sext_i32_i16 s14, s14
	s_sext_i32_i8 s6, s6
	s_add_i32 s30, s13, s6
	s_ashr_i32 s6, s14, 3

.LBB0_229:
	s_add_i32 s101, s30, 1
	s_cmp_eq_u32 s100, s101
	s_cbranch_scc1 .Lip0_fast
	s_mov_b32 s100, s101
	v_mov_b32_e32 v146, v154
	s_mov_b64 s[34:35], s[0:1]
	s_load_dwordx2 s[36:37], s[34:35], 0x138
	v_and_or_b32 v144, v146, 15, s51
	v_lshl_add_u32 v144, s30, 8, v144
	v_ashrrev_i32_e32 v145, 31, v144
	v_mov_b32_e32 v148, 1.0
	s_waitcnt lgkmcnt(0)
	s_add_u32 s30, s36, 0x10000
	s_addc_u32 s31, s37, 0
	s_cmp_lg_u64 s[36:37], 0
	s_cselect_b64 s[34:35], -1, 0
	s_cmp_eq_u64 s[36:37], 0
	v_mov_b32_e32 v150, 1.0
	s_cbranch_scc1 .LBB0_231
	v_lshl_add_u64 v[158:159], v[144:145], 2, s[30:31]
	global_load_dword v145, v[158:159], off
	s_waitcnt vmcnt(0)
	v_fmamk_f32 v145, v145, 0x3a800000, v156
	v_rsq_f32_e32 v150, v145
.LBB0_231:
	s_lshl_b32 s6, s6, 8
	v_lshrrev_b32_e32 v145, 1, v146
	v_and_or_b32 v145, v145, 24, s6
	v_or_b32_e32 v146, s52, v145
	v_ashrrev_i32_e32 v147, 31, v146
	v_lshl_add_u64 v[146:147], v[146:147], 1, s[36:37]
	v_lshl_add_u64 v[146:147], v[146:147], 0, s[14:15]
	v_mov_b32_e32 v228, v150
	v_pk_mul_f32 v[126:127], v[126:127], v[150:151] op_sel_hi:[1,0]
	v_pk_mul_f32 v[124:125], v[124:125], v[150:151] op_sel_hi:[1,0]
	v_pk_mul_f32 v[160:161], v[122:123], v[150:151] op_sel_hi:[1,0]
	v_pk_mul_f32 v[122:123], v[120:121], v[150:151] op_sel_hi:[1,0]
	v_mad_i64_i32 v[158:159], s[6:7], v144, s60, v[146:147]
	v_cvt_pk_bf16_f32 v120, v124, v125
	v_cvt_pk_bf16_f32 v121, v126, v127
	v_cvt_pk_bf16_f32 v122, v122, v123
	v_cvt_pk_bf16_f32 v123, v160, v161
	global_store_dwordx4 v[158:159], v[120:123], off
	v_pk_mul_f32 v[118:119], v[118:119], v[150:151] op_sel_hi:[1,0]
	v_pk_mul_f32 v[116:117], v[116:117], v[150:151] op_sel_hi:[1,0]
	v_pk_mul_f32 v[120:121], v[114:115], v[150:151] op_sel_hi:[1,0]
	v_pk_mul_f32 v[114:115], v[112:113], v[150:151] op_sel_hi:[1,0]
	v_cvt_pk_bf16_f32 v112, v116, v117
	v_cvt_pk_bf16_f32 v113, v118, v119
	v_cvt_pk_bf16_f32 v114, v114, v115
	v_cvt_pk_bf16_f32 v115, v120, v121
	global_store_dwordx4 v[158:159], v[112:115], off offset:256
	s_andn2_b64 vcc, exec, s[34:35]
	s_nop 0
	v_or_b32_e32 v112, 16, v144
	v_cndmask_b32_e64 v113, 0, 1, s[34:35]
	v_cmp_ne_u32_e64 s[6:7], 1, v113
	v_ashrrev_i32_e32 v113, 31, v112
	s_cbranch_vccnz .LBB0_233
	v_lshl_add_u64 v[114:115], v[112:113], 2, s[30:31]
	global_load_dword v113, v[114:115], off
	s_waitcnt vmcnt(0)
	v_fmamk_f32 v113, v113, 0x3a800000, v156
	v_rsq_f32_e32 v148, v113
.LBB0_233:
	s_nop 0
	v_mov_b32_e32 v229, v148
	v_pk_mul_f32 v[110:111], v[110:111], v[148:149] op_sel_hi:[1,0]
	v_pk_mul_f32 v[108:109], v[108:109], v[148:149] op_sel_hi:[1,0]
	v_pk_mul_f32 v[114:115], v[106:107], v[148:149] op_sel_hi:[1,0]
	v_pk_mul_f32 v[106:107], v[104:105], v[148:149] op_sel_hi:[1,0]
	v_mad_i64_i32 v[112:113], s[34:35], v112, s60, v[146:147]
	v_cvt_pk_bf16_f32 v104, v108, v109
	v_cvt_pk_bf16_f32 v105, v110, v111
	v_cvt_pk_bf16_f32 v106, v106, v107
	v_cvt_pk_bf16_f32 v107, v114, v115
	global_store_dwordx4 v[112:113], v[104:107], off
	v_pk_mul_f32 v[102:103], v[102:103], v[148:149] op_sel_hi:[1,0]
	v_pk_mul_f32 v[100:101], v[100:101], v[148:149] op_sel_hi:[1,0]
	v_pk_mul_f32 v[104:105], v[98:99], v[148:149] op_sel_hi:[1,0]
	v_pk_mul_f32 v[98:99], v[96:97], v[148:149] op_sel_hi:[1,0]
	v_cvt_pk_bf16_f32 v96, v100, v101
	v_cvt_pk_bf16_f32 v97, v102, v103
	v_cvt_pk_bf16_f32 v98, v98, v99
	v_cvt_pk_bf16_f32 v99, v104, v105
	v_or_b32_e32 v100, 32, v144
	global_store_dwordx4 v[112:113], v[96:99], off offset:256
	v_ashrrev_i32_e32 v101, 31, v100
	s_and_b64 vcc, exec, s[6:7]
	v_mov_b32_e32 v96, 1.0
	v_mov_b32_e32 v98, 1.0
	s_cbranch_vccnz .LBB0_235
	v_lshl_add_u64 v[98:99], v[100:101], 2, s[30:31]
	global_load_dword v97, v[98:99], off
	s_waitcnt vmcnt(0)
	v_fmamk_f32 v97, v97, 0x3a800000, v156
	v_rsq_f32_e32 v98, v97
.LBB0_235:
	s_nop 0
	v_mov_b32_e32 v230, v98
	v_pk_mul_f32 v[94:95], v[94:95], v[98:99] op_sel_hi:[1,0]
	v_pk_mul_f32 v[92:93], v[92:93], v[98:99] op_sel_hi:[1,0]
	v_pk_mul_f32 v[102:103], v[90:91], v[98:99] op_sel_hi:[1,0]
	v_pk_mul_f32 v[90:91], v[88:89], v[98:99] op_sel_hi:[1,0]
	v_mad_i64_i32 v[100:101], s[34:35], v100, s60, v[146:147]
	v_cvt_pk_bf16_f32 v88, v92, v93
	v_cvt_pk_bf16_f32 v89, v94, v95
	v_cvt_pk_bf16_f32 v90, v90, v91
	v_cvt_pk_bf16_f32 v91, v102, v103
	global_store_dwordx4 v[100:101], v[88:91], off
	v_pk_mul_f32 v[86:87], v[86:87], v[98:99] op_sel_hi:[1,0]
	v_pk_mul_f32 v[84:85], v[84:85], v[98:99] op_sel_hi:[1,0]
	v_pk_mul_f32 v[88:89], v[82:83], v[98:99] op_sel_hi:[1,0]
	v_pk_mul_f32 v[82:83], v[80:81], v[98:99] op_sel_hi:[1,0]
	v_cvt_pk_bf16_f32 v80, v84, v85
	v_cvt_pk_bf16_f32 v81, v86, v87
	v_cvt_pk_bf16_f32 v82, v82, v83
	v_cvt_pk_bf16_f32 v83, v88, v89
	global_store_dwordx4 v[100:101], v[80:83], off offset:256
	s_and_b64 vcc, exec, s[6:7]
	s_nop 0
	v_or_b32_e32 v80, 48, v144
	v_ashrrev_i32_e32 v81, 31, v80
	s_cbranch_vccnz .LBB0_237
	v_lshl_add_u64 v[82:83], v[80:81], 2, s[30:31]
	global_load_dword v81, v[82:83], off
	s_waitcnt vmcnt(0)
	v_fmamk_f32 v81, v81, 0x3a800000, v156
	v_rsq_f32_e32 v96, v81
.LBB0_237:
	s_nop 0
	v_mov_b32_e32 v231, v96
	v_pk_mul_f32 v[78:79], v[78:79], v[96:97] op_sel_hi:[1,0]
	v_pk_mul_f32 v[76:77], v[76:77], v[96:97] op_sel_hi:[1,0]
	v_pk_mul_f32 v[82:83], v[74:75], v[96:97] op_sel_hi:[1,0]
	v_pk_mul_f32 v[74:75], v[72:73], v[96:97] op_sel_hi:[1,0]
	v_mad_i64_i32 v[80:81], s[34:35], v80, s60, v[146:147]
	v_cvt_pk_bf16_f32 v72, v76, v77
	v_cvt_pk_bf16_f32 v73, v78, v79
	v_cvt_pk_bf16_f32 v74, v74, v75
	v_cvt_pk_bf16_f32 v75, v82, v83
	global_store_dwordx4 v[80:81], v[72:75], off
	v_pk_mul_f32 v[70:71], v[70:71], v[96:97] op_sel_hi:[1,0]
	v_pk_mul_f32 v[68:69], v[68:69], v[96:97] op_sel_hi:[1,0]
	v_pk_mul_f32 v[72:73], v[66:67], v[96:97] op_sel_hi:[1,0]
	v_pk_mul_f32 v[66:67], v[64:65], v[96:97] op_sel_hi:[1,0]
	v_cvt_pk_bf16_f32 v64, v68, v69
	v_cvt_pk_bf16_f32 v65, v70, v71
	v_cvt_pk_bf16_f32 v66, v66, v67
	v_cvt_pk_bf16_f32 v67, v72, v73
	v_add_u32_e32 v68, 0x80, v144
	global_store_dwordx4 v[80:81], v[64:67], off offset:256
	v_ashrrev_i32_e32 v69, 31, v68
	s_and_b64 vcc, exec, s[6:7]
	v_mov_b32_e32 v64, 1.0
	v_mov_b32_e32 v66, 1.0
	s_cbranch_vccnz .LBB0_239
	v_lshl_add_u64 v[66:67], v[68:69], 2, s[30:31]
	global_load_dword v65, v[66:67], off
	s_waitcnt vmcnt(0)
	v_fmamk_f32 v65, v65, 0x3a800000, v156
	v_rsq_f32_e32 v66, v65
.LBB0_239:
	s_nop 0
	v_mov_b32_e32 v232, v66
	v_pk_mul_f32 v[62:63], v[62:63], v[66:67] op_sel_hi:[1,0]
	v_pk_mul_f32 v[60:61], v[60:61], v[66:67] op_sel_hi:[1,0]
	v_pk_mul_f32 v[70:71], v[58:59], v[66:67] op_sel_hi:[1,0]
	v_pk_mul_f32 v[58:59], v[56:57], v[66:67] op_sel_hi:[1,0]
	v_mad_i64_i32 v[68:69], s[34:35], v68, s60, v[146:147]
	v_cvt_pk_bf16_f32 v56, v60, v61
	v_cvt_pk_bf16_f32 v57, v62, v63
	v_cvt_pk_bf16_f32 v58, v58, v59
	v_cvt_pk_bf16_f32 v59, v70, v71
	global_store_dwordx4 v[68:69], v[56:59], off
	v_pk_mul_f32 v[54:55], v[54:55], v[66:67] op_sel_hi:[1,0]
	v_pk_mul_f32 v[52:53], v[52:53], v[66:67] op_sel_hi:[1,0]
	v_pk_mul_f32 v[56:57], v[50:51], v[66:67] op_sel_hi:[1,0]
	v_pk_mul_f32 v[50:51], v[48:49], v[66:67] op_sel_hi:[1,0]
	v_cvt_pk_bf16_f32 v48, v52, v53
	v_cvt_pk_bf16_f32 v49, v54, v55
	v_cvt_pk_bf16_f32 v50, v50, v51
	v_cvt_pk_bf16_f32 v51, v56, v57
	global_store_dwordx4 v[68:69], v[48:51], off offset:256
	s_and_b64 vcc, exec, s[6:7]
	s_nop 0
	v_add_u32_e32 v48, 0x90, v144
	v_ashrrev_i32_e32 v49, 31, v48
	s_cbranch_vccnz .LBB0_241
	v_lshl_add_u64 v[50:51], v[48:49], 2, s[30:31]
	global_load_dword v49, v[50:51], off
	s_waitcnt vmcnt(0)
	v_fmamk_f32 v49, v49, 0x3a800000, v156
	v_rsq_f32_e32 v64, v49
.LBB0_241:
	s_nop 0
	v_mov_b32_e32 v233, v64
	v_pk_mul_f32 v[46:47], v[46:47], v[64:65] op_sel_hi:[1,0]
	v_pk_mul_f32 v[44:45], v[44:45], v[64:65] op_sel_hi:[1,0]
	v_pk_mul_f32 v[50:51], v[42:43], v[64:65] op_sel_hi:[1,0]
	v_pk_mul_f32 v[42:43], v[40:41], v[64:65] op_sel_hi:[1,0]
	v_mad_i64_i32 v[48:49], s[34:35], v48, s60, v[146:147]
	v_cvt_pk_bf16_f32 v40, v44, v45
	v_cvt_pk_bf16_f32 v41, v46, v47
	v_cvt_pk_bf16_f32 v42, v42, v43
	v_cvt_pk_bf16_f32 v43, v50, v51
	global_store_dwordx4 v[48:49], v[40:43], off
	v_pk_mul_f32 v[38:39], v[38:39], v[64:65] op_sel_hi:[1,0]
	v_pk_mul_f32 v[36:37], v[36:37], v[64:65] op_sel_hi:[1,0]
	v_pk_mul_f32 v[40:41], v[34:35], v[64:65] op_sel_hi:[1,0]
	v_pk_mul_f32 v[34:35], v[32:33], v[64:65] op_sel_hi:[1,0]
	v_cvt_pk_bf16_f32 v32, v36, v37
	v_cvt_pk_bf16_f32 v33, v38, v39
	v_cvt_pk_bf16_f32 v34, v34, v35
	v_cvt_pk_bf16_f32 v35, v40, v41
	v_add_u32_e32 v36, 0xa0, v144
	global_store_dwordx4 v[48:49], v[32:35], off offset:256
	v_ashrrev_i32_e32 v37, 31, v36
	s_and_b64 vcc, exec, s[6:7]
	v_mov_b32_e32 v32, 1.0
	v_mov_b32_e32 v34, 1.0
	s_cbranch_vccnz .LBB0_243
	v_lshl_add_u64 v[34:35], v[36:37], 2, s[30:31]
	global_load_dword v33, v[34:35], off
	s_waitcnt vmcnt(0)
	v_fmamk_f32 v33, v33, 0x3a800000, v156
	v_rsq_f32_e32 v34, v33
.LBB0_243:
	s_nop 0
	v_mov_b32_e32 v234, v34
	v_pk_mul_f32 v[30:31], v[30:31], v[34:35] op_sel_hi:[1,0]
	v_pk_mul_f32 v[28:29], v[28:29], v[34:35] op_sel_hi:[1,0]
	v_pk_mul_f32 v[38:39], v[26:27], v[34:35] op_sel_hi:[1,0]
	v_pk_mul_f32 v[26:27], v[24:25], v[34:35] op_sel_hi:[1,0]
	v_mad_i64_i32 v[36:37], s[34:35], v36, s60, v[146:147]
	v_cvt_pk_bf16_f32 v24, v28, v29
	v_cvt_pk_bf16_f32 v25, v30, v31
	v_cvt_pk_bf16_f32 v26, v26, v27
	v_cvt_pk_bf16_f32 v27, v38, v39
	global_store_dwordx4 v[36:37], v[24:27], off
	v_pk_mul_f32 v[22:23], v[22:23], v[34:35] op_sel_hi:[1,0]
	v_pk_mul_f32 v[20:21], v[20:21], v[34:35] op_sel_hi:[1,0]
	v_pk_mul_f32 v[24:25], v[18:19], v[34:35] op_sel_hi:[1,0]
	v_pk_mul_f32 v[18:19], v[16:17], v[34:35] op_sel_hi:[1,0]
	v_cvt_pk_bf16_f32 v16, v20, v21
	v_cvt_pk_bf16_f32 v17, v22, v23
	v_cvt_pk_bf16_f32 v18, v18, v19
	v_cvt_pk_bf16_f32 v19, v24, v25
	global_store_dwordx4 v[36:37], v[16:19], off offset:256
	s_and_b64 vcc, exec, s[6:7]
	s_nop 0
	v_add_u32_e32 v16, 0xb0, v144
	v_ashrrev_i32_e32 v17, 31, v16
	s_cbranch_vccnz .LBB0_245
	v_lshl_add_u64 v[18:19], v[16:17], 2, s[30:31]
	global_load_dword v17, v[18:19], off
	s_waitcnt vmcnt(0)
	v_fmamk_f32 v17, v17, 0x3a800000, v156
	v_rsq_f32_e32 v32, v17
.LBB0_245:
	s_nop 0
	v_mov_b32_e32 v235, v32
	v_pk_mul_f32 v[14:15], v[14:15], v[32:33] op_sel_hi:[1,0]
	v_pk_mul_f32 v[12:13], v[12:13], v[32:33] op_sel_hi:[1,0]
	v_pk_mul_f32 v[18:19], v[10:11], v[32:33] op_sel_hi:[1,0]
	v_pk_mul_f32 v[10:11], v[8:9], v[32:33] op_sel_hi:[1,0]
	v_mad_i64_i32 v[16:17], s[6:7], v16, s60, v[146:147]
	v_cvt_pk_bf16_f32 v8, v12, v13
	v_cvt_pk_bf16_f32 v9, v14, v15
	v_cvt_pk_bf16_f32 v10, v10, v11
	v_cvt_pk_bf16_f32 v11, v18, v19
	global_store_dwordx4 v[16:17], v[8:11], off
	v_pk_mul_f32 v[6:7], v[6:7], v[32:33] op_sel_hi:[1,0]
	v_pk_mul_f32 v[4:5], v[4:5], v[32:33] op_sel_hi:[1,0]
	v_pk_mul_f32 v[8:9], v[2:3], v[32:33] op_sel_hi:[1,0]
	v_pk_mul_f32 v[2:3], v[0:1], v[32:33] op_sel_hi:[1,0]
	v_cvt_pk_bf16_f32 v0, v4, v5
	v_cvt_pk_bf16_f32 v1, v6, v7
	v_cvt_pk_bf16_f32 v2, v2, v3
	v_cvt_pk_bf16_f32 v3, v8, v9
	s_andn2_b64 vcc, exec, s[4:5]
	s_mov_b64 s[4:5], -1
	global_store_dwordx4 v[16:17], v[0:3], off offset:256
	s_cbranch_vccnz .LBB0_222
.Lip0_tail:
	s_andn2_b64 vcc, exec, s[8:9]
	s_cbranch_vccnz .LBB0_221
	s_barrier
	s_branch .LBB0_221
.Lip0_fast:
	s_andn2_b64 vcc, exec, s[4:5]
	s_load_dwordx2 s[36:37], s[0:1], 0x138
	s_mov_b32 s94, 0x16000
	s_mov_b32 s95, 0
	s_mov_b32 s96, 0x6e000
	s_mov_b32 s97, 0
	v_and_or_b32 v146, v154, 15, s51
	v_lshl_add_u32 v146, s30, 8, v146
	s_lshl_b32 s101, s6, 8
	v_lshrrev_b32_e32 v144, 1, v154
	v_and_or_b32 v144, v144, 24, s101
	v_or_b32_e32 v144, s52, v144
	v_ashrrev_i32_e32 v145, 31, v144
	s_waitcnt lgkmcnt(0)
	v_lshl_add_u64 v[144:145], v[144:145], 1, s[36:37]
	v_lshl_add_u64 v[144:145], v[144:145], 0, s[14:15]
	v_mad_i64_i32 v[144:145], s[36:37], v146, s60, v[144:145]
	v_pk_mul_f32 v[124:125], v[124:125], v[228:229] op_sel_hi:[1,0]
	v_pk_mul_f32 v[126:127], v[126:127], v[228:229] op_sel_hi:[1,0]
	v_pk_mul_f32 v[120:121], v[120:121], v[228:229] op_sel_hi:[1,0]
	v_pk_mul_f32 v[122:123], v[122:123], v[228:229] op_sel_hi:[1,0]
	v_cvt_pk_bf16_f32 v156, v124, v125
	v_cvt_pk_bf16_f32 v157, v126, v127
	v_cvt_pk_bf16_f32 v158, v120, v121
	v_cvt_pk_bf16_f32 v159, v122, v123
	global_store_dwordx4 v[144:145], v[156:159], off
	v_pk_mul_f32 v[116:117], v[116:117], v[228:229] op_sel_hi:[1,0]
	v_pk_mul_f32 v[118:119], v[118:119], v[228:229] op_sel_hi:[1,0]
	v_pk_mul_f32 v[112:113], v[112:113], v[228:229] op_sel_hi:[1,0]
	v_pk_mul_f32 v[114:115], v[114:115], v[228:229] op_sel_hi:[1,0]
	v_cvt_pk_bf16_f32 v160, v116, v117
	v_cvt_pk_bf16_f32 v161, v118, v119
	v_cvt_pk_bf16_f32 v162, v112, v113
	v_cvt_pk_bf16_f32 v163, v114, v115
	global_store_dwordx4 v[144:145], v[160:163], off offset:256
	v_lshl_add_u64 v[144:145], v[144:145], 0, s[94:95]
	v_pk_mul_f32 v[108:109], v[108:109], v[228:229] op_sel:[0,1] op_sel_hi:[1,1]
	v_pk_mul_f32 v[110:111], v[110:111], v[228:229] op_sel:[0,1] op_sel_hi:[1,1]
	v_pk_mul_f32 v[104:105], v[104:105], v[228:229] op_sel:[0,1] op_sel_hi:[1,1]
	v_pk_mul_f32 v[106:107], v[106:107], v[228:229] op_sel:[0,1] op_sel_hi:[1,1]
	v_cvt_pk_bf16_f32 v156, v108, v109
	v_cvt_pk_bf16_f32 v157, v110, v111
	v_cvt_pk_bf16_f32 v158, v104, v105
	v_cvt_pk_bf16_f32 v159, v106, v107
	global_store_dwordx4 v[144:145], v[156:159], off
	v_pk_mul_f32 v[100:101], v[100:101], v[228:229] op_sel:[0,1] op_sel_hi:[1,1]
	v_pk_mul_f32 v[102:103], v[102:103], v[228:229] op_sel:[0,1] op_sel_hi:[1,1]
	v_pk_mul_f32 v[96:97], v[96:97], v[228:229] op_sel:[0,1] op_sel_hi:[1,1]
	v_pk_mul_f32 v[98:99], v[98:99], v[228:229] op_sel:[0,1] op_sel_hi:[1,1]
	v_cvt_pk_bf16_f32 v160, v100, v101
	v_cvt_pk_bf16_f32 v161, v102, v103
	v_cvt_pk_bf16_f32 v162, v96, v97
	v_cvt_pk_bf16_f32 v163, v98, v99
	global_store_dwordx4 v[144:145], v[160:163], off offset:256
	v_lshl_add_u64 v[144:145], v[144:145], 0, s[94:95]
	v_pk_mul_f32 v[92:93], v[92:93], v[230:231] op_sel_hi:[1,0]
	v_pk_mul_f32 v[94:95], v[94:95], v[230:231] op_sel_hi:[1,0]
	v_pk_mul_f32 v[88:89], v[88:89], v[230:231] op_sel_hi:[1,0]
	v_pk_mul_f32 v[90:91], v[90:91], v[230:231] op_sel_hi:[1,0]
	v_cvt_pk_bf16_f32 v156, v92, v93
	v_cvt_pk_bf16_f32 v157, v94, v95
	v_cvt_pk_bf16_f32 v158, v88, v89
	v_cvt_pk_bf16_f32 v159, v90, v91
	global_store_dwordx4 v[144:145], v[156:159], off
	v_pk_mul_f32 v[84:85], v[84:85], v[230:231] op_sel_hi:[1,0]
	v_pk_mul_f32 v[86:87], v[86:87], v[230:231] op_sel_hi:[1,0]
	v_pk_mul_f32 v[80:81], v[80:81], v[230:231] op_sel_hi:[1,0]
	v_pk_mul_f32 v[82:83], v[82:83], v[230:231] op_sel_hi:[1,0]
	v_cvt_pk_bf16_f32 v160, v84, v85
	v_cvt_pk_bf16_f32 v161, v86, v87
	v_cvt_pk_bf16_f32 v162, v80, v81
	v_cvt_pk_bf16_f32 v163, v82, v83
	global_store_dwordx4 v[144:145], v[160:163], off offset:256
	v_lshl_add_u64 v[144:145], v[144:145], 0, s[94:95]
	v_pk_mul_f32 v[76:77], v[76:77], v[230:231] op_sel:[0,1] op_sel_hi:[1,1]
	v_pk_mul_f32 v[78:79], v[78:79], v[230:231] op_sel:[0,1] op_sel_hi:[1,1]
	v_pk_mul_f32 v[72:73], v[72:73], v[230:231] op_sel:[0,1] op_sel_hi:[1,1]
	v_pk_mul_f32 v[74:75], v[74:75], v[230:231] op_sel:[0,1] op_sel_hi:[1,1]
	v_cvt_pk_bf16_f32 v156, v76, v77
	v_cvt_pk_bf16_f32 v157, v78, v79
	v_cvt_pk_bf16_f32 v158, v72, v73
	v_cvt_pk_bf16_f32 v159, v74, v75
	global_store_dwordx4 v[144:145], v[156:159], off
	v_pk_mul_f32 v[68:69], v[68:69], v[230:231] op_sel:[0,1] op_sel_hi:[1,1]
	v_pk_mul_f32 v[70:71], v[70:71], v[230:231] op_sel:[0,1] op_sel_hi:[1,1]
	v_pk_mul_f32 v[64:65], v[64:65], v[230:231] op_sel:[0,1] op_sel_hi:[1,1]
	v_pk_mul_f32 v[66:67], v[66:67], v[230:231] op_sel:[0,1] op_sel_hi:[1,1]
	v_cvt_pk_bf16_f32 v160, v68, v69
	v_cvt_pk_bf16_f32 v161, v70, v71
	v_cvt_pk_bf16_f32 v162, v64, v65
	v_cvt_pk_bf16_f32 v163, v66, v67
	global_store_dwordx4 v[144:145], v[160:163], off offset:256
	v_lshl_add_u64 v[144:145], v[144:145], 0, s[96:97]
	v_pk_mul_f32 v[60:61], v[60:61], v[232:233] op_sel_hi:[1,0]
	v_pk_mul_f32 v[62:63], v[62:63], v[232:233] op_sel_hi:[1,0]
	v_pk_mul_f32 v[56:57], v[56:57], v[232:233] op_sel_hi:[1,0]
	v_pk_mul_f32 v[58:59], v[58:59], v[232:233] op_sel_hi:[1,0]
	v_cvt_pk_bf16_f32 v156, v60, v61
	v_cvt_pk_bf16_f32 v157, v62, v63
	v_cvt_pk_bf16_f32 v158, v56, v57
	v_cvt_pk_bf16_f32 v159, v58, v59
	global_store_dwordx4 v[144:145], v[156:159], off
	v_pk_mul_f32 v[52:53], v[52:53], v[232:233] op_sel_hi:[1,0]
	v_pk_mul_f32 v[54:55], v[54:55], v[232:233] op_sel_hi:[1,0]
	v_pk_mul_f32 v[48:49], v[48:49], v[232:233] op_sel_hi:[1,0]
	v_pk_mul_f32 v[50:51], v[50:51], v[232:233] op_sel_hi:[1,0]
	v_cvt_pk_bf16_f32 v160, v52, v53
	v_cvt_pk_bf16_f32 v161, v54, v55
	v_cvt_pk_bf16_f32 v162, v48, v49
	v_cvt_pk_bf16_f32 v163, v50, v51
	global_store_dwordx4 v[144:145], v[160:163], off offset:256
	v_lshl_add_u64 v[144:145], v[144:145], 0, s[94:95]
	v_pk_mul_f32 v[44:45], v[44:45], v[232:233] op_sel:[0,1] op_sel_hi:[1,1]
	v_pk_mul_f32 v[46:47], v[46:47], v[232:233] op_sel:[0,1] op_sel_hi:[1,1]
	v_pk_mul_f32 v[40:41], v[40:41], v[232:233] op_sel:[0,1] op_sel_hi:[1,1]
	v_pk_mul_f32 v[42:43], v[42:43], v[232:233] op_sel:[0,1] op_sel_hi:[1,1]
	v_cvt_pk_bf16_f32 v156, v44, v45
	v_cvt_pk_bf16_f32 v157, v46, v47
	v_cvt_pk_bf16_f32 v158, v40, v41
	v_cvt_pk_bf16_f32 v159, v42, v43
	global_store_dwordx4 v[144:145], v[156:159], off
	v_pk_mul_f32 v[36:37], v[36:37], v[232:233] op_sel:[0,1] op_sel_hi:[1,1]
	v_pk_mul_f32 v[38:39], v[38:39], v[232:233] op_sel:[0,1] op_sel_hi:[1,1]
	v_pk_mul_f32 v[32:33], v[32:33], v[232:233] op_sel:[0,1] op_sel_hi:[1,1]
	v_pk_mul_f32 v[34:35], v[34:35], v[232:233] op_sel:[0,1] op_sel_hi:[1,1]
	v_cvt_pk_bf16_f32 v160, v36, v37
	v_cvt_pk_bf16_f32 v161, v38, v39
	v_cvt_pk_bf16_f32 v162, v32, v33
	v_cvt_pk_bf16_f32 v163, v34, v35
	global_store_dwordx4 v[144:145], v[160:163], off offset:256
	v_lshl_add_u64 v[144:145], v[144:145], 0, s[94:95]
	v_pk_mul_f32 v[28:29], v[28:29], v[234:235] op_sel_hi:[1,0]
	v_pk_mul_f32 v[30:31], v[30:31], v[234:235] op_sel_hi:[1,0]
	v_pk_mul_f32 v[24:25], v[24:25], v[234:235] op_sel_hi:[1,0]
	v_pk_mul_f32 v[26:27], v[26:27], v[234:235] op_sel_hi:[1,0]
	v_cvt_pk_bf16_f32 v156, v28, v29
	v_cvt_pk_bf16_f32 v157, v30, v31
	v_cvt_pk_bf16_f32 v158, v24, v25
	v_cvt_pk_bf16_f32 v159, v26, v27
	global_store_dwordx4 v[144:145], v[156:159], off
	v_pk_mul_f32 v[20:21], v[20:21], v[234:235] op_sel_hi:[1,0]
	v_pk_mul_f32 v[22:23], v[22:23], v[234:235] op_sel_hi:[1,0]
	v_pk_mul_f32 v[16:17], v[16:17], v[234:235] op_sel_hi:[1,0]
	v_pk_mul_f32 v[18:19], v[18:19], v[234:235] op_sel_hi:[1,0]
	v_cvt_pk_bf16_f32 v160, v20, v21
	v_cvt_pk_bf16_f32 v161, v22, v23
	v_cvt_pk_bf16_f32 v162, v16, v17
	v_cvt_pk_bf16_f32 v163, v18, v19
	global_store_dwordx4 v[144:145], v[160:163], off offset:256
	v_lshl_add_u64 v[144:145], v[144:145], 0, s[94:95]
	v_pk_mul_f32 v[12:13], v[12:13], v[234:235] op_sel:[0,1] op_sel_hi:[1,1]
	v_pk_mul_f32 v[14:15], v[14:15], v[234:235] op_sel:[0,1] op_sel_hi:[1,1]
	v_pk_mul_f32 v[8:9], v[8:9], v[234:235] op_sel:[0,1] op_sel_hi:[1,1]
	v_pk_mul_f32 v[10:11], v[10:11], v[234:235] op_sel:[0,1] op_sel_hi:[1,1]
	v_cvt_pk_bf16_f32 v156, v12, v13
	v_cvt_pk_bf16_f32 v157, v14, v15
	v_cvt_pk_bf16_f32 v158, v8, v9
	v_cvt_pk_bf16_f32 v159, v10, v11
	global_store_dwordx4 v[144:145], v[156:159], off
	v_pk_mul_f32 v[4:5], v[4:5], v[234:235] op_sel:[0,1] op_sel_hi:[1,1]
	v_pk_mul_f32 v[6:7], v[6:7], v[234:235] op_sel:[0,1] op_sel_hi:[1,1]
	v_pk_mul_f32 v[0:1], v[0:1], v[234:235] op_sel:[0,1] op_sel_hi:[1,1]
	v_pk_mul_f32 v[2:3], v[2:3], v[234:235] op_sel:[0,1] op_sel_hi:[1,1]
	v_cvt_pk_bf16_f32 v160, v4, v5
	v_cvt_pk_bf16_f32 v161, v6, v7
	v_cvt_pk_bf16_f32 v162, v0, v1
	v_cvt_pk_bf16_f32 v163, v2, v3
	global_store_dwordx4 v[144:145], v[160:163], off offset:256
	s_mov_b64 s[4:5], -1
	s_cbranch_vccnz .LBB0_222
	s_branch .Lip0_tail

.LBB0_674:
	s_or_b64 exec, exec, s[4:5]
	s_mov_b32 s100, 0
	s_mov_b64 s[4:5], s[0:1]
	s_mov_b64 s[8:9], s[0:1]
	s_mov_b32 s3, s33
	s_mov_b32 s40, s2
	v_mov_b32_e32 v8, v154
	s_waitcnt lgkmcnt(0)
	s_barrier
	s_cmpk_gt_i32 s40, 0x57f
	v_readfirstlane_b32 s12, v8
	s_cbranch_scc1 .LBB0_690
	v_lshlrev_b32_e32 v0, 4, v8
	v_add_u32_e32 v1, 0x2000, v0
	v_ashrrev_i32_e32 v2, 31, v1
	v_lshrrev_b32_e32 v2, 22, v2
	v_add_u32_e32 v2, v1, v2
	v_ashrrev_i32_e32 v9, 10, v2
	v_mul_i32_i24_e32 v2, 0x400, v9
	v_sub_u32_e32 v1, v1, v2
	v_lshrrev_b32_e32 v2, 4, v1
	v_bitop3_b32 v1, v2, v1, 32 bitop3:0x6c
	v_ashrrev_i32_e32 v2, 31, v1
	v_lshrrev_b32_e32 v2, 26, v2
	v_add_u32_e32 v2, v1, v2
	v_lshlrev_b32_e32 v3, 3, v9
	v_ashrrev_i32_e32 v10, 6, v2
	v_and_b32_e32 v3, -16, v3
	v_add_u32_e32 v3, v10, v3
	s_load_dwordx2 s[10:11], s[8:9], 0x138
	s_load_dwordx2 s[6:7], s[4:5], 0x130
	v_and_b32_e32 v4, 3, v10
	s_mov_b32 s4, 0x1fffe0
	v_lshrrev_b32_e32 v5, 2, v3
	v_lshlrev_b32_e32 v6, 1, v3
	v_and_b32_e32 v2, 0xc0, v2
	v_and_or_b32 v4, v3, s4, v4
	v_and_b32_e32 v5, 4, v5
	v_and_b32_e32 v6, 24, v6
	v_sub_u32_e32 v1, v1, v2
	v_mov_b32_e32 v2, 1
	v_or3_b32 v4, v4, v5, v6
	v_lshlrev_b32_e32 v5, 5, v9
	v_ashrrev_i16_sdwa v1, v2, sext(v1) dst_sel:DWORD dst_unused:UNUSED_PAD src0_sel:DWORD src1_sel:BYTE_0
	v_and_b32_e32 v5, 32, v5
	v_bfe_i32 v11, v1, 0, 16
	v_add_lshl_u32 v1, v5, v11, 1
	v_lshl_add_u32 v128, v4, 11, v1
	v_lshl_add_u32 v130, v3, 11, v1
	v_bfe_i32 v1, v8, 27, 1
	v_lshrrev_b32_e32 v1, 22, v1
	v_add_u32_e32 v1, v0, v1
	v_and_b32_e32 v1, 0xfffffc00, v1
	v_sub_u32_e32 v0, v0, v1
	v_lshrrev_b32_e32 v1, 4, v0
	v_ashrrev_i32_e32 v3, 31, v8
	v_bitop3_b32 v0, v1, v0, 32 bitop3:0x6c
	v_lshrrev_b32_e32 v3, 26, v3
	v_ashrrev_i32_e32 v1, 31, v0
	v_add_u32_e32 v3, v8, v3
	v_lshrrev_b32_e32 v1, 26, v1
	v_ashrrev_i32_e32 v13, 6, v3
	v_add_u32_e32 v1, v0, v1
	v_lshlrev_b32_e32 v3, 3, v13
	s_waitcnt lgkmcnt(0)
	s_add_u32 s41, s10, 0xa80000
	v_ashrrev_i32_e32 v12, 6, v1
	v_and_b32_e32 v3, -16, v3
	s_addc_u32 s42, s11, 0
	v_add_u32_e32 v3, v12, v3
	v_and_b32_e32 v4, 3, v12
	s_ashr_i32 s44, s40, 31
	v_and_or_b32 v4, v3, s4, v4
	s_lshr_b32 s4, s44, 29
	s_add_i32 s4, s40, s4
	s_ashr_i32 s10, s12, 6
	s_ashr_i32 s8, s4, 3
	s_and_b32 s4, s4, -8
	s_ashr_i32 s5, s12, 8
	s_lshl_b32 s43, s10, 10
	s_sub_i32 s4, s40, s4
	s_cmp_lt_i32 s4, 0
	s_movk_i32 s45, 0xb1
	s_cselect_b32 s9, s45, 0xb0
	s_mul_i32 s4, s9, s4
	s_add_i32 s4, s4, s8
	s_mul_hi_i32 s8, s4, 0x2e8ba2e9
	s_lshr_b32 s9, s8, 31
	s_ashr_i32 s8, s8, 5
	s_add_i32 s8, s8, s9
	s_lshl_b32 s9, s8, 3
	s_mulk_i32 s8, 0xb0
	s_sub_i32 s8, s4, s8
	s_bfe_u32 s4, s8, 0x3001c
	s_add_i32 s11, s8, s4
	s_sext_i32_i16 s4, s11
	s_and_b32 s11, s11, 0xfff8
	s_sub_i32 s8, s8, s11
	s_sext_i32_i16 s8, s8
	v_lshrrev_b32_e32 v5, 2, v3
	v_lshlrev_b32_e32 v6, 1, v3
	v_and_b32_e32 v1, 0xc0, v1
	s_lshr_b32 s4, s4, 3
	s_add_i32 s34, s9, s8
	v_and_b32_e32 v5, 4, v5
	v_and_b32_e32 v6, 24, v6
	v_sub_u32_e32 v0, v0, v1
	s_ashr_i32 s35, s34, 31
	s_bfe_i64 s[14:15], s[4:5], 0x100000
	v_or3_b32 v4, v4, v5, v6
	v_lshlrev_b32_e32 v5, 5, v13
	v_ashrrev_i16_sdwa v0, v2, sext(v0) dst_sel:DWORD dst_unused:UNUSED_PAD src0_sel:DWORD src1_sel:BYTE_0
	s_lshl_b64 s[8:9], s[34:35], 19
	s_lshl_b64 s[14:15], s[14:15], 19
	v_and_b32_e32 v5, 32, v5
	v_bfe_i32 v14, v0, 0, 16
	s_add_u32 s30, s41, s14
	v_add_lshl_u32 v0, v5, v14, 1
	s_addc_u32 s31, s42, s15
	s_add_i32 s35, s43, 0
	v_lshl_add_u32 v132, v4, 11, v0
	s_add_i32 m0, s35, 0x10000
	v_lshl_add_u32 v134, v3, 11, v0
	global_load_lds_dwordx4 v132, s[30:31]
	s_add_i32 m0, s35, 0x12000
	s_add_u32 s14, s30, 0x40000
	global_load_lds_dwordx4 v128, s[30:31]
	s_addc_u32 s15, s31, 0
	s_add_i32 m0, s35, 0x14000
	v_mov_b32_e32 v133, 0
	global_load_lds_dwordx4 v132, s[14:15]
	s_add_i32 m0, s35, 0x16000
	s_add_u32 s36, s6, s8
	s_addc_u32 s37, s7, s9
	s_add_i32 s46, s35, 0x2000
	global_load_lds_dwordx4 v128, s[14:15]
	s_mov_b32 m0, s35
	s_add_u32 s8, s36, 0x40000
	global_load_lds_dwordx4 v134, s[36:37]
	s_mov_b32 m0, s46
	s_addc_u32 s9, s37, 0
	s_add_i32 s47, s35, 0x4000
	global_load_lds_dwordx4 v130, s[36:37]
	s_mov_b32 m0, s47
	s_add_i32 s48, s35, 0x6000
	global_load_lds_dwordx4 v134, s[8:9]
	s_mov_b32 m0, s48
	v_mov_b32_e32 v129, v133
	global_load_lds_dwordx4 v130, s[8:9]
	v_mov_b32_e32 v135, v133
	v_mov_b32_e32 v131, v133
	s_cmp_eq_u32 s5, 1
	s_mov_b32 s49, 0
	v_lshl_add_u64 v[6:7], s[30:31], 0, v[132:133]
	v_lshl_add_u64 v[4:5], s[30:31], 0, v[128:129]
	v_lshl_add_u64 v[0:1], s[36:37], 0, v[134:135]
	s_cselect_b64 s[8:9], -1, 0
	s_cmp_lg_u32 s5, 1
	v_lshl_add_u64 v[2:3], s[36:37], 0, v[130:131]
	s_cbranch_scc1 .LBB0_677
	s_barrier

.LBB0_686:
	s_add_i32 s101, s34, 1
	s_cmp_eq_u32 s100, s101
	s_cbranch_scc1 .Lgu0_fast
	s_mov_b32 s100, s101
	v_mov_b32_e32 v153, v154
	s_mov_b64 s[30:31], s[0:1]
	s_load_dwordx2 s[36:37], s[30:31], 0x138
	s_waitcnt lgkmcnt(0)
	s_add_u32 s30, s36, 0xfd00000
	s_addc_u32 s31, s37, 0
	s_lshl_b32 s17, s34, 8
	s_add_i32 s17, s17, s50
	v_and_or_b32 v146, v153, 15, s17
	v_ashrrev_i32_e32 v147, 31, v146
	v_lshlrev_b64 v[144:145], 6, v[146:147]
	v_lshl_add_u64 v[144:145], s[30:31], 0, v[144:145]
	global_load_dwordx4 v[156:159], v[144:145], off
	global_load_dwordx4 v[160:163], v[144:145], off offset:32
	global_load_dwordx4 v[164:167], v[144:145], off offset:16
	global_load_dwordx4 v[168:171], v[144:145], off offset:48
	v_lshrrev_b32_e32 v144, 2, v153
	s_lshl_b32 s17, s58, 7
	s_or_b32 s17, s17, s53
	v_and_or_b32 v144, v144, 12, s17
	v_ashrrev_i32_e32 v145, 31, v144
	v_or_b32_e32 v172, 16, v146
	v_lshl_add_u64 v[144:145], v[144:145], 1, s[36:37]
	v_ashrrev_i32_e32 v173, 31, v172
	v_lshl_add_u64 v[144:145], v[144:145], 0, s[14:15]
	v_lshlrev_b64 v[174:175], 6, v[172:173]
	s_andn2_b64 vcc, exec, s[4:5]
	s_waitcnt vmcnt(0)
	v_mov_b32_e32 v176, v156
	v_mov_b32_e32 v177, v160
	v_mov_b32_e32 v160, v157
	v_mov_b32_e32 v156, v158
	v_mov_b32_e32 v157, v162
	v_mov_b32_e32 v162, v159
	v_mov_b32_e32 v158, v164
	v_mov_b32_e32 v159, v168
	v_mov_b32_e32 v168, v165
	v_mov_b32_e32 v164, v166
	v_mov_b32_e32 v165, v170
	v_mov_b32_e32 v170, v167
	v_pk_add_f32 v[160:161], v[176:177], v[160:161]
	v_pk_add_f32 v[156:157], v[156:157], v[162:163]
	v_pk_add_f32 v[158:159], v[158:159], v[168:169]
	v_pk_add_f32 v[162:163], v[164:165], v[170:171]
	v_pk_add_f32 v[156:157], v[160:161], v[156:157]
	v_pk_add_f32 v[158:159], v[158:159], v[162:163]
	v_lshl_add_u64 v[160:161], s[30:31], 0, v[174:175]
	v_pk_add_f32 v[156:157], v[156:157], v[158:159]
	v_mad_i64_i32 v[158:159], s[36:37], v146, s57, v[144:145]
	v_add_f32_e32 v147, v156, v157
	v_fmamk_f32 v147, v147, 0x3a800000, v152
	v_rsq_f32_e32 v156, v147
	s_nop 0
	v_mov_b32_e32 v228, v156
	v_pk_mul_f32 v[124:125], v[124:125], v[156:157] op_sel_hi:[1,0]
	v_pk_mul_f32 v[126:127], v[126:127], v[156:157] op_sel_hi:[1,0]
	v_pk_mul_f32 v[120:121], v[120:121], v[156:157] op_sel_hi:[1,0]
	v_pk_mul_f32 v[122:123], v[122:123], v[156:157] op_sel_hi:[1,0]
	v_pk_mul_f32 v[116:117], v[116:117], v[156:157] op_sel_hi:[1,0]
	v_pk_mul_f32 v[112:113], v[112:113], v[156:157] op_sel_hi:[1,0]
	v_pk_mul_f32 v[118:119], v[118:119], v[156:157] op_sel_hi:[1,0]
	v_pk_mul_f32 v[114:115], v[114:115], v[156:157] op_sel_hi:[1,0]
	v_mul_f32_e32 v147, 0xbfb8aa3b, v124
	v_mul_f32_e32 v153, 0xbfb8aa3b, v125
	v_mul_f32_e32 v156, 0xbfb8aa3b, v126
	v_mul_f32_e32 v157, 0xbfb8aa3b, v127
	v_mul_f32_e32 v162, 0xbfb8aa3b, v116
	v_mul_f32_e32 v163, 0xbfb8aa3b, v117
	v_mul_f32_e32 v164, 0xbfb8aa3b, v118
	v_mul_f32_e32 v165, 0xbfb8aa3b, v119
	v_exp_f32_e32 v147, v147
	v_exp_f32_e32 v153, v153
	v_exp_f32_e32 v156, v156
	v_exp_f32_e32 v157, v157
	v_exp_f32_e32 v162, v162
	v_exp_f32_e32 v163, v163
	v_exp_f32_e32 v164, v164
	v_exp_f32_e32 v165, v165
	v_add_f32_e32 v147, 1.0, v147
	v_add_f32_e32 v153, 1.0, v153
	v_add_f32_e32 v166, 1.0, v156
	v_add_f32_e32 v167, 1.0, v157
	v_add_f32_e32 v168, 1.0, v162
	v_add_f32_e32 v169, 1.0, v163
	v_add_f32_e32 v170, 1.0, v164
	v_add_f32_e32 v171, 1.0, v165
	v_rcp_f32_e32 v156, v147
	v_rcp_f32_e32 v157, v153
	v_rcp_f32_e32 v162, v166
	v_rcp_f32_e32 v163, v167
	v_rcp_f32_e32 v164, v168
	v_rcp_f32_e32 v165, v169
	v_rcp_f32_e32 v166, v170
	v_rcp_f32_e32 v167, v171
	v_pk_mul_f32 v[124:125], v[124:125], v[156:157]
	v_pk_mul_f32 v[126:127], v[126:127], v[162:163]
	v_pk_mul_f32 v[116:117], v[116:117], v[164:165]
	v_pk_mul_f32 v[118:119], v[118:119], v[166:167]
	v_pk_mul_f32 v[120:121], v[120:121], v[124:125]
	v_pk_mul_f32 v[122:123], v[122:123], v[126:127]
	v_pk_mul_f32 v[112:113], v[112:113], v[116:117]
	v_pk_mul_f32 v[114:115], v[114:115], v[118:119]
	v_cvt_pk_bf16_f32 v116, v120, v121
	v_cvt_pk_bf16_f32 v117, v122, v123
	v_cvt_pk_bf16_f32 v112, v112, v113
	v_cvt_pk_bf16_f32 v113, v114, v115
	global_store_dwordx2 v[158:159], v[116:117], off
	global_store_dwordx2 v[158:159], v[112:113], off offset:128
	global_load_dwordx4 v[112:115], v[160:161], off
	s_nop 0
	global_load_dwordx4 v[116:119], v[160:161], off offset:32
	global_load_dwordx4 v[120:123], v[160:161], off offset:16
	global_load_dwordx4 v[124:127], v[160:161], off offset:48
	v_or_b32_e32 v156, 32, v146
	v_ashrrev_i32_e32 v157, 31, v156
	v_lshlrev_b64 v[158:159], 6, v[156:157]
	s_waitcnt vmcnt(3)
	v_mov_b32_e32 v160, v112
	s_waitcnt vmcnt(2)
	v_mov_b32_e32 v161, v116
	v_mov_b32_e32 v116, v113
	v_mov_b32_e32 v112, v114
	v_mov_b32_e32 v113, v118
	v_mov_b32_e32 v118, v115
	s_waitcnt vmcnt(1)
	v_mov_b32_e32 v114, v120
	s_waitcnt vmcnt(0)
	v_mov_b32_e32 v115, v124
	v_mov_b32_e32 v124, v121
	v_mov_b32_e32 v120, v122
	v_mov_b32_e32 v121, v126
	v_mov_b32_e32 v126, v123
	v_pk_add_f32 v[116:117], v[160:161], v[116:117]
	v_pk_add_f32 v[112:113], v[112:113], v[118:119]
	v_pk_add_f32 v[114:115], v[114:115], v[124:125]
	v_pk_add_f32 v[118:119], v[120:121], v[126:127]
	v_pk_add_f32 v[112:113], v[116:117], v[112:113]
	v_pk_add_f32 v[114:115], v[114:115], v[118:119]
	v_lshl_add_u64 v[116:117], s[30:31], 0, v[158:159]
	v_pk_add_f32 v[112:113], v[112:113], v[114:115]
	v_mad_i64_i32 v[114:115], s[36:37], v172, s57, v[144:145]
	v_add_f32_e32 v112, v112, v113
	v_fmamk_f32 v112, v112, 0x3a800000, v152
	v_rsq_f32_e32 v112, v112
	s_nop 0
	v_mov_b32_e32 v229, v112
	v_pk_mul_f32 v[108:109], v[108:109], v[112:113] op_sel_hi:[1,0]
	v_pk_mul_f32 v[110:111], v[110:111], v[112:113] op_sel_hi:[1,0]
	v_pk_mul_f32 v[104:105], v[104:105], v[112:113] op_sel_hi:[1,0]
	v_pk_mul_f32 v[106:107], v[106:107], v[112:113] op_sel_hi:[1,0]
	v_pk_mul_f32 v[100:101], v[100:101], v[112:113] op_sel_hi:[1,0]
	v_pk_mul_f32 v[96:97], v[96:97], v[112:113] op_sel_hi:[1,0]
	v_pk_mul_f32 v[102:103], v[102:103], v[112:113] op_sel_hi:[1,0]
	v_pk_mul_f32 v[98:99], v[98:99], v[112:113] op_sel_hi:[1,0]
	v_mul_f32_e32 v112, 0xbfb8aa3b, v108
	v_mul_f32_e32 v113, 0xbfb8aa3b, v109
	v_mul_f32_e32 v118, 0xbfb8aa3b, v110
	v_mul_f32_e32 v119, 0xbfb8aa3b, v111
	v_mul_f32_e32 v120, 0xbfb8aa3b, v100
	v_mul_f32_e32 v121, 0xbfb8aa3b, v101
	v_mul_f32_e32 v122, 0xbfb8aa3b, v102
	v_mul_f32_e32 v123, 0xbfb8aa3b, v103
	v_exp_f32_e32 v112, v112
	v_exp_f32_e32 v113, v113
	v_exp_f32_e32 v118, v118
	v_exp_f32_e32 v119, v119
	v_exp_f32_e32 v120, v120
	v_exp_f32_e32 v121, v121
	v_exp_f32_e32 v122, v122
	v_exp_f32_e32 v123, v123
	v_add_f32_e32 v112, 1.0, v112
	v_add_f32_e32 v113, 1.0, v113
	v_add_f32_e32 v118, 1.0, v118
	v_add_f32_e32 v119, 1.0, v119
	v_add_f32_e32 v120, 1.0, v120
	v_add_f32_e32 v121, 1.0, v121
	v_add_f32_e32 v122, 1.0, v122
	v_add_f32_e32 v123, 1.0, v123
	v_rcp_f32_e32 v112, v112
	v_rcp_f32_e32 v113, v113
	v_rcp_f32_e32 v118, v118
	v_rcp_f32_e32 v119, v119
	v_rcp_f32_e32 v120, v120
	v_rcp_f32_e32 v121, v121
	v_rcp_f32_e32 v122, v122
	v_rcp_f32_e32 v123, v123
	v_pk_mul_f32 v[108:109], v[108:109], v[112:113]
	v_pk_mul_f32 v[110:111], v[110:111], v[118:119]
	v_pk_mul_f32 v[100:101], v[100:101], v[120:121]
	v_pk_mul_f32 v[102:103], v[102:103], v[122:123]
	v_pk_mul_f32 v[104:105], v[104:105], v[108:109]
	v_pk_mul_f32 v[106:107], v[106:107], v[110:111]
	v_pk_mul_f32 v[96:97], v[96:97], v[100:101]
	v_pk_mul_f32 v[98:99], v[98:99], v[102:103]
	v_cvt_pk_bf16_f32 v100, v104, v105
	v_cvt_pk_bf16_f32 v101, v106, v107
	v_cvt_pk_bf16_f32 v96, v96, v97
	v_cvt_pk_bf16_f32 v97, v98, v99
	global_store_dwordx2 v[114:115], v[100:101], off
	global_store_dwordx2 v[114:115], v[96:97], off offset:128
	global_load_dwordx4 v[96:99], v[116:117], off
	s_nop 0
	global_load_dwordx4 v[100:103], v[116:117], off offset:32
	global_load_dwordx4 v[104:107], v[116:117], off offset:16
	global_load_dwordx4 v[108:111], v[116:117], off offset:48
	v_or_b32_e32 v112, 48, v146
	v_ashrrev_i32_e32 v113, 31, v112
	v_lshlrev_b64 v[114:115], 6, v[112:113]
	s_waitcnt vmcnt(3)
	v_mov_b32_e32 v116, v96
	s_waitcnt vmcnt(2)
	v_mov_b32_e32 v117, v100
	v_mov_b32_e32 v100, v97
	v_mov_b32_e32 v96, v98
	v_mov_b32_e32 v97, v102
	v_mov_b32_e32 v102, v99
	s_waitcnt vmcnt(1)
	v_mov_b32_e32 v98, v104
	s_waitcnt vmcnt(0)
	v_mov_b32_e32 v99, v108
	v_mov_b32_e32 v108, v105
	v_mov_b32_e32 v104, v106
	v_mov_b32_e32 v105, v110
	v_mov_b32_e32 v110, v107
	v_pk_add_f32 v[100:101], v[116:117], v[100:101]
	v_pk_add_f32 v[96:97], v[96:97], v[102:103]
	v_pk_add_f32 v[98:99], v[98:99], v[108:109]
	v_pk_add_f32 v[102:103], v[104:105], v[110:111]
	v_pk_add_f32 v[96:97], v[100:101], v[96:97]
	v_pk_add_f32 v[98:99], v[98:99], v[102:103]
	v_lshl_add_u64 v[100:101], s[30:31], 0, v[114:115]
	v_pk_add_f32 v[96:97], v[96:97], v[98:99]
	v_mad_i64_i32 v[98:99], s[36:37], v156, s57, v[144:145]
	v_add_f32_e32 v96, v96, v97
	v_fmamk_f32 v96, v96, 0x3a800000, v152
	v_rsq_f32_e32 v96, v96
	s_nop 0
	v_mov_b32_e32 v230, v96
	v_pk_mul_f32 v[92:93], v[92:93], v[96:97] op_sel_hi:[1,0]
	v_pk_mul_f32 v[94:95], v[94:95], v[96:97] op_sel_hi:[1,0]
	v_pk_mul_f32 v[88:89], v[88:89], v[96:97] op_sel_hi:[1,0]
	v_pk_mul_f32 v[90:91], v[90:91], v[96:97] op_sel_hi:[1,0]
	v_pk_mul_f32 v[84:85], v[84:85], v[96:97] op_sel_hi:[1,0]
	v_pk_mul_f32 v[80:81], v[80:81], v[96:97] op_sel_hi:[1,0]
	v_pk_mul_f32 v[86:87], v[86:87], v[96:97] op_sel_hi:[1,0]
	v_pk_mul_f32 v[82:83], v[82:83], v[96:97] op_sel_hi:[1,0]
	v_mul_f32_e32 v96, 0xbfb8aa3b, v92
	v_mul_f32_e32 v97, 0xbfb8aa3b, v93
	v_mul_f32_e32 v102, 0xbfb8aa3b, v94
	v_mul_f32_e32 v103, 0xbfb8aa3b, v95
	v_mul_f32_e32 v104, 0xbfb8aa3b, v84
	v_mul_f32_e32 v105, 0xbfb8aa3b, v85
	v_mul_f32_e32 v106, 0xbfb8aa3b, v86
	v_mul_f32_e32 v107, 0xbfb8aa3b, v87
	v_exp_f32_e32 v96, v96
	v_exp_f32_e32 v97, v97
	v_exp_f32_e32 v102, v102
	v_exp_f32_e32 v103, v103
	v_exp_f32_e32 v104, v104
	v_exp_f32_e32 v105, v105
	v_exp_f32_e32 v106, v106
	v_exp_f32_e32 v107, v107
	v_add_f32_e32 v96, 1.0, v96
	v_add_f32_e32 v97, 1.0, v97
	v_add_f32_e32 v102, 1.0, v102
	v_add_f32_e32 v103, 1.0, v103
	v_add_f32_e32 v104, 1.0, v104
	v_add_f32_e32 v105, 1.0, v105
	v_add_f32_e32 v106, 1.0, v106
	v_add_f32_e32 v107, 1.0, v107
	v_rcp_f32_e32 v96, v96
	v_rcp_f32_e32 v97, v97
	v_rcp_f32_e32 v102, v102
	v_rcp_f32_e32 v103, v103
	v_rcp_f32_e32 v104, v104
	v_rcp_f32_e32 v105, v105
	v_rcp_f32_e32 v106, v106
	v_rcp_f32_e32 v107, v107
	v_pk_mul_f32 v[92:93], v[92:93], v[96:97]
	v_pk_mul_f32 v[94:95], v[94:95], v[102:103]
	v_pk_mul_f32 v[84:85], v[84:85], v[104:105]
	v_pk_mul_f32 v[86:87], v[86:87], v[106:107]
	v_pk_mul_f32 v[88:89], v[88:89], v[92:93]
	v_pk_mul_f32 v[90:91], v[90:91], v[94:95]
	v_pk_mul_f32 v[80:81], v[80:81], v[84:85]
	v_pk_mul_f32 v[82:83], v[82:83], v[86:87]
	v_cvt_pk_bf16_f32 v84, v88, v89
	v_cvt_pk_bf16_f32 v85, v90, v91
	v_cvt_pk_bf16_f32 v80, v80, v81
	v_cvt_pk_bf16_f32 v81, v82, v83
	global_store_dwordx2 v[98:99], v[84:85], off
	global_store_dwordx2 v[98:99], v[80:81], off offset:128
	global_load_dwordx4 v[80:83], v[100:101], off
	s_nop 0
	global_load_dwordx4 v[84:87], v[100:101], off offset:32
	global_load_dwordx4 v[88:91], v[100:101], off offset:16
	global_load_dwordx4 v[92:95], v[100:101], off offset:48
	v_add_u32_e32 v96, 0x80, v146
	v_ashrrev_i32_e32 v97, 31, v96
	v_lshlrev_b64 v[98:99], 6, v[96:97]
	s_waitcnt vmcnt(3)
	v_mov_b32_e32 v100, v80
	s_waitcnt vmcnt(2)
	v_mov_b32_e32 v101, v84
	v_mov_b32_e32 v84, v81
	v_mov_b32_e32 v80, v82
	v_mov_b32_e32 v81, v86
	v_mov_b32_e32 v86, v83
	s_waitcnt vmcnt(1)
	v_mov_b32_e32 v82, v88
	s_waitcnt vmcnt(0)
	v_mov_b32_e32 v83, v92
	v_mov_b32_e32 v92, v89
	v_mov_b32_e32 v88, v90
	v_mov_b32_e32 v89, v94
	v_mov_b32_e32 v94, v91
	v_pk_add_f32 v[84:85], v[100:101], v[84:85]
	v_pk_add_f32 v[80:81], v[80:81], v[86:87]
	v_pk_add_f32 v[82:83], v[82:83], v[92:93]
	v_pk_add_f32 v[86:87], v[88:89], v[94:95]
	v_pk_add_f32 v[80:81], v[84:85], v[80:81]
	v_pk_add_f32 v[82:83], v[82:83], v[86:87]
	v_lshl_add_u64 v[84:85], s[30:31], 0, v[98:99]
	v_pk_add_f32 v[80:81], v[80:81], v[82:83]
	v_mad_i64_i32 v[82:83], s[36:37], v112, s57, v[144:145]
	v_add_f32_e32 v80, v80, v81
	v_fmamk_f32 v80, v80, 0x3a800000, v152
	v_rsq_f32_e32 v80, v80
	s_nop 0
	v_mov_b32_e32 v231, v80
	v_pk_mul_f32 v[76:77], v[76:77], v[80:81] op_sel_hi:[1,0]
	v_pk_mul_f32 v[78:79], v[78:79], v[80:81] op_sel_hi:[1,0]
	v_pk_mul_f32 v[72:73], v[72:73], v[80:81] op_sel_hi:[1,0]
	v_pk_mul_f32 v[74:75], v[74:75], v[80:81] op_sel_hi:[1,0]
	v_pk_mul_f32 v[68:69], v[68:69], v[80:81] op_sel_hi:[1,0]
	v_pk_mul_f32 v[64:65], v[64:65], v[80:81] op_sel_hi:[1,0]
	v_pk_mul_f32 v[70:71], v[70:71], v[80:81] op_sel_hi:[1,0]
	v_pk_mul_f32 v[66:67], v[66:67], v[80:81] op_sel_hi:[1,0]
	v_mul_f32_e32 v80, 0xbfb8aa3b, v76
	v_mul_f32_e32 v81, 0xbfb8aa3b, v77
	v_mul_f32_e32 v86, 0xbfb8aa3b, v78
	v_mul_f32_e32 v87, 0xbfb8aa3b, v79
	v_mul_f32_e32 v88, 0xbfb8aa3b, v68
	v_mul_f32_e32 v89, 0xbfb8aa3b, v69
	v_mul_f32_e32 v90, 0xbfb8aa3b, v70
	v_mul_f32_e32 v91, 0xbfb8aa3b, v71
	v_exp_f32_e32 v80, v80
	v_exp_f32_e32 v81, v81
	v_exp_f32_e32 v86, v86
	v_exp_f32_e32 v87, v87
	v_exp_f32_e32 v88, v88
	v_exp_f32_e32 v89, v89
	v_exp_f32_e32 v90, v90
	v_exp_f32_e32 v91, v91
	v_add_f32_e32 v80, 1.0, v80
	v_add_f32_e32 v81, 1.0, v81
	v_add_f32_e32 v86, 1.0, v86
	v_add_f32_e32 v87, 1.0, v87
	v_add_f32_e32 v88, 1.0, v88
	v_add_f32_e32 v89, 1.0, v89
	v_add_f32_e32 v90, 1.0, v90
	v_add_f32_e32 v91, 1.0, v91
	v_rcp_f32_e32 v80, v80
	v_rcp_f32_e32 v81, v81
	v_rcp_f32_e32 v86, v86
	v_rcp_f32_e32 v87, v87
	v_rcp_f32_e32 v88, v88
	v_rcp_f32_e32 v89, v89
	v_rcp_f32_e32 v90, v90
	v_rcp_f32_e32 v91, v91
	v_pk_mul_f32 v[76:77], v[76:77], v[80:81]
	v_pk_mul_f32 v[78:79], v[78:79], v[86:87]
	v_pk_mul_f32 v[68:69], v[68:69], v[88:89]
	v_pk_mul_f32 v[70:71], v[70:71], v[90:91]
	v_pk_mul_f32 v[72:73], v[72:73], v[76:77]
	v_pk_mul_f32 v[74:75], v[74:75], v[78:79]
	v_pk_mul_f32 v[64:65], v[64:65], v[68:69]
	v_pk_mul_f32 v[66:67], v[66:67], v[70:71]
	v_cvt_pk_bf16_f32 v68, v72, v73
	v_cvt_pk_bf16_f32 v69, v74, v75
	v_cvt_pk_bf16_f32 v64, v64, v65
	v_cvt_pk_bf16_f32 v65, v66, v67
	global_store_dwordx2 v[82:83], v[68:69], off
	global_store_dwordx2 v[82:83], v[64:65], off offset:128
	global_load_dwordx4 v[64:67], v[84:85], off
	s_nop 0
	global_load_dwordx4 v[68:71], v[84:85], off offset:32
	global_load_dwordx4 v[72:75], v[84:85], off offset:16
	global_load_dwordx4 v[76:79], v[84:85], off offset:48
	v_add_u32_e32 v80, 0x90, v146
	v_ashrrev_i32_e32 v81, 31, v80
	v_lshlrev_b64 v[82:83], 6, v[80:81]
	s_waitcnt vmcnt(3)
	v_mov_b32_e32 v84, v64
	s_waitcnt vmcnt(2)
	v_mov_b32_e32 v85, v68
	v_mov_b32_e32 v68, v65
	v_mov_b32_e32 v64, v66
	v_mov_b32_e32 v65, v70
	v_mov_b32_e32 v70, v67
	s_waitcnt vmcnt(1)
	v_mov_b32_e32 v66, v72
	s_waitcnt vmcnt(0)
	v_mov_b32_e32 v67, v76
	v_mov_b32_e32 v76, v73
	v_mov_b32_e32 v72, v74
	v_mov_b32_e32 v73, v78
	v_mov_b32_e32 v78, v75
	v_pk_add_f32 v[68:69], v[84:85], v[68:69]
	v_pk_add_f32 v[64:65], v[64:65], v[70:71]
	v_pk_add_f32 v[66:67], v[66:67], v[76:77]
	v_pk_add_f32 v[70:71], v[72:73], v[78:79]
	v_pk_add_f32 v[64:65], v[68:69], v[64:65]
	v_pk_add_f32 v[66:67], v[66:67], v[70:71]
	v_lshl_add_u64 v[68:69], s[30:31], 0, v[82:83]
	v_pk_add_f32 v[64:65], v[64:65], v[66:67]
	v_mad_i64_i32 v[66:67], s[36:37], v96, s57, v[144:145]
	v_add_f32_e32 v64, v64, v65
	v_fmamk_f32 v64, v64, 0x3a800000, v152
	v_rsq_f32_e32 v64, v64
	s_nop 0
	v_mov_b32_e32 v232, v64
	v_pk_mul_f32 v[60:61], v[60:61], v[64:65] op_sel_hi:[1,0]
	v_pk_mul_f32 v[62:63], v[62:63], v[64:65] op_sel_hi:[1,0]
	v_pk_mul_f32 v[56:57], v[56:57], v[64:65] op_sel_hi:[1,0]
	v_pk_mul_f32 v[58:59], v[58:59], v[64:65] op_sel_hi:[1,0]
	v_pk_mul_f32 v[52:53], v[52:53], v[64:65] op_sel_hi:[1,0]
	v_pk_mul_f32 v[48:49], v[48:49], v[64:65] op_sel_hi:[1,0]
	v_pk_mul_f32 v[54:55], v[54:55], v[64:65] op_sel_hi:[1,0]
	v_pk_mul_f32 v[50:51], v[50:51], v[64:65] op_sel_hi:[1,0]
	v_mul_f32_e32 v64, 0xbfb8aa3b, v60
	v_mul_f32_e32 v65, 0xbfb8aa3b, v61
	v_mul_f32_e32 v70, 0xbfb8aa3b, v62
	v_mul_f32_e32 v71, 0xbfb8aa3b, v63
	v_mul_f32_e32 v72, 0xbfb8aa3b, v52
	v_mul_f32_e32 v73, 0xbfb8aa3b, v53
	v_mul_f32_e32 v74, 0xbfb8aa3b, v54
	v_mul_f32_e32 v75, 0xbfb8aa3b, v55
	v_exp_f32_e32 v64, v64
	v_exp_f32_e32 v65, v65
	v_exp_f32_e32 v70, v70
	v_exp_f32_e32 v71, v71
	v_exp_f32_e32 v72, v72
	v_exp_f32_e32 v73, v73
	v_exp_f32_e32 v74, v74
	v_exp_f32_e32 v75, v75
	v_add_f32_e32 v64, 1.0, v64
	v_add_f32_e32 v65, 1.0, v65
	v_add_f32_e32 v70, 1.0, v70
	v_add_f32_e32 v71, 1.0, v71
	v_add_f32_e32 v72, 1.0, v72
	v_add_f32_e32 v73, 1.0, v73
	v_add_f32_e32 v74, 1.0, v74
	v_add_f32_e32 v75, 1.0, v75
	v_rcp_f32_e32 v64, v64
	v_rcp_f32_e32 v65, v65
	v_rcp_f32_e32 v70, v70
	v_rcp_f32_e32 v71, v71
	v_rcp_f32_e32 v72, v72
	v_rcp_f32_e32 v73, v73
	v_rcp_f32_e32 v74, v74
	v_rcp_f32_e32 v75, v75
	v_pk_mul_f32 v[60:61], v[60:61], v[64:65]
	v_pk_mul_f32 v[62:63], v[62:63], v[70:71]
	v_pk_mul_f32 v[52:53], v[52:53], v[72:73]
	v_pk_mul_f32 v[54:55], v[54:55], v[74:75]
	v_pk_mul_f32 v[56:57], v[56:57], v[60:61]
	v_pk_mul_f32 v[58:59], v[58:59], v[62:63]
	v_pk_mul_f32 v[48:49], v[48:49], v[52:53]
	v_pk_mul_f32 v[50:51], v[50:51], v[54:55]
	v_cvt_pk_bf16_f32 v52, v56, v57
	v_cvt_pk_bf16_f32 v53, v58, v59
	v_cvt_pk_bf16_f32 v48, v48, v49
	v_cvt_pk_bf16_f32 v49, v50, v51
	global_store_dwordx2 v[66:67], v[52:53], off
	global_store_dwordx2 v[66:67], v[48:49], off offset:128
	global_load_dwordx4 v[48:51], v[68:69], off
	s_nop 0
	global_load_dwordx4 v[52:55], v[68:69], off offset:32
	global_load_dwordx4 v[56:59], v[68:69], off offset:16
	global_load_dwordx4 v[60:63], v[68:69], off offset:48
	v_add_u32_e32 v64, 0xa0, v146
	v_ashrrev_i32_e32 v65, 31, v64
	v_lshlrev_b64 v[66:67], 6, v[64:65]
	s_waitcnt vmcnt(3)
	v_mov_b32_e32 v68, v48
	s_waitcnt vmcnt(2)
	v_mov_b32_e32 v69, v52
	v_mov_b32_e32 v52, v49
	v_mov_b32_e32 v48, v50
	v_mov_b32_e32 v49, v54
	v_mov_b32_e32 v54, v51
	s_waitcnt vmcnt(1)
	v_mov_b32_e32 v50, v56
	s_waitcnt vmcnt(0)
	v_mov_b32_e32 v51, v60
	v_mov_b32_e32 v60, v57
	v_mov_b32_e32 v56, v58
	v_mov_b32_e32 v57, v62
	v_mov_b32_e32 v62, v59
	v_pk_add_f32 v[52:53], v[68:69], v[52:53]
	v_pk_add_f32 v[48:49], v[48:49], v[54:55]
	v_pk_add_f32 v[50:51], v[50:51], v[60:61]
	v_pk_add_f32 v[54:55], v[56:57], v[62:63]
	v_pk_add_f32 v[48:49], v[52:53], v[48:49]
	v_pk_add_f32 v[50:51], v[50:51], v[54:55]
	v_lshl_add_u64 v[52:53], s[30:31], 0, v[66:67]
	v_pk_add_f32 v[48:49], v[48:49], v[50:51]
	v_mad_i64_i32 v[50:51], s[36:37], v80, s57, v[144:145]
	v_add_f32_e32 v48, v48, v49
	v_fmamk_f32 v48, v48, 0x3a800000, v152
	v_rsq_f32_e32 v48, v48
	s_nop 0
	v_mov_b32_e32 v233, v48
	v_pk_mul_f32 v[44:45], v[44:45], v[48:49] op_sel_hi:[1,0]
	v_pk_mul_f32 v[46:47], v[46:47], v[48:49] op_sel_hi:[1,0]
	v_pk_mul_f32 v[40:41], v[40:41], v[48:49] op_sel_hi:[1,0]
	v_pk_mul_f32 v[42:43], v[42:43], v[48:49] op_sel_hi:[1,0]
	v_pk_mul_f32 v[36:37], v[36:37], v[48:49] op_sel_hi:[1,0]
	v_pk_mul_f32 v[32:33], v[32:33], v[48:49] op_sel_hi:[1,0]
	v_pk_mul_f32 v[38:39], v[38:39], v[48:49] op_sel_hi:[1,0]
	v_pk_mul_f32 v[34:35], v[34:35], v[48:49] op_sel_hi:[1,0]
	v_mul_f32_e32 v48, 0xbfb8aa3b, v44
	v_mul_f32_e32 v49, 0xbfb8aa3b, v45
	v_mul_f32_e32 v54, 0xbfb8aa3b, v46
	v_mul_f32_e32 v55, 0xbfb8aa3b, v47
	v_mul_f32_e32 v56, 0xbfb8aa3b, v36
	v_mul_f32_e32 v57, 0xbfb8aa3b, v37
	v_mul_f32_e32 v58, 0xbfb8aa3b, v38
	v_mul_f32_e32 v59, 0xbfb8aa3b, v39
	v_exp_f32_e32 v48, v48
	v_exp_f32_e32 v49, v49
	v_exp_f32_e32 v54, v54
	v_exp_f32_e32 v55, v55
	v_exp_f32_e32 v56, v56
	v_exp_f32_e32 v57, v57
	v_exp_f32_e32 v58, v58
	v_exp_f32_e32 v59, v59
	v_add_f32_e32 v48, 1.0, v48
	v_add_f32_e32 v49, 1.0, v49
	v_add_f32_e32 v54, 1.0, v54
	v_add_f32_e32 v55, 1.0, v55
	v_add_f32_e32 v56, 1.0, v56
	v_add_f32_e32 v57, 1.0, v57
	v_add_f32_e32 v58, 1.0, v58
	v_add_f32_e32 v59, 1.0, v59
	v_rcp_f32_e32 v48, v48
	v_rcp_f32_e32 v49, v49
	v_rcp_f32_e32 v54, v54
	v_rcp_f32_e32 v55, v55
	v_rcp_f32_e32 v56, v56
	v_rcp_f32_e32 v57, v57
	v_rcp_f32_e32 v58, v58
	v_rcp_f32_e32 v59, v59
	v_pk_mul_f32 v[44:45], v[44:45], v[48:49]
	v_pk_mul_f32 v[46:47], v[46:47], v[54:55]
	v_pk_mul_f32 v[36:37], v[36:37], v[56:57]
	v_pk_mul_f32 v[38:39], v[38:39], v[58:59]
	v_pk_mul_f32 v[40:41], v[40:41], v[44:45]
	v_pk_mul_f32 v[42:43], v[42:43], v[46:47]
	v_pk_mul_f32 v[32:33], v[32:33], v[36:37]
	v_pk_mul_f32 v[34:35], v[34:35], v[38:39]
	v_cvt_pk_bf16_f32 v36, v40, v41
	v_cvt_pk_bf16_f32 v37, v42, v43
	v_cvt_pk_bf16_f32 v32, v32, v33
	v_cvt_pk_bf16_f32 v33, v34, v35
	global_store_dwordx2 v[50:51], v[36:37], off
	global_store_dwordx2 v[50:51], v[32:33], off offset:128
	global_load_dwordx4 v[32:35], v[52:53], off
	s_nop 0
	global_load_dwordx4 v[36:39], v[52:53], off offset:32
	global_load_dwordx4 v[40:43], v[52:53], off offset:16
	global_load_dwordx4 v[44:47], v[52:53], off offset:48
	v_add_u32_e32 v48, 0xb0, v146
	v_ashrrev_i32_e32 v49, 31, v48
	v_lshlrev_b64 v[50:51], 6, v[48:49]
	s_waitcnt vmcnt(3)
	v_mov_b32_e32 v52, v32
	s_waitcnt vmcnt(2)
	v_mov_b32_e32 v53, v36
	v_mov_b32_e32 v36, v33
	v_mov_b32_e32 v32, v34
	v_mov_b32_e32 v33, v38
	v_mov_b32_e32 v38, v35
	s_waitcnt vmcnt(1)
	v_mov_b32_e32 v34, v40
	s_waitcnt vmcnt(0)
	v_mov_b32_e32 v35, v44
	v_mov_b32_e32 v44, v41
	v_mov_b32_e32 v40, v42
	v_mov_b32_e32 v41, v46
	v_mov_b32_e32 v46, v43
	v_pk_add_f32 v[36:37], v[52:53], v[36:37]
	v_pk_add_f32 v[32:33], v[32:33], v[38:39]
	v_pk_add_f32 v[34:35], v[34:35], v[44:45]
	v_pk_add_f32 v[38:39], v[40:41], v[46:47]
	v_pk_add_f32 v[32:33], v[36:37], v[32:33]
	v_pk_add_f32 v[34:35], v[34:35], v[38:39]
	v_lshl_add_u64 v[36:37], s[30:31], 0, v[50:51]
	v_pk_add_f32 v[32:33], v[32:33], v[34:35]
	v_mad_i64_i32 v[34:35], s[36:37], v64, s57, v[144:145]
	v_add_f32_e32 v32, v32, v33
	v_fmamk_f32 v32, v32, 0x3a800000, v152
	v_rsq_f32_e32 v32, v32
	s_nop 0
	v_mov_b32_e32 v234, v32
	v_pk_mul_f32 v[28:29], v[28:29], v[32:33] op_sel_hi:[1,0]
	v_pk_mul_f32 v[30:31], v[30:31], v[32:33] op_sel_hi:[1,0]
	v_pk_mul_f32 v[24:25], v[24:25], v[32:33] op_sel_hi:[1,0]
	v_pk_mul_f32 v[26:27], v[26:27], v[32:33] op_sel_hi:[1,0]
	v_pk_mul_f32 v[20:21], v[20:21], v[32:33] op_sel_hi:[1,0]
	v_pk_mul_f32 v[16:17], v[16:17], v[32:33] op_sel_hi:[1,0]
	v_pk_mul_f32 v[22:23], v[22:23], v[32:33] op_sel_hi:[1,0]
	v_pk_mul_f32 v[18:19], v[18:19], v[32:33] op_sel_hi:[1,0]
	v_mul_f32_e32 v32, 0xbfb8aa3b, v28
	v_mul_f32_e32 v33, 0xbfb8aa3b, v29
	v_mul_f32_e32 v38, 0xbfb8aa3b, v30
	v_mul_f32_e32 v39, 0xbfb8aa3b, v31
	v_mul_f32_e32 v40, 0xbfb8aa3b, v20
	v_mul_f32_e32 v41, 0xbfb8aa3b, v21
	v_mul_f32_e32 v42, 0xbfb8aa3b, v22
	v_mul_f32_e32 v43, 0xbfb8aa3b, v23
	v_exp_f32_e32 v32, v32
	v_exp_f32_e32 v33, v33
	v_exp_f32_e32 v38, v38
	v_exp_f32_e32 v39, v39
	v_exp_f32_e32 v40, v40
	v_exp_f32_e32 v41, v41
	v_exp_f32_e32 v42, v42
	v_exp_f32_e32 v43, v43
	v_add_f32_e32 v32, 1.0, v32
	v_add_f32_e32 v33, 1.0, v33
	v_add_f32_e32 v38, 1.0, v38
	v_add_f32_e32 v39, 1.0, v39
	v_add_f32_e32 v40, 1.0, v40
	v_add_f32_e32 v41, 1.0, v41
	v_add_f32_e32 v42, 1.0, v42
	v_add_f32_e32 v43, 1.0, v43
	v_rcp_f32_e32 v32, v32
	v_rcp_f32_e32 v33, v33
	v_rcp_f32_e32 v38, v38
	v_rcp_f32_e32 v39, v39
	v_rcp_f32_e32 v40, v40
	v_rcp_f32_e32 v41, v41
	v_rcp_f32_e32 v42, v42
	v_rcp_f32_e32 v43, v43
	v_pk_mul_f32 v[28:29], v[28:29], v[32:33]
	v_pk_mul_f32 v[30:31], v[30:31], v[38:39]
	v_pk_mul_f32 v[20:21], v[20:21], v[40:41]
	v_pk_mul_f32 v[22:23], v[22:23], v[42:43]
	v_pk_mul_f32 v[24:25], v[24:25], v[28:29]
	v_pk_mul_f32 v[26:27], v[26:27], v[30:31]
	v_pk_mul_f32 v[16:17], v[16:17], v[20:21]
	v_pk_mul_f32 v[18:19], v[18:19], v[22:23]
	v_cvt_pk_bf16_f32 v20, v24, v25
	v_cvt_pk_bf16_f32 v21, v26, v27
	v_cvt_pk_bf16_f32 v16, v16, v17
	v_cvt_pk_bf16_f32 v17, v18, v19
	global_store_dwordx2 v[34:35], v[20:21], off
	global_store_dwordx2 v[34:35], v[16:17], off offset:128
	global_load_dwordx4 v[16:19], v[36:37], off
	s_nop 0
	global_load_dwordx4 v[20:23], v[36:37], off offset:32
	global_load_dwordx4 v[24:27], v[36:37], off offset:16
	global_load_dwordx4 v[28:31], v[36:37], off offset:48
	s_waitcnt vmcnt(3)
	v_mov_b32_e32 v32, v16
	s_waitcnt vmcnt(2)
	v_mov_b32_e32 v33, v20
	v_mov_b32_e32 v20, v17
	v_mov_b32_e32 v16, v18
	v_mov_b32_e32 v17, v22
	v_mov_b32_e32 v22, v19
	s_waitcnt vmcnt(1)
	v_mov_b32_e32 v18, v24
	s_waitcnt vmcnt(0)
	v_mov_b32_e32 v19, v28
	v_mov_b32_e32 v28, v25
	v_mov_b32_e32 v24, v26
	v_mov_b32_e32 v25, v30
	v_mov_b32_e32 v30, v27
	v_pk_add_f32 v[20:21], v[32:33], v[20:21]
	v_pk_add_f32 v[16:17], v[16:17], v[22:23]
	v_pk_add_f32 v[18:19], v[18:19], v[28:29]
	v_pk_add_f32 v[22:23], v[24:25], v[30:31]
	v_pk_add_f32 v[16:17], v[20:21], v[16:17]
	v_pk_add_f32 v[18:19], v[18:19], v[22:23]
	s_nop 0
	v_pk_add_f32 v[16:17], v[16:17], v[18:19]
	v_mad_i64_i32 v[18:19], s[4:5], v48, s57, v[144:145]
	v_add_f32_e32 v16, v16, v17
	v_fmamk_f32 v16, v16, 0x3a800000, v152
	v_rsq_f32_e32 v16, v16
	s_mov_b64 s[4:5], -1
	v_mov_b32_e32 v235, v16
	v_pk_mul_f32 v[12:13], v[12:13], v[16:17] op_sel_hi:[1,0]
	v_pk_mul_f32 v[14:15], v[14:15], v[16:17] op_sel_hi:[1,0]
	v_pk_mul_f32 v[8:9], v[8:9], v[16:17] op_sel_hi:[1,0]
	v_pk_mul_f32 v[10:11], v[10:11], v[16:17] op_sel_hi:[1,0]
	v_pk_mul_f32 v[4:5], v[4:5], v[16:17] op_sel_hi:[1,0]
	v_pk_mul_f32 v[0:1], v[0:1], v[16:17] op_sel_hi:[1,0]
	v_pk_mul_f32 v[6:7], v[6:7], v[16:17] op_sel_hi:[1,0]
	v_pk_mul_f32 v[2:3], v[2:3], v[16:17] op_sel_hi:[1,0]
	v_mul_f32_e32 v16, 0xbfb8aa3b, v12
	v_mul_f32_e32 v17, 0xbfb8aa3b, v13
	v_mul_f32_e32 v20, 0xbfb8aa3b, v14
	v_mul_f32_e32 v21, 0xbfb8aa3b, v15
	v_mul_f32_e32 v22, 0xbfb8aa3b, v4
	v_mul_f32_e32 v23, 0xbfb8aa3b, v5
	v_mul_f32_e32 v24, 0xbfb8aa3b, v6
	v_mul_f32_e32 v25, 0xbfb8aa3b, v7
	v_exp_f32_e32 v16, v16
	v_exp_f32_e32 v17, v17
	v_exp_f32_e32 v20, v20
	v_exp_f32_e32 v21, v21
	v_exp_f32_e32 v22, v22
	v_exp_f32_e32 v23, v23
	v_exp_f32_e32 v24, v24
	v_exp_f32_e32 v25, v25
	v_add_f32_e32 v16, 1.0, v16
	v_add_f32_e32 v17, 1.0, v17
	v_add_f32_e32 v20, 1.0, v20
	v_add_f32_e32 v21, 1.0, v21
	v_add_f32_e32 v22, 1.0, v22
	v_add_f32_e32 v23, 1.0, v23
	v_add_f32_e32 v24, 1.0, v24
	v_add_f32_e32 v25, 1.0, v25
	v_rcp_f32_e32 v16, v16
	v_rcp_f32_e32 v17, v17
	v_rcp_f32_e32 v20, v20
	v_rcp_f32_e32 v21, v21
	v_rcp_f32_e32 v22, v22
	v_rcp_f32_e32 v23, v23
	v_rcp_f32_e32 v24, v24
	v_rcp_f32_e32 v25, v25
	v_pk_mul_f32 v[12:13], v[12:13], v[16:17]
	v_pk_mul_f32 v[14:15], v[14:15], v[20:21]
	v_pk_mul_f32 v[4:5], v[4:5], v[22:23]
	v_pk_mul_f32 v[6:7], v[6:7], v[24:25]
	v_pk_mul_f32 v[8:9], v[8:9], v[12:13]
	v_pk_mul_f32 v[10:11], v[10:11], v[14:15]
	v_pk_mul_f32 v[0:1], v[0:1], v[4:5]
	v_pk_mul_f32 v[2:3], v[2:3], v[6:7]
	v_cvt_pk_bf16_f32 v4, v8, v9
	v_cvt_pk_bf16_f32 v5, v10, v11
	v_cvt_pk_bf16_f32 v0, v0, v1
	v_cvt_pk_bf16_f32 v1, v2, v3
	global_store_dwordx2 v[18:19], v[4:5], off
	global_store_dwordx2 v[18:19], v[0:1], off offset:128
	s_cbranch_vccnz .LBB0_679

.Lgu0_fast:
	s_andn2_b64 vcc, exec, s[4:5]
	s_load_dwordx2 s[36:37], s[0:1], 0x138
	s_mov_b32 s94, 0x16000
	s_mov_b32 s95, 0
	s_mov_b32 s96, 0x6e000
	s_mov_b32 s97, 0
	s_lshl_b32 s17, s34, 8
	s_add_i32 s17, s17, s50
	v_and_or_b32 v146, v154, 15, s17
	v_lshrrev_b32_e32 v144, 2, v154
	s_lshl_b32 s17, s58, 7
	s_or_b32 s17, s17, s53
	v_and_or_b32 v144, v144, 12, s17
	v_ashrrev_i32_e32 v145, 31, v144
	s_waitcnt lgkmcnt(0)
	v_lshl_add_u64 v[144:145], v[144:145], 1, s[36:37]
	v_lshl_add_u64 v[144:145], v[144:145], 0, s[14:15]
	v_mad_i64_i32 v[144:145], s[36:37], v146, s57, v[144:145]
	v_pk_mul_f32 v[124:125], v[124:125], v[228:229] op_sel_hi:[1,0]
	v_pk_mul_f32 v[126:127], v[126:127], v[228:229] op_sel_hi:[1,0]
	v_pk_mul_f32 v[120:121], v[120:121], v[228:229] op_sel_hi:[1,0]
	v_pk_mul_f32 v[122:123], v[122:123], v[228:229] op_sel_hi:[1,0]
	v_pk_mul_f32 v[116:117], v[116:117], v[228:229] op_sel_hi:[1,0]
	v_pk_mul_f32 v[118:119], v[118:119], v[228:229] op_sel_hi:[1,0]
	v_pk_mul_f32 v[112:113], v[112:113], v[228:229] op_sel_hi:[1,0]
	v_pk_mul_f32 v[114:115], v[114:115], v[228:229] op_sel_hi:[1,0]
	v_mul_f32_e32 v156, 0xbfb8aa3b, v124
	v_mul_f32_e32 v157, 0xbfb8aa3b, v125
	v_mul_f32_e32 v158, 0xbfb8aa3b, v126
	v_mul_f32_e32 v159, 0xbfb8aa3b, v127
	v_mul_f32_e32 v160, 0xbfb8aa3b, v116
	v_mul_f32_e32 v161, 0xbfb8aa3b, v117
	v_mul_f32_e32 v162, 0xbfb8aa3b, v118
	v_mul_f32_e32 v163, 0xbfb8aa3b, v119
	v_exp_f32_e32 v156, v156
	v_exp_f32_e32 v157, v157
	v_exp_f32_e32 v158, v158
	v_exp_f32_e32 v159, v159
	v_exp_f32_e32 v160, v160
	v_exp_f32_e32 v161, v161
	v_exp_f32_e32 v162, v162
	v_exp_f32_e32 v163, v163
	v_add_f32_e32 v156, 1.0, v156
	v_add_f32_e32 v157, 1.0, v157
	v_add_f32_e32 v158, 1.0, v158
	v_add_f32_e32 v159, 1.0, v159
	v_add_f32_e32 v160, 1.0, v160
	v_add_f32_e32 v161, 1.0, v161
	v_add_f32_e32 v162, 1.0, v162
	v_add_f32_e32 v163, 1.0, v163
	v_rcp_f32_e32 v156, v156
	v_rcp_f32_e32 v157, v157
	v_rcp_f32_e32 v158, v158
	v_rcp_f32_e32 v159, v159
	v_rcp_f32_e32 v160, v160
	v_rcp_f32_e32 v161, v161
	v_rcp_f32_e32 v162, v162
	v_rcp_f32_e32 v163, v163
	v_pk_mul_f32 v[124:125], v[124:125], v[156:157]
	v_pk_mul_f32 v[126:127], v[126:127], v[158:159]
	v_pk_mul_f32 v[116:117], v[116:117], v[160:161]
	v_pk_mul_f32 v[118:119], v[118:119], v[162:163]
	v_pk_mul_f32 v[120:121], v[120:121], v[124:125]
	v_pk_mul_f32 v[122:123], v[122:123], v[126:127]
	v_pk_mul_f32 v[112:113], v[112:113], v[116:117]
	v_pk_mul_f32 v[114:115], v[114:115], v[118:119]
	v_cvt_pk_bf16_f32 v156, v120, v121
	v_cvt_pk_bf16_f32 v157, v122, v123
	v_cvt_pk_bf16_f32 v158, v112, v113
	v_cvt_pk_bf16_f32 v159, v114, v115
	global_store_dwordx2 v[144:145], v[156:157], off
	global_store_dwordx2 v[144:145], v[158:159], off offset:128
	v_lshl_add_u64 v[144:145], v[144:145], 0, s[94:95]
	v_pk_mul_f32 v[108:109], v[108:109], v[228:229] op_sel:[0,1] op_sel_hi:[1,1]
	v_pk_mul_f32 v[110:111], v[110:111], v[228:229] op_sel:[0,1] op_sel_hi:[1,1]
	v_pk_mul_f32 v[104:105], v[104:105], v[228:229] op_sel:[0,1] op_sel_hi:[1,1]
	v_pk_mul_f32 v[106:107], v[106:107], v[228:229] op_sel:[0,1] op_sel_hi:[1,1]
	v_pk_mul_f32 v[100:101], v[100:101], v[228:229] op_sel:[0,1] op_sel_hi:[1,1]
	v_pk_mul_f32 v[102:103], v[102:103], v[228:229] op_sel:[0,1] op_sel_hi:[1,1]
	v_pk_mul_f32 v[96:97], v[96:97], v[228:229] op_sel:[0,1] op_sel_hi:[1,1]
	v_pk_mul_f32 v[98:99], v[98:99], v[228:229] op_sel:[0,1] op_sel_hi:[1,1]
	v_mul_f32_e32 v156, 0xbfb8aa3b, v108
	v_mul_f32_e32 v157, 0xbfb8aa3b, v109
	v_mul_f32_e32 v158, 0xbfb8aa3b, v110
	v_mul_f32_e32 v159, 0xbfb8aa3b, v111
	v_mul_f32_e32 v160, 0xbfb8aa3b, v100
	v_mul_f32_e32 v161, 0xbfb8aa3b, v101
	v_mul_f32_e32 v162, 0xbfb8aa3b, v102
	v_mul_f32_e32 v163, 0xbfb8aa3b, v103
	v_exp_f32_e32 v156, v156
	v_exp_f32_e32 v157, v157
	v_exp_f32_e32 v158, v158
	v_exp_f32_e32 v159, v159
	v_exp_f32_e32 v160, v160
	v_exp_f32_e32 v161, v161
	v_exp_f32_e32 v162, v162
	v_exp_f32_e32 v163, v163
	v_add_f32_e32 v156, 1.0, v156
	v_add_f32_e32 v157, 1.0, v157
	v_add_f32_e32 v158, 1.0, v158
	v_add_f32_e32 v159, 1.0, v159
	v_add_f32_e32 v160, 1.0, v160
	v_add_f32_e32 v161, 1.0, v161
	v_add_f32_e32 v162, 1.0, v162
	v_add_f32_e32 v163, 1.0, v163
	v_rcp_f32_e32 v156, v156
	v_rcp_f32_e32 v157, v157
	v_rcp_f32_e32 v158, v158
	v_rcp_f32_e32 v159, v159
	v_rcp_f32_e32 v160, v160
	v_rcp_f32_e32 v161, v161
	v_rcp_f32_e32 v162, v162
	v_rcp_f32_e32 v163, v163
	v_pk_mul_f32 v[108:109], v[108:109], v[156:157]
	v_pk_mul_f32 v[110:111], v[110:111], v[158:159]
	v_pk_mul_f32 v[100:101], v[100:101], v[160:161]
	v_pk_mul_f32 v[102:103], v[102:103], v[162:163]
	v_pk_mul_f32 v[104:105], v[104:105], v[108:109]
	v_pk_mul_f32 v[106:107], v[106:107], v[110:111]
	v_pk_mul_f32 v[96:97], v[96:97], v[100:101]
	v_pk_mul_f32 v[98:99], v[98:99], v[102:103]
	v_cvt_pk_bf16_f32 v156, v104, v105
	v_cvt_pk_bf16_f32 v157, v106, v107
	v_cvt_pk_bf16_f32 v158, v96, v97
	v_cvt_pk_bf16_f32 v159, v98, v99
	global_store_dwordx2 v[144:145], v[156:157], off
	global_store_dwordx2 v[144:145], v[158:159], off offset:128
	v_lshl_add_u64 v[144:145], v[144:145], 0, s[94:95]
	v_pk_mul_f32 v[92:93], v[92:93], v[230:231] op_sel_hi:[1,0]
	v_pk_mul_f32 v[94:95], v[94:95], v[230:231] op_sel_hi:[1,0]
	v_pk_mul_f32 v[88:89], v[88:89], v[230:231] op_sel_hi:[1,0]
	v_pk_mul_f32 v[90:91], v[90:91], v[230:231] op_sel_hi:[1,0]
	v_pk_mul_f32 v[84:85], v[84:85], v[230:231] op_sel_hi:[1,0]
	v_pk_mul_f32 v[86:87], v[86:87], v[230:231] op_sel_hi:[1,0]
	v_pk_mul_f32 v[80:81], v[80:81], v[230:231] op_sel_hi:[1,0]
	v_pk_mul_f32 v[82:83], v[82:83], v[230:231] op_sel_hi:[1,0]
	v_mul_f32_e32 v156, 0xbfb8aa3b, v92
	v_mul_f32_e32 v157, 0xbfb8aa3b, v93
	v_mul_f32_e32 v158, 0xbfb8aa3b, v94
	v_mul_f32_e32 v159, 0xbfb8aa3b, v95
	v_mul_f32_e32 v160, 0xbfb8aa3b, v84
	v_mul_f32_e32 v161, 0xbfb8aa3b, v85
	v_mul_f32_e32 v162, 0xbfb8aa3b, v86
	v_mul_f32_e32 v163, 0xbfb8aa3b, v87
	v_exp_f32_e32 v156, v156
	v_exp_f32_e32 v157, v157
	v_exp_f32_e32 v158, v158
	v_exp_f32_e32 v159, v159
	v_exp_f32_e32 v160, v160
	v_exp_f32_e32 v161, v161
	v_exp_f32_e32 v162, v162
	v_exp_f32_e32 v163, v163
	v_add_f32_e32 v156, 1.0, v156
	v_add_f32_e32 v157, 1.0, v157
	v_add_f32_e32 v158, 1.0, v158
	v_add_f32_e32 v159, 1.0, v159
	v_add_f32_e32 v160, 1.0, v160
	v_add_f32_e32 v161, 1.0, v161
	v_add_f32_e32 v162, 1.0, v162
	v_add_f32_e32 v163, 1.0, v163
	v_rcp_f32_e32 v156, v156
	v_rcp_f32_e32 v157, v157
	v_rcp_f32_e32 v158, v158
	v_rcp_f32_e32 v159, v159
	v_rcp_f32_e32 v160, v160
	v_rcp_f32_e32 v161, v161
	v_rcp_f32_e32 v162, v162
	v_rcp_f32_e32 v163, v163
	v_pk_mul_f32 v[92:93], v[92:93], v[156:157]
	v_pk_mul_f32 v[94:95], v[94:95], v[158:159]
	v_pk_mul_f32 v[84:85], v[84:85], v[160:161]
	v_pk_mul_f32 v[86:87], v[86:87], v[162:163]
	v_pk_mul_f32 v[88:89], v[88:89], v[92:93]
	v_pk_mul_f32 v[90:91], v[90:91], v[94:95]
	v_pk_mul_f32 v[80:81], v[80:81], v[84:85]
	v_pk_mul_f32 v[82:83], v[82:83], v[86:87]
	v_cvt_pk_bf16_f32 v156, v88, v89
	v_cvt_pk_bf16_f32 v157, v90, v91
	v_cvt_pk_bf16_f32 v158, v80, v81
	v_cvt_pk_bf16_f32 v159, v82, v83
	global_store_dwordx2 v[144:145], v[156:157], off
	global_store_dwordx2 v[144:145], v[158:159], off offset:128
	v_lshl_add_u64 v[144:145], v[144:145], 0, s[94:95]
	v_pk_mul_f32 v[76:77], v[76:77], v[230:231] op_sel:[0,1] op_sel_hi:[1,1]
	v_pk_mul_f32 v[78:79], v[78:79], v[230:231] op_sel:[0,1] op_sel_hi:[1,1]
	v_pk_mul_f32 v[72:73], v[72:73], v[230:231] op_sel:[0,1] op_sel_hi:[1,1]
	v_pk_mul_f32 v[74:75], v[74:75], v[230:231] op_sel:[0,1] op_sel_hi:[1,1]
	v_pk_mul_f32 v[68:69], v[68:69], v[230:231] op_sel:[0,1] op_sel_hi:[1,1]
	v_pk_mul_f32 v[70:71], v[70:71], v[230:231] op_sel:[0,1] op_sel_hi:[1,1]
	v_pk_mul_f32 v[64:65], v[64:65], v[230:231] op_sel:[0,1] op_sel_hi:[1,1]
	v_pk_mul_f32 v[66:67], v[66:67], v[230:231] op_sel:[0,1] op_sel_hi:[1,1]
	v_mul_f32_e32 v156, 0xbfb8aa3b, v76
	v_mul_f32_e32 v157, 0xbfb8aa3b, v77
	v_mul_f32_e32 v158, 0xbfb8aa3b, v78
	v_mul_f32_e32 v159, 0xbfb8aa3b, v79
	v_mul_f32_e32 v160, 0xbfb8aa3b, v68
	v_mul_f32_e32 v161, 0xbfb8aa3b, v69
	v_mul_f32_e32 v162, 0xbfb8aa3b, v70
	v_mul_f32_e32 v163, 0xbfb8aa3b, v71
	v_exp_f32_e32 v156, v156
	v_exp_f32_e32 v157, v157
	v_exp_f32_e32 v158, v158
	v_exp_f32_e32 v159, v159
	v_exp_f32_e32 v160, v160
	v_exp_f32_e32 v161, v161
	v_exp_f32_e32 v162, v162
	v_exp_f32_e32 v163, v163
	v_add_f32_e32 v156, 1.0, v156
	v_add_f32_e32 v157, 1.0, v157
	v_add_f32_e32 v158, 1.0, v158
	v_add_f32_e32 v159, 1.0, v159
	v_add_f32_e32 v160, 1.0, v160
	v_add_f32_e32 v161, 1.0, v161
	v_add_f32_e32 v162, 1.0, v162
	v_add_f32_e32 v163, 1.0, v163
	v_rcp_f32_e32 v156, v156
	v_rcp_f32_e32 v157, v157
	v_rcp_f32_e32 v158, v158
	v_rcp_f32_e32 v159, v159
	v_rcp_f32_e32 v160, v160
	v_rcp_f32_e32 v161, v161
	v_rcp_f32_e32 v162, v162
	v_rcp_f32_e32 v163, v163
	v_pk_mul_f32 v[76:77], v[76:77], v[156:157]
	v_pk_mul_f32 v[78:79], v[78:79], v[158:159]
	v_pk_mul_f32 v[68:69], v[68:69], v[160:161]
	v_pk_mul_f32 v[70:71], v[70:71], v[162:163]
	v_pk_mul_f32 v[72:73], v[72:73], v[76:77]
	v_pk_mul_f32 v[74:75], v[74:75], v[78:79]
	v_pk_mul_f32 v[64:65], v[64:65], v[68:69]
	v_pk_mul_f32 v[66:67], v[66:67], v[70:71]
	v_cvt_pk_bf16_f32 v156, v72, v73
	v_cvt_pk_bf16_f32 v157, v74, v75
	v_cvt_pk_bf16_f32 v158, v64, v65
	v_cvt_pk_bf16_f32 v159, v66, v67
	global_store_dwordx2 v[144:145], v[156:157], off
	global_store_dwordx2 v[144:145], v[158:159], off offset:128
	v_lshl_add_u64 v[144:145], v[144:145], 0, s[96:97]
	v_pk_mul_f32 v[60:61], v[60:61], v[232:233] op_sel_hi:[1,0]
	v_pk_mul_f32 v[62:63], v[62:63], v[232:233] op_sel_hi:[1,0]
	v_pk_mul_f32 v[56:57], v[56:57], v[232:233] op_sel_hi:[1,0]
	v_pk_mul_f32 v[58:59], v[58:59], v[232:233] op_sel_hi:[1,0]
	v_pk_mul_f32 v[52:53], v[52:53], v[232:233] op_sel_hi:[1,0]
	v_pk_mul_f32 v[54:55], v[54:55], v[232:233] op_sel_hi:[1,0]
	v_pk_mul_f32 v[48:49], v[48:49], v[232:233] op_sel_hi:[1,0]
	v_pk_mul_f32 v[50:51], v[50:51], v[232:233] op_sel_hi:[1,0]
	v_mul_f32_e32 v156, 0xbfb8aa3b, v60
	v_mul_f32_e32 v157, 0xbfb8aa3b, v61
	v_mul_f32_e32 v158, 0xbfb8aa3b, v62
	v_mul_f32_e32 v159, 0xbfb8aa3b, v63
	v_mul_f32_e32 v160, 0xbfb8aa3b, v52
	v_mul_f32_e32 v161, 0xbfb8aa3b, v53
	v_mul_f32_e32 v162, 0xbfb8aa3b, v54
	v_mul_f32_e32 v163, 0xbfb8aa3b, v55
	v_exp_f32_e32 v156, v156
	v_exp_f32_e32 v157, v157
	v_exp_f32_e32 v158, v158
	v_exp_f32_e32 v159, v159
	v_exp_f32_e32 v160, v160
	v_exp_f32_e32 v161, v161
	v_exp_f32_e32 v162, v162
	v_exp_f32_e32 v163, v163
	v_add_f32_e32 v156, 1.0, v156
	v_add_f32_e32 v157, 1.0, v157
	v_add_f32_e32 v158, 1.0, v158
	v_add_f32_e32 v159, 1.0, v159
	v_add_f32_e32 v160, 1.0, v160
	v_add_f32_e32 v161, 1.0, v161
	v_add_f32_e32 v162, 1.0, v162
	v_add_f32_e32 v163, 1.0, v163
	v_rcp_f32_e32 v156, v156
	v_rcp_f32_e32 v157, v157
	v_rcp_f32_e32 v158, v158
	v_rcp_f32_e32 v159, v159
	v_rcp_f32_e32 v160, v160
	v_rcp_f32_e32 v161, v161
	v_rcp_f32_e32 v162, v162
	v_rcp_f32_e32 v163, v163
	v_pk_mul_f32 v[60:61], v[60:61], v[156:157]
	v_pk_mul_f32 v[62:63], v[62:63], v[158:159]
	v_pk_mul_f32 v[52:53], v[52:53], v[160:161]
	v_pk_mul_f32 v[54:55], v[54:55], v[162:163]
	v_pk_mul_f32 v[56:57], v[56:57], v[60:61]
	v_pk_mul_f32 v[58:59], v[58:59], v[62:63]
	v_pk_mul_f32 v[48:49], v[48:49], v[52:53]
	v_pk_mul_f32 v[50:51], v[50:51], v[54:55]
	v_cvt_pk_bf16_f32 v156, v56, v57
	v_cvt_pk_bf16_f32 v157, v58, v59
	v_cvt_pk_bf16_f32 v158, v48, v49
	v_cvt_pk_bf16_f32 v159, v50, v51
	global_store_dwordx2 v[144:145], v[156:157], off
	global_store_dwordx2 v[144:145], v[158:159], off offset:128
	v_lshl_add_u64 v[144:145], v[144:145], 0, s[94:95]
	v_pk_mul_f32 v[44:45], v[44:45], v[232:233] op_sel:[0,1] op_sel_hi:[1,1]
	v_pk_mul_f32 v[46:47], v[46:47], v[232:233] op_sel:[0,1] op_sel_hi:[1,1]
	v_pk_mul_f32 v[40:41], v[40:41], v[232:233] op_sel:[0,1] op_sel_hi:[1,1]
	v_pk_mul_f32 v[42:43], v[42:43], v[232:233] op_sel:[0,1] op_sel_hi:[1,1]
	v_pk_mul_f32 v[36:37], v[36:37], v[232:233] op_sel:[0,1] op_sel_hi:[1,1]
	v_pk_mul_f32 v[38:39], v[38:39], v[232:233] op_sel:[0,1] op_sel_hi:[1,1]
	v_pk_mul_f32 v[32:33], v[32:33], v[232:233] op_sel:[0,1] op_sel_hi:[1,1]
	v_pk_mul_f32 v[34:35], v[34:35], v[232:233] op_sel:[0,1] op_sel_hi:[1,1]
	v_mul_f32_e32 v156, 0xbfb8aa3b, v44
	v_mul_f32_e32 v157, 0xbfb8aa3b, v45
	v_mul_f32_e32 v158, 0xbfb8aa3b, v46
	v_mul_f32_e32 v159, 0xbfb8aa3b, v47
	v_mul_f32_e32 v160, 0xbfb8aa3b, v36
	v_mul_f32_e32 v161, 0xbfb8aa3b, v37
	v_mul_f32_e32 v162, 0xbfb8aa3b, v38
	v_mul_f32_e32 v163, 0xbfb8aa3b, v39
	v_exp_f32_e32 v156, v156
	v_exp_f32_e32 v157, v157
	v_exp_f32_e32 v158, v158
	v_exp_f32_e32 v159, v159
	v_exp_f32_e32 v160, v160
	v_exp_f32_e32 v161, v161
	v_exp_f32_e32 v162, v162
	v_exp_f32_e32 v163, v163
	v_add_f32_e32 v156, 1.0, v156
	v_add_f32_e32 v157, 1.0, v157
	v_add_f32_e32 v158, 1.0, v158
	v_add_f32_e32 v159, 1.0, v159
	v_add_f32_e32 v160, 1.0, v160
	v_add_f32_e32 v161, 1.0, v161
	v_add_f32_e32 v162, 1.0, v162
	v_add_f32_e32 v163, 1.0, v163
	v_rcp_f32_e32 v156, v156
	v_rcp_f32_e32 v157, v157
	v_rcp_f32_e32 v158, v158
	v_rcp_f32_e32 v159, v159
	v_rcp_f32_e32 v160, v160
	v_rcp_f32_e32 v161, v161
	v_rcp_f32_e32 v162, v162
	v_rcp_f32_e32 v163, v163
	v_pk_mul_f32 v[44:45], v[44:45], v[156:157]
	v_pk_mul_f32 v[46:47], v[46:47], v[158:159]
	v_pk_mul_f32 v[36:37], v[36:37], v[160:161]
	v_pk_mul_f32 v[38:39], v[38:39], v[162:163]
	v_pk_mul_f32 v[40:41], v[40:41], v[44:45]
	v_pk_mul_f32 v[42:43], v[42:43], v[46:47]
	v_pk_mul_f32 v[32:33], v[32:33], v[36:37]
	v_pk_mul_f32 v[34:35], v[34:35], v[38:39]
	v_cvt_pk_bf16_f32 v156, v40, v41
	v_cvt_pk_bf16_f32 v157, v42, v43
	v_cvt_pk_bf16_f32 v158, v32, v33
	v_cvt_pk_bf16_f32 v159, v34, v35
	global_store_dwordx2 v[144:145], v[156:157], off
	global_store_dwordx2 v[144:145], v[158:159], off offset:128
	v_lshl_add_u64 v[144:145], v[144:145], 0, s[94:95]
	v_pk_mul_f32 v[28:29], v[28:29], v[234:235] op_sel_hi:[1,0]
	v_pk_mul_f32 v[30:31], v[30:31], v[234:235] op_sel_hi:[1,0]
	v_pk_mul_f32 v[24:25], v[24:25], v[234:235] op_sel_hi:[1,0]
	v_pk_mul_f32 v[26:27], v[26:27], v[234:235] op_sel_hi:[1,0]
	v_pk_mul_f32 v[20:21], v[20:21], v[234:235] op_sel_hi:[1,0]
	v_pk_mul_f32 v[22:23], v[22:23], v[234:235] op_sel_hi:[1,0]
	v_pk_mul_f32 v[16:17], v[16:17], v[234:235] op_sel_hi:[1,0]
	v_pk_mul_f32 v[18:19], v[18:19], v[234:235] op_sel_hi:[1,0]
	v_mul_f32_e32 v156, 0xbfb8aa3b, v28
	v_mul_f32_e32 v157, 0xbfb8aa3b, v29
	v_mul_f32_e32 v158, 0xbfb8aa3b, v30
	v_mul_f32_e32 v159, 0xbfb8aa3b, v31
	v_mul_f32_e32 v160, 0xbfb8aa3b, v20
	v_mul_f32_e32 v161, 0xbfb8aa3b, v21
	v_mul_f32_e32 v162, 0xbfb8aa3b, v22
	v_mul_f32_e32 v163, 0xbfb8aa3b, v23
	v_exp_f32_e32 v156, v156
	v_exp_f32_e32 v157, v157
	v_exp_f32_e32 v158, v158
	v_exp_f32_e32 v159, v159
	v_exp_f32_e32 v160, v160
	v_exp_f32_e32 v161, v161
	v_exp_f32_e32 v162, v162
	v_exp_f32_e32 v163, v163
	v_add_f32_e32 v156, 1.0, v156
	v_add_f32_e32 v157, 1.0, v157
	v_add_f32_e32 v158, 1.0, v158
	v_add_f32_e32 v159, 1.0, v159
	v_add_f32_e32 v160, 1.0, v160
	v_add_f32_e32 v161, 1.0, v161
	v_add_f32_e32 v162, 1.0, v162
	v_add_f32_e32 v163, 1.0, v163
	v_rcp_f32_e32 v156, v156
	v_rcp_f32_e32 v157, v157
	v_rcp_f32_e32 v158, v158
	v_rcp_f32_e32 v159, v159
	v_rcp_f32_e32 v160, v160
	v_rcp_f32_e32 v161, v161
	v_rcp_f32_e32 v162, v162
	v_rcp_f32_e32 v163, v163
	v_pk_mul_f32 v[28:29], v[28:29], v[156:157]
	v_pk_mul_f32 v[30:31], v[30:31], v[158:159]
	v_pk_mul_f32 v[20:21], v[20:21], v[160:161]
	v_pk_mul_f32 v[22:23], v[22:23], v[162:163]
	v_pk_mul_f32 v[24:25], v[24:25], v[28:29]
	v_pk_mul_f32 v[26:27], v[26:27], v[30:31]
	v_pk_mul_f32 v[16:17], v[16:17], v[20:21]
	v_pk_mul_f32 v[18:19], v[18:19], v[22:23]
	v_cvt_pk_bf16_f32 v156, v24, v25
	v_cvt_pk_bf16_f32 v157, v26, v27
	v_cvt_pk_bf16_f32 v158, v16, v17
	v_cvt_pk_bf16_f32 v159, v18, v19
	global_store_dwordx2 v[144:145], v[156:157], off
	global_store_dwordx2 v[144:145], v[158:159], off offset:128
	v_lshl_add_u64 v[144:145], v[144:145], 0, s[94:95]
	v_pk_mul_f32 v[12:13], v[12:13], v[234:235] op_sel:[0,1] op_sel_hi:[1,1]
	v_pk_mul_f32 v[14:15], v[14:15], v[234:235] op_sel:[0,1] op_sel_hi:[1,1]
	v_pk_mul_f32 v[8:9], v[8:9], v[234:235] op_sel:[0,1] op_sel_hi:[1,1]
	v_pk_mul_f32 v[10:11], v[10:11], v[234:235] op_sel:[0,1] op_sel_hi:[1,1]
	v_pk_mul_f32 v[4:5], v[4:5], v[234:235] op_sel:[0,1] op_sel_hi:[1,1]
	v_pk_mul_f32 v[6:7], v[6:7], v[234:235] op_sel:[0,1] op_sel_hi:[1,1]
	v_pk_mul_f32 v[0:1], v[0:1], v[234:235] op_sel:[0,1] op_sel_hi:[1,1]
	v_pk_mul_f32 v[2:3], v[2:3], v[234:235] op_sel:[0,1] op_sel_hi:[1,1]
	v_mul_f32_e32 v156, 0xbfb8aa3b, v12
	v_mul_f32_e32 v157, 0xbfb8aa3b, v13
	v_mul_f32_e32 v158, 0xbfb8aa3b, v14
	v_mul_f32_e32 v159, 0xbfb8aa3b, v15
	v_mul_f32_e32 v160, 0xbfb8aa3b, v4
	v_mul_f32_e32 v161, 0xbfb8aa3b, v5
	v_mul_f32_e32 v162, 0xbfb8aa3b, v6
	v_mul_f32_e32 v163, 0xbfb8aa3b, v7
	v_exp_f32_e32 v156, v156
	v_exp_f32_e32 v157, v157
	v_exp_f32_e32 v158, v158
	v_exp_f32_e32 v159, v159
	v_exp_f32_e32 v160, v160
	v_exp_f32_e32 v161, v161
	v_exp_f32_e32 v162, v162
	v_exp_f32_e32 v163, v163
	v_add_f32_e32 v156, 1.0, v156
	v_add_f32_e32 v157, 1.0, v157
	v_add_f32_e32 v158, 1.0, v158
	v_add_f32_e32 v159, 1.0, v159
	v_add_f32_e32 v160, 1.0, v160
	v_add_f32_e32 v161, 1.0, v161
	v_add_f32_e32 v162, 1.0, v162
	v_add_f32_e32 v163, 1.0, v163
	v_rcp_f32_e32 v156, v156
	v_rcp_f32_e32 v157, v157
	v_rcp_f32_e32 v158, v158
	v_rcp_f32_e32 v159, v159
	v_rcp_f32_e32 v160, v160
	v_rcp_f32_e32 v161, v161
	v_rcp_f32_e32 v162, v162
	v_rcp_f32_e32 v163, v163
	v_pk_mul_f32 v[12:13], v[12:13], v[156:157]
	v_pk_mul_f32 v[14:15], v[14:15], v[158:159]
	v_pk_mul_f32 v[4:5], v[4:5], v[160:161]
	v_pk_mul_f32 v[6:7], v[6:7], v[162:163]
	v_pk_mul_f32 v[8:9], v[8:9], v[12:13]
	v_pk_mul_f32 v[10:11], v[10:11], v[14:15]
	v_pk_mul_f32 v[0:1], v[0:1], v[4:5]
	v_pk_mul_f32 v[2:3], v[2:3], v[6:7]
	v_cvt_pk_bf16_f32 v156, v8, v9
	v_cvt_pk_bf16_f32 v157, v10, v11
	v_cvt_pk_bf16_f32 v158, v0, v1
	v_cvt_pk_bf16_f32 v159, v2, v3
	global_store_dwordx2 v[144:145], v[156:157], off
	global_store_dwordx2 v[144:145], v[158:159], off offset:128
	s_mov_b64 s[4:5], -1
	s_cbranch_vccnz .LBB0_679
	s_branch .Lgu0_tail

.LBB0_958:
	s_or_b64 exec, exec, s[4:5]
	s_mov_b32 s100, 0
	s_mov_b64 s[4:5], s[0:1]
	s_mov_b64 s[6:7], s[0:1]
	s_mov_b32 s3, s33
	s_mov_b32 s38, s2
	v_mov_b32_e32 v8, v154
	s_waitcnt lgkmcnt(0)
	s_barrier
	s_cmpk_gt_i32 s38, 0x3bf
	v_readfirstlane_b32 s10, v8
	s_cbranch_scc1 .LBB0_974
	v_lshlrev_b32_e32 v0, 4, v8
	v_add_u32_e32 v1, 0x2000, v0
	v_ashrrev_i32_e32 v2, 31, v1
	v_lshrrev_b32_e32 v2, 22, v2
	v_add_u32_e32 v2, v1, v2
	v_ashrrev_i32_e32 v9, 10, v2
	v_mul_i32_i24_e32 v2, 0x400, v9
	v_sub_u32_e32 v1, v1, v2
	v_lshrrev_b32_e32 v2, 4, v1
	v_bitop3_b32 v1, v2, v1, 32 bitop3:0x6c
	v_ashrrev_i32_e32 v2, 31, v1
	v_lshrrev_b32_e32 v2, 26, v2
	v_add_u32_e32 v2, v1, v2
	v_lshlrev_b32_e32 v3, 3, v9
	v_ashrrev_i32_e32 v10, 6, v2
	v_and_b32_e32 v3, -16, v3
	v_add_u32_e32 v3, v10, v3
	s_load_dwordx2 s[8:9], s[4:5], 0x130
	s_load_dwordx2 s[12:13], s[6:7], 0x138
	v_and_b32_e32 v4, 3, v10
	s_mov_b32 s4, 0x1fffe0
	v_lshrrev_b32_e32 v5, 2, v3
	v_lshlrev_b32_e32 v6, 1, v3
	v_and_b32_e32 v2, 0xc0, v2
	v_and_or_b32 v4, v3, s4, v4
	v_and_b32_e32 v5, 4, v5
	v_and_b32_e32 v6, 24, v6
	v_sub_u32_e32 v1, v1, v2
	v_mov_b32_e32 v2, 1
	v_or3_b32 v4, v4, v5, v6
	v_lshlrev_b32_e32 v5, 5, v9
	v_ashrrev_i16_sdwa v1, v2, sext(v1) dst_sel:DWORD dst_unused:UNUSED_PAD src0_sel:DWORD src1_sel:BYTE_0
	v_and_b32_e32 v5, 32, v5
	v_bfe_i32 v11, v1, 0, 16
	v_add_lshl_u32 v1, v5, v11, 1
	v_lshl_add_u32 v128, v4, 11, v1
	v_lshl_add_u32 v130, v3, 11, v1
	v_bfe_i32 v1, v8, 27, 1
	v_lshrrev_b32_e32 v1, 22, v1
	v_add_u32_e32 v1, v0, v1
	v_and_b32_e32 v1, 0xfffffc00, v1
	v_sub_u32_e32 v0, v0, v1
	v_lshrrev_b32_e32 v1, 4, v0
	v_ashrrev_i32_e32 v3, 31, v8
	v_bitop3_b32 v0, v1, v0, 32 bitop3:0x6c
	v_lshrrev_b32_e32 v3, 26, v3
	v_ashrrev_i32_e32 v1, 31, v0
	v_add_u32_e32 v3, v8, v3
	s_waitcnt lgkmcnt(0)
	s_add_u32 s39, s8, 0x2000000
	v_lshrrev_b32_e32 v1, 26, v1
	v_ashrrev_i32_e32 v13, 6, v3
	s_addc_u32 s40, s9, 0
	v_add_u32_e32 v1, v0, v1
	v_lshlrev_b32_e32 v3, 3, v13
	s_add_u32 s41, s12, 0x100000
	v_ashrrev_i32_e32 v12, 6, v1
	v_and_b32_e32 v3, -16, v3
	s_addc_u32 s42, s13, 0
	v_add_u32_e32 v3, v12, v3
	v_and_b32_e32 v4, 3, v12
	s_ashr_i32 s44, s38, 31
	v_and_or_b32 v4, v3, s4, v4
	s_lshr_b32 s4, s44, 29
	s_add_i32 s4, s38, s4
	s_ashr_i32 s5, s10, 6
	s_ashr_i32 s6, s4, 3
	s_and_b32 s4, s4, -8
	s_ashr_i32 s8, s10, 8
	s_lshl_b32 s43, s5, 10
	s_sub_i32 s4, s38, s4
	s_cmp_lt_i32 s4, 0
	s_movk_i32 s45, 0x79
	s_cselect_b32 s7, s45, 0x78
	s_mul_i32 s4, s7, s4
	s_add_i32 s4, s4, s6
	s_mul_hi_i32 s6, s4, 0x88888889
	s_add_i32 s6, s6, s4
	s_lshr_b32 s7, s6, 31
	s_ashr_i32 s6, s6, 6
	s_add_i32 s6, s6, s7
	s_lshl_b32 s7, s6, 3
	s_mulk_i32 s6, 0x78
	s_sub_i32 s6, s4, s6
	s_bfe_i32 s4, s6, 0x80000
	s_bfe_u32 s4, s4, 0x3000c
	s_add_i32 s9, s6, s4
	s_bfe_i32 s4, s9, 0x80000
	s_and_b32 s9, s9, 0xf8
	s_sub_i32 s6, s6, s9
	s_sext_i32_i16 s4, s4
	s_sext_i32_i8 s6, s6
	v_lshrrev_b32_e32 v5, 2, v3
	v_lshlrev_b32_e32 v6, 1, v3
	v_and_b32_e32 v1, 0xc0, v1
	s_lshr_b32 s4, s4, 3
	s_add_i32 s28, s7, s6
	v_and_b32_e32 v5, 4, v5
	v_and_b32_e32 v6, 24, v6
	v_sub_u32_e32 v0, v0, v1
	s_ashr_i32 s29, s28, 31
	s_bfe_i64 s[12:13], s[4:5], 0x100000
	v_or3_b32 v4, v4, v5, v6
	v_lshlrev_b32_e32 v5, 5, v13
	v_ashrrev_i16_sdwa v0, v2, sext(v0) dst_sel:DWORD dst_unused:UNUSED_PAD src0_sel:DWORD src1_sel:BYTE_0
	s_lshl_b64 s[6:7], s[28:29], 19
	s_lshl_b64 s[12:13], s[12:13], 19
	v_and_b32_e32 v5, 32, v5
	v_bfe_i32 v14, v0, 0, 16
	s_add_u32 s30, s41, s12
	v_add_lshl_u32 v0, v5, v14, 1
	s_addc_u32 s31, s42, s13
	s_add_i32 s46, s43, 0
	v_lshl_add_u32 v132, v4, 11, v0
	s_add_i32 m0, s46, 0x10000
	v_lshl_add_u32 v134, v3, 11, v0
	global_load_lds_dwordx4 v132, s[30:31]
	s_add_i32 m0, s46, 0x12000
	s_add_u32 s12, s30, 0x40000
	global_load_lds_dwordx4 v128, s[30:31]
	s_addc_u32 s13, s31, 0
	s_add_i32 m0, s46, 0x14000
	v_mov_b32_e32 v133, 0
	global_load_lds_dwordx4 v132, s[12:13]
	s_add_i32 m0, s46, 0x16000
	s_add_u32 s34, s39, s6
	s_addc_u32 s35, s40, s7
	s_add_i32 s47, s46, 0x2000
	global_load_lds_dwordx4 v128, s[12:13]
	s_mov_b32 m0, s46
	s_add_u32 s6, s34, 0x40000
	global_load_lds_dwordx4 v134, s[34:35]
	s_mov_b32 m0, s47
	s_addc_u32 s7, s35, 0
	s_add_i32 s48, s46, 0x4000
	global_load_lds_dwordx4 v130, s[34:35]
	s_mov_b32 m0, s48
	s_add_i32 s49, s46, 0x6000
	global_load_lds_dwordx4 v134, s[6:7]
	s_mov_b32 m0, s49
	v_mov_b32_e32 v129, v133
	global_load_lds_dwordx4 v130, s[6:7]
	v_mov_b32_e32 v135, v133
	v_mov_b32_e32 v131, v133
	s_cmp_eq_u32 s8, 1
	s_mov_b32 s50, 0
	v_lshl_add_u64 v[6:7], s[30:31], 0, v[132:133]
	v_lshl_add_u64 v[4:5], s[30:31], 0, v[128:129]
	v_lshl_add_u64 v[0:1], s[34:35], 0, v[134:135]
	s_cselect_b64 s[6:7], -1, 0
	s_cmp_lg_u32 s8, 1
	v_lshl_add_u64 v[2:3], s[34:35], 0, v[130:131]
	s_cbranch_scc1 .LBB0_961
	s_barrier

.LBB0_970:
	s_add_i32 s101, s28, 1
	s_cmp_eq_u32 s100, s101
	s_cbranch_scc1 .Lip1_fast
	s_mov_b32 s100, s101
	v_mov_b32_e32 v153, v154
	s_mov_b64 s[30:31], s[0:1]
	s_load_dwordx2 s[30:31], s[30:31], 0x138
	v_and_or_b32 v144, v153, 15, s51
	v_lshl_add_u32 v146, s28, 8, v144
	v_ashrrev_i32_e32 v147, 31, v146
	v_lshlrev_b64 v[144:145], 6, v[146:147]
	s_waitcnt lgkmcnt(0)
	s_add_u32 s28, s30, 0xfd00000
	s_addc_u32 s29, s31, 0
	v_lshl_add_u64 v[144:145], s[28:29], 0, v[144:145]
	global_load_dwordx4 v[156:159], v[144:145], off
	global_load_dwordx4 v[160:163], v[144:145], off offset:32
	global_load_dwordx4 v[164:167], v[144:145], off offset:16
	global_load_dwordx4 v[168:171], v[144:145], off offset:48
	v_or_b32_e32 v172, 16, v146
	v_lshrrev_b32_e32 v147, 1, v153
	v_ashrrev_i32_e32 v173, 31, v172
	s_lshl_b32 s15, s59, 8
	v_lshlrev_b64 v[144:145], 6, v[172:173]
	v_and_or_b32 v147, v147, 24, s15
	v_lshl_add_u64 v[174:175], s[28:29], 0, v[144:145]
	v_or_b32_e32 v144, s52, v147
	v_ashrrev_i32_e32 v145, 31, v144
	v_lshl_add_u64 v[144:145], v[144:145], 1, s[30:31]
	v_lshl_add_u64 v[144:145], v[144:145], 0, s[12:13]
	s_andn2_b64 vcc, exec, s[4:5]
	s_waitcnt vmcnt(0)
	v_mov_b32_e32 v176, v156
	v_mov_b32_e32 v177, v160
	v_mov_b32_e32 v160, v157
	v_mov_b32_e32 v156, v158
	v_mov_b32_e32 v157, v162
	v_mov_b32_e32 v162, v159
	v_mov_b32_e32 v158, v164
	v_mov_b32_e32 v159, v168
	v_mov_b32_e32 v168, v165
	v_mov_b32_e32 v164, v166
	v_mov_b32_e32 v165, v170
	v_mov_b32_e32 v170, v167
	v_pk_add_f32 v[160:161], v[176:177], v[160:161]
	v_pk_add_f32 v[156:157], v[156:157], v[162:163]
	v_pk_add_f32 v[158:159], v[158:159], v[168:169]
	v_pk_add_f32 v[162:163], v[164:165], v[170:171]
	v_pk_add_f32 v[156:157], v[160:161], v[156:157]
	v_pk_add_f32 v[158:159], v[158:159], v[162:163]
	s_nop 0
	v_pk_add_f32 v[156:157], v[156:157], v[158:159]
	v_mad_i64_i32 v[158:159], s[30:31], v146, s58, v[144:145]
	v_add_f32_e32 v147, v156, v157
	v_fmamk_f32 v147, v147, 0x3a800000, v152
	v_rsq_f32_e32 v156, v147
	s_nop 0
	v_mov_b32_e32 v228, v156
	v_pk_mul_f32 v[126:127], v[126:127], v[156:157] op_sel_hi:[1,0]
	v_pk_mul_f32 v[124:125], v[124:125], v[156:157] op_sel_hi:[1,0]
	v_pk_mul_f32 v[122:123], v[122:123], v[156:157] op_sel_hi:[1,0]
	v_pk_mul_f32 v[120:121], v[120:121], v[156:157] op_sel_hi:[1,0]
	v_pk_mul_f32 v[118:119], v[118:119], v[156:157] op_sel_hi:[1,0]
	v_pk_mul_f32 v[116:117], v[116:117], v[156:157] op_sel_hi:[1,0]
	v_pk_mul_f32 v[160:161], v[114:115], v[156:157] op_sel_hi:[1,0]
	v_pk_mul_f32 v[156:157], v[112:113], v[156:157] op_sel_hi:[1,0]
	v_cvt_pk_bf16_f32 v112, v124, v125
	v_cvt_pk_bf16_f32 v113, v126, v127
	v_cvt_pk_bf16_f32 v114, v120, v121
	v_cvt_pk_bf16_f32 v115, v122, v123
	v_cvt_pk_bf16_f32 v116, v116, v117
	v_cvt_pk_bf16_f32 v117, v118, v119
	v_cvt_pk_bf16_f32 v118, v156, v157
	v_cvt_pk_bf16_f32 v119, v160, v161
	global_store_dwordx4 v[158:159], v[112:115], off
	global_store_dwordx4 v[158:159], v[116:119], off offset:256
	global_load_dwordx4 v[112:115], v[174:175], off
	s_nop 0
	global_load_dwordx4 v[116:119], v[174:175], off offset:32
	global_load_dwordx4 v[120:123], v[174:175], off offset:16
	global_load_dwordx4 v[124:127], v[174:175], off offset:48
	v_or_b32_e32 v156, 32, v146
	v_ashrrev_i32_e32 v157, 31, v156
	v_lshlrev_b64 v[158:159], 6, v[156:157]
	s_waitcnt vmcnt(3)
	v_mov_b32_e32 v160, v112
	s_waitcnt vmcnt(2)
	v_mov_b32_e32 v161, v116
	v_mov_b32_e32 v116, v113
	v_mov_b32_e32 v112, v114
	v_mov_b32_e32 v113, v118
	v_mov_b32_e32 v118, v115
	s_waitcnt vmcnt(1)
	v_mov_b32_e32 v114, v120
	s_waitcnt vmcnt(0)
	v_mov_b32_e32 v115, v124
	v_mov_b32_e32 v124, v121
	v_mov_b32_e32 v120, v122
	v_mov_b32_e32 v121, v126
	v_mov_b32_e32 v126, v123
	v_pk_add_f32 v[116:117], v[160:161], v[116:117]
	v_pk_add_f32 v[112:113], v[112:113], v[118:119]
	v_pk_add_f32 v[114:115], v[114:115], v[124:125]
	v_pk_add_f32 v[118:119], v[120:121], v[126:127]
	v_pk_add_f32 v[112:113], v[116:117], v[112:113]
	v_pk_add_f32 v[114:115], v[114:115], v[118:119]
	v_mad_i64_i32 v[116:117], s[30:31], v172, s58, v[144:145]
	v_pk_add_f32 v[112:113], v[112:113], v[114:115]
	v_lshl_add_u64 v[114:115], s[28:29], 0, v[158:159]
	v_add_f32_e32 v112, v112, v113
	v_fmamk_f32 v112, v112, 0x3a800000, v152
	v_rsq_f32_e32 v112, v112
	s_nop 0
	v_mov_b32_e32 v229, v112
	v_pk_mul_f32 v[110:111], v[110:111], v[112:113] op_sel_hi:[1,0]
	v_pk_mul_f32 v[108:109], v[108:109], v[112:113] op_sel_hi:[1,0]
	v_pk_mul_f32 v[106:107], v[106:107], v[112:113] op_sel_hi:[1,0]
	v_pk_mul_f32 v[104:105], v[104:105], v[112:113] op_sel_hi:[1,0]
	v_pk_mul_f32 v[102:103], v[102:103], v[112:113] op_sel_hi:[1,0]
	v_pk_mul_f32 v[100:101], v[100:101], v[112:113] op_sel_hi:[1,0]
	v_pk_mul_f32 v[118:119], v[98:99], v[112:113] op_sel_hi:[1,0]
	v_pk_mul_f32 v[112:113], v[96:97], v[112:113] op_sel_hi:[1,0]
	v_cvt_pk_bf16_f32 v96, v108, v109
	v_cvt_pk_bf16_f32 v97, v110, v111
	v_cvt_pk_bf16_f32 v98, v104, v105
	v_cvt_pk_bf16_f32 v99, v106, v107
	v_cvt_pk_bf16_f32 v100, v100, v101
	v_cvt_pk_bf16_f32 v101, v102, v103
	v_cvt_pk_bf16_f32 v102, v112, v113
	v_cvt_pk_bf16_f32 v103, v118, v119
	global_store_dwordx4 v[116:117], v[96:99], off
	global_store_dwordx4 v[116:117], v[100:103], off offset:256
	global_load_dwordx4 v[96:99], v[114:115], off
	s_nop 0
	global_load_dwordx4 v[100:103], v[114:115], off offset:32
	global_load_dwordx4 v[104:107], v[114:115], off offset:16
	global_load_dwordx4 v[108:111], v[114:115], off offset:48
	v_or_b32_e32 v112, 48, v146
	v_ashrrev_i32_e32 v113, 31, v112
	v_lshlrev_b64 v[114:115], 6, v[112:113]
	s_waitcnt vmcnt(3)
	v_mov_b32_e32 v116, v96
	s_waitcnt vmcnt(2)
	v_mov_b32_e32 v117, v100
	v_mov_b32_e32 v100, v97
	v_mov_b32_e32 v96, v98
	v_mov_b32_e32 v97, v102
	v_mov_b32_e32 v102, v99
	s_waitcnt vmcnt(1)
	v_mov_b32_e32 v98, v104
	s_waitcnt vmcnt(0)
	v_mov_b32_e32 v99, v108
	v_mov_b32_e32 v108, v105
	v_mov_b32_e32 v104, v106
	v_mov_b32_e32 v105, v110
	v_mov_b32_e32 v110, v107
	v_pk_add_f32 v[100:101], v[116:117], v[100:101]
	v_pk_add_f32 v[96:97], v[96:97], v[102:103]
	v_pk_add_f32 v[98:99], v[98:99], v[108:109]
	v_pk_add_f32 v[102:103], v[104:105], v[110:111]
	v_pk_add_f32 v[96:97], v[100:101], v[96:97]
	v_pk_add_f32 v[98:99], v[98:99], v[102:103]
	v_mad_i64_i32 v[100:101], s[30:31], v156, s58, v[144:145]
	v_pk_add_f32 v[96:97], v[96:97], v[98:99]
	v_lshl_add_u64 v[98:99], s[28:29], 0, v[114:115]
	v_add_f32_e32 v96, v96, v97
	v_fmamk_f32 v96, v96, 0x3a800000, v152
	v_rsq_f32_e32 v96, v96
	s_nop 0
	v_mov_b32_e32 v230, v96
	v_pk_mul_f32 v[94:95], v[94:95], v[96:97] op_sel_hi:[1,0]
	v_pk_mul_f32 v[92:93], v[92:93], v[96:97] op_sel_hi:[1,0]
	v_pk_mul_f32 v[90:91], v[90:91], v[96:97] op_sel_hi:[1,0]
	v_pk_mul_f32 v[88:89], v[88:89], v[96:97] op_sel_hi:[1,0]
	v_pk_mul_f32 v[86:87], v[86:87], v[96:97] op_sel_hi:[1,0]
	v_pk_mul_f32 v[84:85], v[84:85], v[96:97] op_sel_hi:[1,0]
	v_pk_mul_f32 v[102:103], v[82:83], v[96:97] op_sel_hi:[1,0]
	v_pk_mul_f32 v[96:97], v[80:81], v[96:97] op_sel_hi:[1,0]
	v_cvt_pk_bf16_f32 v80, v92, v93
	v_cvt_pk_bf16_f32 v81, v94, v95
	v_cvt_pk_bf16_f32 v82, v88, v89
	v_cvt_pk_bf16_f32 v83, v90, v91
	v_cvt_pk_bf16_f32 v84, v84, v85
	v_cvt_pk_bf16_f32 v85, v86, v87
	v_cvt_pk_bf16_f32 v86, v96, v97
	v_cvt_pk_bf16_f32 v87, v102, v103
	global_store_dwordx4 v[100:101], v[80:83], off
	global_store_dwordx4 v[100:101], v[84:87], off offset:256
	global_load_dwordx4 v[80:83], v[98:99], off
	s_nop 0
	global_load_dwordx4 v[84:87], v[98:99], off offset:32
	global_load_dwordx4 v[88:91], v[98:99], off offset:16
	global_load_dwordx4 v[92:95], v[98:99], off offset:48
	v_add_u32_e32 v96, 0x80, v146
	v_ashrrev_i32_e32 v97, 31, v96
	v_lshlrev_b64 v[98:99], 6, v[96:97]
	s_waitcnt vmcnt(3)
	v_mov_b32_e32 v100, v80
	s_waitcnt vmcnt(2)
	v_mov_b32_e32 v101, v84
	v_mov_b32_e32 v84, v81
	v_mov_b32_e32 v80, v82
	v_mov_b32_e32 v81, v86
	v_mov_b32_e32 v86, v83
	s_waitcnt vmcnt(1)
	v_mov_b32_e32 v82, v88
	s_waitcnt vmcnt(0)
	v_mov_b32_e32 v83, v92
	v_mov_b32_e32 v92, v89
	v_mov_b32_e32 v88, v90
	v_mov_b32_e32 v89, v94
	v_mov_b32_e32 v94, v91
	v_pk_add_f32 v[84:85], v[100:101], v[84:85]
	v_pk_add_f32 v[80:81], v[80:81], v[86:87]
	v_pk_add_f32 v[82:83], v[82:83], v[92:93]
	v_pk_add_f32 v[86:87], v[88:89], v[94:95]
	v_pk_add_f32 v[80:81], v[84:85], v[80:81]
	v_pk_add_f32 v[82:83], v[82:83], v[86:87]
	v_mad_i64_i32 v[84:85], s[30:31], v112, s58, v[144:145]
	v_pk_add_f32 v[80:81], v[80:81], v[82:83]
	v_lshl_add_u64 v[82:83], s[28:29], 0, v[98:99]
	v_add_f32_e32 v80, v80, v81
	v_fmamk_f32 v80, v80, 0x3a800000, v152
	v_rsq_f32_e32 v80, v80
	s_nop 0
	v_mov_b32_e32 v231, v80
	v_pk_mul_f32 v[78:79], v[78:79], v[80:81] op_sel_hi:[1,0]
	v_pk_mul_f32 v[76:77], v[76:77], v[80:81] op_sel_hi:[1,0]
	v_pk_mul_f32 v[74:75], v[74:75], v[80:81] op_sel_hi:[1,0]
	v_pk_mul_f32 v[72:73], v[72:73], v[80:81] op_sel_hi:[1,0]
	v_pk_mul_f32 v[70:71], v[70:71], v[80:81] op_sel_hi:[1,0]
	v_pk_mul_f32 v[68:69], v[68:69], v[80:81] op_sel_hi:[1,0]
	v_pk_mul_f32 v[86:87], v[66:67], v[80:81] op_sel_hi:[1,0]
	v_pk_mul_f32 v[80:81], v[64:65], v[80:81] op_sel_hi:[1,0]
	v_cvt_pk_bf16_f32 v64, v76, v77
	v_cvt_pk_bf16_f32 v65, v78, v79
	v_cvt_pk_bf16_f32 v66, v72, v73
	v_cvt_pk_bf16_f32 v67, v74, v75
	v_cvt_pk_bf16_f32 v68, v68, v69
	v_cvt_pk_bf16_f32 v69, v70, v71
	v_cvt_pk_bf16_f32 v70, v80, v81
	v_cvt_pk_bf16_f32 v71, v86, v87
	global_store_dwordx4 v[84:85], v[64:67], off
	global_store_dwordx4 v[84:85], v[68:71], off offset:256
	global_load_dwordx4 v[64:67], v[82:83], off
	s_nop 0
	global_load_dwordx4 v[68:71], v[82:83], off offset:32
	global_load_dwordx4 v[72:75], v[82:83], off offset:16
	global_load_dwordx4 v[76:79], v[82:83], off offset:48
	v_add_u32_e32 v80, 0x90, v146
	v_ashrrev_i32_e32 v81, 31, v80
	v_lshlrev_b64 v[82:83], 6, v[80:81]
	s_waitcnt vmcnt(3)
	v_mov_b32_e32 v84, v64
	s_waitcnt vmcnt(2)
	v_mov_b32_e32 v85, v68
	v_mov_b32_e32 v68, v65
	v_mov_b32_e32 v64, v66
	v_mov_b32_e32 v65, v70
	v_mov_b32_e32 v70, v67
	s_waitcnt vmcnt(1)
	v_mov_b32_e32 v66, v72
	s_waitcnt vmcnt(0)
	v_mov_b32_e32 v67, v76
	v_mov_b32_e32 v76, v73
	v_mov_b32_e32 v72, v74
	v_mov_b32_e32 v73, v78
	v_mov_b32_e32 v78, v75
	v_pk_add_f32 v[68:69], v[84:85], v[68:69]
	v_pk_add_f32 v[64:65], v[64:65], v[70:71]
	v_pk_add_f32 v[66:67], v[66:67], v[76:77]
	v_pk_add_f32 v[70:71], v[72:73], v[78:79]
	v_pk_add_f32 v[64:65], v[68:69], v[64:65]
	v_pk_add_f32 v[66:67], v[66:67], v[70:71]
	v_mad_i64_i32 v[68:69], s[30:31], v96, s58, v[144:145]
	v_pk_add_f32 v[64:65], v[64:65], v[66:67]
	v_lshl_add_u64 v[66:67], s[28:29], 0, v[82:83]
	v_add_f32_e32 v64, v64, v65
	v_fmamk_f32 v64, v64, 0x3a800000, v152
	v_rsq_f32_e32 v64, v64
	s_nop 0
	v_mov_b32_e32 v232, v64
	v_pk_mul_f32 v[62:63], v[62:63], v[64:65] op_sel_hi:[1,0]
	v_pk_mul_f32 v[60:61], v[60:61], v[64:65] op_sel_hi:[1,0]
	v_pk_mul_f32 v[58:59], v[58:59], v[64:65] op_sel_hi:[1,0]
	v_pk_mul_f32 v[56:57], v[56:57], v[64:65] op_sel_hi:[1,0]
	v_pk_mul_f32 v[54:55], v[54:55], v[64:65] op_sel_hi:[1,0]
	v_pk_mul_f32 v[52:53], v[52:53], v[64:65] op_sel_hi:[1,0]
	v_pk_mul_f32 v[70:71], v[50:51], v[64:65] op_sel_hi:[1,0]
	v_pk_mul_f32 v[64:65], v[48:49], v[64:65] op_sel_hi:[1,0]
	v_cvt_pk_bf16_f32 v48, v60, v61
	v_cvt_pk_bf16_f32 v49, v62, v63
	v_cvt_pk_bf16_f32 v50, v56, v57
	v_cvt_pk_bf16_f32 v51, v58, v59
	v_cvt_pk_bf16_f32 v52, v52, v53
	v_cvt_pk_bf16_f32 v53, v54, v55
	v_cvt_pk_bf16_f32 v54, v64, v65
	v_cvt_pk_bf16_f32 v55, v70, v71
	global_store_dwordx4 v[68:69], v[48:51], off
	global_store_dwordx4 v[68:69], v[52:55], off offset:256
	global_load_dwordx4 v[48:51], v[66:67], off
	s_nop 0
	global_load_dwordx4 v[52:55], v[66:67], off offset:32
	global_load_dwordx4 v[56:59], v[66:67], off offset:16
	global_load_dwordx4 v[60:63], v[66:67], off offset:48
	v_add_u32_e32 v64, 0xa0, v146
	v_ashrrev_i32_e32 v65, 31, v64
	v_lshlrev_b64 v[66:67], 6, v[64:65]
	s_waitcnt vmcnt(3)
	v_mov_b32_e32 v68, v48
	s_waitcnt vmcnt(2)
	v_mov_b32_e32 v69, v52
	v_mov_b32_e32 v52, v49
	v_mov_b32_e32 v48, v50
	v_mov_b32_e32 v49, v54
	v_mov_b32_e32 v54, v51
	s_waitcnt vmcnt(1)
	v_mov_b32_e32 v50, v56
	s_waitcnt vmcnt(0)
	v_mov_b32_e32 v51, v60
	v_mov_b32_e32 v60, v57
	v_mov_b32_e32 v56, v58
	v_mov_b32_e32 v57, v62
	v_mov_b32_e32 v62, v59
	v_pk_add_f32 v[52:53], v[68:69], v[52:53]
	v_pk_add_f32 v[48:49], v[48:49], v[54:55]
	v_pk_add_f32 v[50:51], v[50:51], v[60:61]
	v_pk_add_f32 v[54:55], v[56:57], v[62:63]
	v_pk_add_f32 v[48:49], v[52:53], v[48:49]
	v_pk_add_f32 v[50:51], v[50:51], v[54:55]
	v_mad_i64_i32 v[52:53], s[30:31], v80, s58, v[144:145]
	v_pk_add_f32 v[48:49], v[48:49], v[50:51]
	v_lshl_add_u64 v[50:51], s[28:29], 0, v[66:67]
	v_add_f32_e32 v48, v48, v49
	v_fmamk_f32 v48, v48, 0x3a800000, v152
	v_rsq_f32_e32 v48, v48
	s_nop 0
	v_mov_b32_e32 v233, v48
	v_pk_mul_f32 v[46:47], v[46:47], v[48:49] op_sel_hi:[1,0]
	v_pk_mul_f32 v[44:45], v[44:45], v[48:49] op_sel_hi:[1,0]
	v_pk_mul_f32 v[42:43], v[42:43], v[48:49] op_sel_hi:[1,0]
	v_pk_mul_f32 v[40:41], v[40:41], v[48:49] op_sel_hi:[1,0]
	v_pk_mul_f32 v[38:39], v[38:39], v[48:49] op_sel_hi:[1,0]
	v_pk_mul_f32 v[36:37], v[36:37], v[48:49] op_sel_hi:[1,0]
	v_pk_mul_f32 v[54:55], v[34:35], v[48:49] op_sel_hi:[1,0]
	v_pk_mul_f32 v[48:49], v[32:33], v[48:49] op_sel_hi:[1,0]
	v_cvt_pk_bf16_f32 v32, v44, v45
	v_cvt_pk_bf16_f32 v33, v46, v47
	v_cvt_pk_bf16_f32 v34, v40, v41
	v_cvt_pk_bf16_f32 v35, v42, v43
	v_cvt_pk_bf16_f32 v36, v36, v37
	v_cvt_pk_bf16_f32 v37, v38, v39
	v_cvt_pk_bf16_f32 v38, v48, v49
	v_cvt_pk_bf16_f32 v39, v54, v55
	global_store_dwordx4 v[52:53], v[32:35], off
	global_store_dwordx4 v[52:53], v[36:39], off offset:256
	global_load_dwordx4 v[32:35], v[50:51], off
	s_nop 0
	global_load_dwordx4 v[36:39], v[50:51], off offset:32
	global_load_dwordx4 v[40:43], v[50:51], off offset:16
	global_load_dwordx4 v[44:47], v[50:51], off offset:48
	v_add_u32_e32 v48, 0xb0, v146
	v_ashrrev_i32_e32 v49, 31, v48
	v_lshlrev_b64 v[50:51], 6, v[48:49]
	s_waitcnt vmcnt(3)
	v_mov_b32_e32 v52, v32
	s_waitcnt vmcnt(2)
	v_mov_b32_e32 v53, v36
	v_mov_b32_e32 v36, v33
	v_mov_b32_e32 v32, v34
	v_mov_b32_e32 v33, v38
	v_mov_b32_e32 v38, v35
	s_waitcnt vmcnt(1)
	v_mov_b32_e32 v34, v40
	s_waitcnt vmcnt(0)
	v_mov_b32_e32 v35, v44
	v_mov_b32_e32 v44, v41
	v_mov_b32_e32 v40, v42
	v_mov_b32_e32 v41, v46
	v_mov_b32_e32 v46, v43
	v_pk_add_f32 v[36:37], v[52:53], v[36:37]
	v_pk_add_f32 v[32:33], v[32:33], v[38:39]
	v_pk_add_f32 v[34:35], v[34:35], v[44:45]
	v_pk_add_f32 v[38:39], v[40:41], v[46:47]
	v_pk_add_f32 v[32:33], v[36:37], v[32:33]
	v_pk_add_f32 v[34:35], v[34:35], v[38:39]
	s_nop 0
	v_pk_add_f32 v[32:33], v[32:33], v[34:35]
	v_lshl_add_u64 v[34:35], s[28:29], 0, v[50:51]
	v_add_f32_e32 v32, v32, v33
	v_fmamk_f32 v32, v32, 0x3a800000, v152
	v_rsq_f32_e32 v32, v32
	v_mad_i64_i32 v[36:37], s[28:29], v64, s58, v[144:145]
	v_mov_b32_e32 v234, v32
	v_pk_mul_f32 v[30:31], v[30:31], v[32:33] op_sel_hi:[1,0]
	v_pk_mul_f32 v[28:29], v[28:29], v[32:33] op_sel_hi:[1,0]
	v_pk_mul_f32 v[26:27], v[26:27], v[32:33] op_sel_hi:[1,0]
	v_pk_mul_f32 v[24:25], v[24:25], v[32:33] op_sel_hi:[1,0]
	v_pk_mul_f32 v[22:23], v[22:23], v[32:33] op_sel_hi:[1,0]
	v_pk_mul_f32 v[20:21], v[20:21], v[32:33] op_sel_hi:[1,0]
	v_pk_mul_f32 v[38:39], v[18:19], v[32:33] op_sel_hi:[1,0]
	v_pk_mul_f32 v[32:33], v[16:17], v[32:33] op_sel_hi:[1,0]
	v_cvt_pk_bf16_f32 v16, v28, v29
	v_cvt_pk_bf16_f32 v17, v30, v31
	v_cvt_pk_bf16_f32 v18, v24, v25
	v_cvt_pk_bf16_f32 v19, v26, v27
	v_cvt_pk_bf16_f32 v20, v20, v21
	v_cvt_pk_bf16_f32 v21, v22, v23
	v_cvt_pk_bf16_f32 v22, v32, v33
	v_cvt_pk_bf16_f32 v23, v38, v39
	global_store_dwordx4 v[36:37], v[16:19], off
	global_store_dwordx4 v[36:37], v[20:23], off offset:256
	global_load_dwordx4 v[16:19], v[34:35], off
	s_nop 0
	global_load_dwordx4 v[20:23], v[34:35], off offset:32
	global_load_dwordx4 v[24:27], v[34:35], off offset:16
	global_load_dwordx4 v[28:31], v[34:35], off offset:48
	s_waitcnt vmcnt(3)
	v_mov_b32_e32 v32, v16
	s_waitcnt vmcnt(2)
	v_mov_b32_e32 v33, v20
	v_mov_b32_e32 v20, v17
	v_mov_b32_e32 v16, v18
	v_mov_b32_e32 v17, v22
	v_mov_b32_e32 v22, v19
	s_waitcnt vmcnt(1)
	v_mov_b32_e32 v18, v24
	s_waitcnt vmcnt(0)
	v_mov_b32_e32 v19, v28
	v_mov_b32_e32 v28, v25
	v_mov_b32_e32 v24, v26
	v_mov_b32_e32 v25, v30
	v_mov_b32_e32 v30, v27
	v_pk_add_f32 v[20:21], v[32:33], v[20:21]
	v_pk_add_f32 v[16:17], v[16:17], v[22:23]
	v_pk_add_f32 v[18:19], v[18:19], v[28:29]
	v_pk_add_f32 v[22:23], v[24:25], v[30:31]
	v_pk_add_f32 v[16:17], v[20:21], v[16:17]
	v_pk_add_f32 v[18:19], v[18:19], v[22:23]
	s_nop 0
	v_pk_add_f32 v[16:17], v[16:17], v[18:19]
	v_mad_i64_i32 v[18:19], s[4:5], v48, s58, v[144:145]
	v_add_f32_e32 v16, v16, v17
	v_fmamk_f32 v16, v16, 0x3a800000, v152
	v_rsq_f32_e32 v16, v16
	s_mov_b64 s[4:5], -1
	v_mov_b32_e32 v235, v16
	v_pk_mul_f32 v[14:15], v[14:15], v[16:17] op_sel_hi:[1,0]
	v_pk_mul_f32 v[12:13], v[12:13], v[16:17] op_sel_hi:[1,0]
	v_pk_mul_f32 v[10:11], v[10:11], v[16:17] op_sel_hi:[1,0]
	v_pk_mul_f32 v[8:9], v[8:9], v[16:17] op_sel_hi:[1,0]
	v_pk_mul_f32 v[6:7], v[6:7], v[16:17] op_sel_hi:[1,0]
	v_pk_mul_f32 v[4:5], v[4:5], v[16:17] op_sel_hi:[1,0]
	v_pk_mul_f32 v[20:21], v[2:3], v[16:17] op_sel_hi:[1,0]
	v_pk_mul_f32 v[16:17], v[0:1], v[16:17] op_sel_hi:[1,0]
	v_cvt_pk_bf16_f32 v0, v12, v13
	v_cvt_pk_bf16_f32 v1, v14, v15
	v_cvt_pk_bf16_f32 v2, v8, v9
	v_cvt_pk_bf16_f32 v3, v10, v11
	v_cvt_pk_bf16_f32 v4, v4, v5
	v_cvt_pk_bf16_f32 v5, v6, v7
	v_cvt_pk_bf16_f32 v6, v16, v17
	v_cvt_pk_bf16_f32 v7, v20, v21
	global_store_dwordx4 v[18:19], v[0:3], off
	global_store_dwordx4 v[18:19], v[4:7], off offset:256
	s_cbranch_vccnz .LBB0_963
.Lip1_tail:
	s_andn2_b64 vcc, exec, s[6:7]
	s_cbranch_vccnz .LBB0_962
	s_barrier
	s_branch .LBB0_962
.Lip1_fast:
	s_andn2_b64 vcc, exec, s[4:5]
	s_load_dwordx2 s[30:31], s[0:1], 0x138
	s_mov_b32 s94, 0x1e000
	s_mov_b32 s95, 0
	s_mov_b32 s96, 0x96000
	s_mov_b32 s97, 0
	v_and_or_b32 v146, v154, 15, s51
	v_lshl_add_u32 v146, s28, 8, v146
	s_lshl_b32 s101, s59, 8
	v_lshrrev_b32_e32 v144, 1, v154
	v_and_or_b32 v144, v144, 24, s101
	v_or_b32_e32 v144, s52, v144
	v_ashrrev_i32_e32 v145, 31, v144
	s_waitcnt lgkmcnt(0)
	v_lshl_add_u64 v[144:145], v[144:145], 1, s[30:31]
	v_lshl_add_u64 v[144:145], v[144:145], 0, s[12:13]
	v_mad_i64_i32 v[144:145], s[30:31], v146, s58, v[144:145]
	v_pk_mul_f32 v[124:125], v[124:125], v[228:229] op_sel_hi:[1,0]
	v_pk_mul_f32 v[126:127], v[126:127], v[228:229] op_sel_hi:[1,0]
	v_pk_mul_f32 v[120:121], v[120:121], v[228:229] op_sel_hi:[1,0]
	v_pk_mul_f32 v[122:123], v[122:123], v[228:229] op_sel_hi:[1,0]
	v_cvt_pk_bf16_f32 v156, v124, v125
	v_cvt_pk_bf16_f32 v157, v126, v127
	v_cvt_pk_bf16_f32 v158, v120, v121
	v_cvt_pk_bf16_f32 v159, v122, v123
	global_store_dwordx4 v[144:145], v[156:159], off
	v_pk_mul_f32 v[116:117], v[116:117], v[228:229] op_sel_hi:[1,0]
	v_pk_mul_f32 v[118:119], v[118:119], v[228:229] op_sel_hi:[1,0]
	v_pk_mul_f32 v[112:113], v[112:113], v[228:229] op_sel_hi:[1,0]
	v_pk_mul_f32 v[114:115], v[114:115], v[228:229] op_sel_hi:[1,0]
	v_cvt_pk_bf16_f32 v160, v116, v117
	v_cvt_pk_bf16_f32 v161, v118, v119
	v_cvt_pk_bf16_f32 v162, v112, v113
	v_cvt_pk_bf16_f32 v163, v114, v115
	global_store_dwordx4 v[144:145], v[160:163], off offset:256
	v_lshl_add_u64 v[144:145], v[144:145], 0, s[94:95]
	v_pk_mul_f32 v[108:109], v[108:109], v[228:229] op_sel:[0,1] op_sel_hi:[1,1]
	v_pk_mul_f32 v[110:111], v[110:111], v[228:229] op_sel:[0,1] op_sel_hi:[1,1]
	v_pk_mul_f32 v[104:105], v[104:105], v[228:229] op_sel:[0,1] op_sel_hi:[1,1]
	v_pk_mul_f32 v[106:107], v[106:107], v[228:229] op_sel:[0,1] op_sel_hi:[1,1]
	v_cvt_pk_bf16_f32 v156, v108, v109
	v_cvt_pk_bf16_f32 v157, v110, v111
	v_cvt_pk_bf16_f32 v158, v104, v105
	v_cvt_pk_bf16_f32 v159, v106, v107
	global_store_dwordx4 v[144:145], v[156:159], off
	v_pk_mul_f32 v[100:101], v[100:101], v[228:229] op_sel:[0,1] op_sel_hi:[1,1]
	v_pk_mul_f32 v[102:103], v[102:103], v[228:229] op_sel:[0,1] op_sel_hi:[1,1]
	v_pk_mul_f32 v[96:97], v[96:97], v[228:229] op_sel:[0,1] op_sel_hi:[1,1]
	v_pk_mul_f32 v[98:99], v[98:99], v[228:229] op_sel:[0,1] op_sel_hi:[1,1]
	v_cvt_pk_bf16_f32 v160, v100, v101
	v_cvt_pk_bf16_f32 v161, v102, v103
	v_cvt_pk_bf16_f32 v162, v96, v97
	v_cvt_pk_bf16_f32 v163, v98, v99
	global_store_dwordx4 v[144:145], v[160:163], off offset:256
	v_lshl_add_u64 v[144:145], v[144:145], 0, s[94:95]
	v_pk_mul_f32 v[92:93], v[92:93], v[230:231] op_sel_hi:[1,0]
	v_pk_mul_f32 v[94:95], v[94:95], v[230:231] op_sel_hi:[1,0]
	v_pk_mul_f32 v[88:89], v[88:89], v[230:231] op_sel_hi:[1,0]
	v_pk_mul_f32 v[90:91], v[90:91], v[230:231] op_sel_hi:[1,0]
	v_cvt_pk_bf16_f32 v156, v92, v93
	v_cvt_pk_bf16_f32 v157, v94, v95
	v_cvt_pk_bf16_f32 v158, v88, v89
	v_cvt_pk_bf16_f32 v159, v90, v91
	global_store_dwordx4 v[144:145], v[156:159], off
	v_pk_mul_f32 v[84:85], v[84:85], v[230:231] op_sel_hi:[1,0]
	v_pk_mul_f32 v[86:87], v[86:87], v[230:231] op_sel_hi:[1,0]
	v_pk_mul_f32 v[80:81], v[80:81], v[230:231] op_sel_hi:[1,0]
	v_pk_mul_f32 v[82:83], v[82:83], v[230:231] op_sel_hi:[1,0]
	v_cvt_pk_bf16_f32 v160, v84, v85
	v_cvt_pk_bf16_f32 v161, v86, v87
	v_cvt_pk_bf16_f32 v162, v80, v81
	v_cvt_pk_bf16_f32 v163, v82, v83
	global_store_dwordx4 v[144:145], v[160:163], off offset:256
	v_lshl_add_u64 v[144:145], v[144:145], 0, s[94:95]
	v_pk_mul_f32 v[76:77], v[76:77], v[230:231] op_sel:[0,1] op_sel_hi:[1,1]
	v_pk_mul_f32 v[78:79], v[78:79], v[230:231] op_sel:[0,1] op_sel_hi:[1,1]
	v_pk_mul_f32 v[72:73], v[72:73], v[230:231] op_sel:[0,1] op_sel_hi:[1,1]
	v_pk_mul_f32 v[74:75], v[74:75], v[230:231] op_sel:[0,1] op_sel_hi:[1,1]
	v_cvt_pk_bf16_f32 v156, v76, v77
	v_cvt_pk_bf16_f32 v157, v78, v79
	v_cvt_pk_bf16_f32 v158, v72, v73
	v_cvt_pk_bf16_f32 v159, v74, v75
	global_store_dwordx4 v[144:145], v[156:159], off
	v_pk_mul_f32 v[68:69], v[68:69], v[230:231] op_sel:[0,1] op_sel_hi:[1,1]
	v_pk_mul_f32 v[70:71], v[70:71], v[230:231] op_sel:[0,1] op_sel_hi:[1,1]
	v_pk_mul_f32 v[64:65], v[64:65], v[230:231] op_sel:[0,1] op_sel_hi:[1,1]
	v_pk_mul_f32 v[66:67], v[66:67], v[230:231] op_sel:[0,1] op_sel_hi:[1,1]
	v_cvt_pk_bf16_f32 v160, v68, v69
	v_cvt_pk_bf16_f32 v161, v70, v71
	v_cvt_pk_bf16_f32 v162, v64, v65
	v_cvt_pk_bf16_f32 v163, v66, v67
	global_store_dwordx4 v[144:145], v[160:163], off offset:256
	v_lshl_add_u64 v[144:145], v[144:145], 0, s[96:97]
	v_pk_mul_f32 v[60:61], v[60:61], v[232:233] op_sel_hi:[1,0]
	v_pk_mul_f32 v[62:63], v[62:63], v[232:233] op_sel_hi:[1,0]
	v_pk_mul_f32 v[56:57], v[56:57], v[232:233] op_sel_hi:[1,0]
	v_pk_mul_f32 v[58:59], v[58:59], v[232:233] op_sel_hi:[1,0]
	v_cvt_pk_bf16_f32 v156, v60, v61
	v_cvt_pk_bf16_f32 v157, v62, v63
	v_cvt_pk_bf16_f32 v158, v56, v57
	v_cvt_pk_bf16_f32 v159, v58, v59
	global_store_dwordx4 v[144:145], v[156:159], off
	v_pk_mul_f32 v[52:53], v[52:53], v[232:233] op_sel_hi:[1,0]
	v_pk_mul_f32 v[54:55], v[54:55], v[232:233] op_sel_hi:[1,0]
	v_pk_mul_f32 v[48:49], v[48:49], v[232:233] op_sel_hi:[1,0]
	v_pk_mul_f32 v[50:51], v[50:51], v[232:233] op_sel_hi:[1,0]
	v_cvt_pk_bf16_f32 v160, v52, v53
	v_cvt_pk_bf16_f32 v161, v54, v55
	v_cvt_pk_bf16_f32 v162, v48, v49
	v_cvt_pk_bf16_f32 v163, v50, v51
	global_store_dwordx4 v[144:145], v[160:163], off offset:256
	v_lshl_add_u64 v[144:145], v[144:145], 0, s[94:95]
	v_pk_mul_f32 v[44:45], v[44:45], v[232:233] op_sel:[0,1] op_sel_hi:[1,1]
	v_pk_mul_f32 v[46:47], v[46:47], v[232:233] op_sel:[0,1] op_sel_hi:[1,1]
	v_pk_mul_f32 v[40:41], v[40:41], v[232:233] op_sel:[0,1] op_sel_hi:[1,1]
	v_pk_mul_f32 v[42:43], v[42:43], v[232:233] op_sel:[0,1] op_sel_hi:[1,1]
	v_cvt_pk_bf16_f32 v156, v44, v45
	v_cvt_pk_bf16_f32 v157, v46, v47
	v_cvt_pk_bf16_f32 v158, v40, v41
	v_cvt_pk_bf16_f32 v159, v42, v43
	global_store_dwordx4 v[144:145], v[156:159], off
	v_pk_mul_f32 v[36:37], v[36:37], v[232:233] op_sel:[0,1] op_sel_hi:[1,1]
	v_pk_mul_f32 v[38:39], v[38:39], v[232:233] op_sel:[0,1] op_sel_hi:[1,1]
	v_pk_mul_f32 v[32:33], v[32:33], v[232:233] op_sel:[0,1] op_sel_hi:[1,1]
	v_pk_mul_f32 v[34:35], v[34:35], v[232:233] op_sel:[0,1] op_sel_hi:[1,1]
	v_cvt_pk_bf16_f32 v160, v36, v37
	v_cvt_pk_bf16_f32 v161, v38, v39
	v_cvt_pk_bf16_f32 v162, v32, v33
	v_cvt_pk_bf16_f32 v163, v34, v35
	global_store_dwordx4 v[144:145], v[160:163], off offset:256
	v_lshl_add_u64 v[144:145], v[144:145], 0, s[94:95]
	v_pk_mul_f32 v[28:29], v[28:29], v[234:235] op_sel_hi:[1,0]
	v_pk_mul_f32 v[30:31], v[30:31], v[234:235] op_sel_hi:[1,0]
	v_pk_mul_f32 v[24:25], v[24:25], v[234:235] op_sel_hi:[1,0]
	v_pk_mul_f32 v[26:27], v[26:27], v[234:235] op_sel_hi:[1,0]
	v_cvt_pk_bf16_f32 v156, v28, v29
	v_cvt_pk_bf16_f32 v157, v30, v31
	v_cvt_pk_bf16_f32 v158, v24, v25
	v_cvt_pk_bf16_f32 v159, v26, v27
	global_store_dwordx4 v[144:145], v[156:159], off
	v_pk_mul_f32 v[20:21], v[20:21], v[234:235] op_sel_hi:[1,0]
	v_pk_mul_f32 v[22:23], v[22:23], v[234:235] op_sel_hi:[1,0]
	v_pk_mul_f32 v[16:17], v[16:17], v[234:235] op_sel_hi:[1,0]
	v_pk_mul_f32 v[18:19], v[18:19], v[234:235] op_sel_hi:[1,0]
	v_cvt_pk_bf16_f32 v160, v20, v21
	v_cvt_pk_bf16_f32 v161, v22, v23
	v_cvt_pk_bf16_f32 v162, v16, v17
	v_cvt_pk_bf16_f32 v163, v18, v19
	global_store_dwordx4 v[144:145], v[160:163], off offset:256
	v_lshl_add_u64 v[144:145], v[144:145], 0, s[94:95]
	v_pk_mul_f32 v[12:13], v[12:13], v[234:235] op_sel:[0,1] op_sel_hi:[1,1]
	v_pk_mul_f32 v[14:15], v[14:15], v[234:235] op_sel:[0,1] op_sel_hi:[1,1]
	v_pk_mul_f32 v[8:9], v[8:9], v[234:235] op_sel:[0,1] op_sel_hi:[1,1]
	v_pk_mul_f32 v[10:11], v[10:11], v[234:235] op_sel:[0,1] op_sel_hi:[1,1]
	v_cvt_pk_bf16_f32 v156, v12, v13
	v_cvt_pk_bf16_f32 v157, v14, v15
	v_cvt_pk_bf16_f32 v158, v8, v9
	v_cvt_pk_bf16_f32 v159, v10, v11
	global_store_dwordx4 v[144:145], v[156:159], off
	v_pk_mul_f32 v[4:5], v[4:5], v[234:235] op_sel:[0,1] op_sel_hi:[1,1]
	v_pk_mul_f32 v[6:7], v[6:7], v[234:235] op_sel:[0,1] op_sel_hi:[1,1]
	v_pk_mul_f32 v[0:1], v[0:1], v[234:235] op_sel:[0,1] op_sel_hi:[1,1]
	v_pk_mul_f32 v[2:3], v[2:3], v[234:235] op_sel:[0,1] op_sel_hi:[1,1]
	v_cvt_pk_bf16_f32 v160, v4, v5
	v_cvt_pk_bf16_f32 v161, v6, v7
	v_cvt_pk_bf16_f32 v162, v0, v1
	v_cvt_pk_bf16_f32 v163, v2, v3
	global_store_dwordx4 v[144:145], v[160:163], off offset:256
	s_mov_b64 s[4:5], -1
	s_cbranch_vccnz .LBB0_963
	s_branch .Lip1_tail

.LBB0_1604:
	s_or_b64 exec, exec, s[4:5]
	s_mov_b32 s100, 0
	s_mov_b64 s[4:5], s[0:1]
	s_mov_b64 s[6:7], s[0:1]
	s_mov_b32 s3, s33
	s_mov_b32 s38, s2
	v_mov_b32_e32 v8, v154
	s_waitcnt lgkmcnt(0)
	s_barrier
	s_cmpk_gt_i32 s38, 0x57f
	v_readfirstlane_b32 s10, v8
	s_cbranch_scc1 .LBB0_1620
	v_lshlrev_b32_e32 v0, 4, v8
	v_add_u32_e32 v1, 0x2000, v0
	v_ashrrev_i32_e32 v2, 31, v1
	v_lshrrev_b32_e32 v2, 22, v2
	v_add_u32_e32 v2, v1, v2
	v_ashrrev_i32_e32 v9, 10, v2
	v_mul_i32_i24_e32 v2, 0x400, v9
	v_sub_u32_e32 v1, v1, v2
	v_lshrrev_b32_e32 v2, 4, v1
	v_bitop3_b32 v1, v2, v1, 32 bitop3:0x6c
	v_ashrrev_i32_e32 v2, 31, v1
	v_lshrrev_b32_e32 v2, 26, v2
	v_add_u32_e32 v2, v1, v2
	v_lshlrev_b32_e32 v3, 3, v9
	v_ashrrev_i32_e32 v10, 6, v2
	v_and_b32_e32 v3, -16, v3
	v_add_u32_e32 v3, v10, v3
	s_load_dwordx2 s[8:9], s[4:5], 0x130
	s_load_dwordx2 s[12:13], s[6:7], 0x138
	v_and_b32_e32 v4, 3, v10
	s_mov_b32 s4, 0x1fffe0
	v_lshrrev_b32_e32 v5, 2, v3
	v_lshlrev_b32_e32 v6, 1, v3
	v_and_b32_e32 v2, 0xc0, v2
	v_and_or_b32 v4, v3, s4, v4
	v_and_b32_e32 v5, 4, v5
	v_and_b32_e32 v6, 24, v6
	v_sub_u32_e32 v1, v1, v2
	v_mov_b32_e32 v2, 1
	v_or3_b32 v4, v4, v5, v6
	v_lshlrev_b32_e32 v5, 5, v9
	v_ashrrev_i16_sdwa v1, v2, sext(v1) dst_sel:DWORD dst_unused:UNUSED_PAD src0_sel:DWORD src1_sel:BYTE_0
	v_and_b32_e32 v5, 32, v5
	v_bfe_i32 v11, v1, 0, 16
	v_add_lshl_u32 v1, v5, v11, 1
	v_lshl_add_u32 v128, v4, 11, v1
	v_lshl_add_u32 v130, v3, 11, v1
	v_bfe_i32 v1, v8, 27, 1
	v_lshrrev_b32_e32 v1, 22, v1
	v_add_u32_e32 v1, v0, v1
	v_and_b32_e32 v1, 0xfffffc00, v1
	v_sub_u32_e32 v0, v0, v1
	v_lshrrev_b32_e32 v1, 4, v0
	v_ashrrev_i32_e32 v3, 31, v8
	v_bitop3_b32 v0, v1, v0, 32 bitop3:0x6c
	v_lshrrev_b32_e32 v3, 26, v3
	v_ashrrev_i32_e32 v1, 31, v0
	v_add_u32_e32 v3, v8, v3
	s_waitcnt lgkmcnt(0)
	s_add_u32 s39, s8, 0x2000000
	v_lshrrev_b32_e32 v1, 26, v1
	v_ashrrev_i32_e32 v13, 6, v3
	s_addc_u32 s40, s9, 0
	v_add_u32_e32 v1, v0, v1
	v_lshlrev_b32_e32 v3, 3, v13
	s_add_u32 s41, s12, 0xa80000
	v_ashrrev_i32_e32 v12, 6, v1
	v_and_b32_e32 v3, -16, v3
	s_addc_u32 s42, s13, 0
	v_add_u32_e32 v3, v12, v3
	v_and_b32_e32 v4, 3, v12
	s_ashr_i32 s44, s38, 31
	v_and_or_b32 v4, v3, s4, v4
	s_lshr_b32 s4, s44, 29
	s_add_i32 s4, s38, s4
	s_ashr_i32 s8, s10, 6
	s_ashr_i32 s6, s4, 3
	s_and_b32 s4, s4, -8
	s_ashr_i32 s5, s10, 8
	s_lshl_b32 s43, s8, 10
	s_sub_i32 s4, s38, s4
	s_cmp_lt_i32 s4, 0
	s_movk_i32 s45, 0xb1
	s_cselect_b32 s7, s45, 0xb0
	s_mul_i32 s4, s7, s4
	s_add_i32 s4, s4, s6
	s_mul_hi_i32 s6, s4, 0x2e8ba2e9
	s_lshr_b32 s7, s6, 31
	s_ashr_i32 s6, s6, 5
	s_add_i32 s6, s6, s7
	s_lshl_b32 s7, s6, 3
	s_mulk_i32 s6, 0xb0
	s_sub_i32 s6, s4, s6
	s_bfe_u32 s4, s6, 0x3001c
	s_add_i32 s9, s6, s4
	s_sext_i32_i16 s4, s9
	s_and_b32 s9, s9, 0xfff8
	s_sub_i32 s6, s6, s9
	s_sext_i32_i16 s6, s6
	v_lshrrev_b32_e32 v5, 2, v3
	v_lshlrev_b32_e32 v6, 1, v3
	v_and_b32_e32 v1, 0xc0, v1
	s_lshr_b32 s4, s4, 3
	s_add_i32 s30, s7, s6
	v_and_b32_e32 v5, 4, v5
	v_and_b32_e32 v6, 24, v6
	v_sub_u32_e32 v0, v0, v1
	s_ashr_i32 s31, s30, 31
	s_bfe_i64 s[12:13], s[4:5], 0x100000
	v_or3_b32 v4, v4, v5, v6
	v_lshlrev_b32_e32 v5, 5, v13
	v_ashrrev_i16_sdwa v0, v2, sext(v0) dst_sel:DWORD dst_unused:UNUSED_PAD src0_sel:DWORD src1_sel:BYTE_0
	s_lshl_b64 s[6:7], s[30:31], 19
	s_lshl_b64 s[12:13], s[12:13], 19
	v_and_b32_e32 v5, 32, v5
	v_bfe_i32 v14, v0, 0, 16
	s_add_u32 s28, s41, s12
	v_add_lshl_u32 v0, v5, v14, 1
	s_addc_u32 s29, s42, s13
	s_add_i32 s31, s43, 0
	v_lshl_add_u32 v132, v4, 11, v0
	s_add_i32 m0, s31, 0x10000
	v_lshl_add_u32 v134, v3, 11, v0
	global_load_lds_dwordx4 v132, s[28:29]
	s_add_i32 m0, s31, 0x12000
	s_add_u32 s12, s28, 0x40000
	global_load_lds_dwordx4 v128, s[28:29]
	s_addc_u32 s13, s29, 0
	s_add_i32 m0, s31, 0x14000
	v_mov_b32_e32 v133, 0
	global_load_lds_dwordx4 v132, s[12:13]
	s_add_i32 m0, s31, 0x16000
	s_add_u32 s34, s39, s6
	s_addc_u32 s35, s40, s7
	s_add_i32 s46, s31, 0x2000
	global_load_lds_dwordx4 v128, s[12:13]
	s_mov_b32 m0, s31
	s_add_u32 s6, s34, 0x40000
	global_load_lds_dwordx4 v134, s[34:35]
	s_mov_b32 m0, s46
	s_addc_u32 s7, s35, 0
	s_add_i32 s47, s31, 0x4000
	global_load_lds_dwordx4 v130, s[34:35]
	s_mov_b32 m0, s47
	s_add_i32 s48, s31, 0x6000
	global_load_lds_dwordx4 v134, s[6:7]
	s_mov_b32 m0, s48
	v_mov_b32_e32 v129, v133
	global_load_lds_dwordx4 v130, s[6:7]
	v_mov_b32_e32 v135, v133
	v_mov_b32_e32 v131, v133
	s_cmp_eq_u32 s5, 1
	s_mov_b32 s49, 0
	v_lshl_add_u64 v[6:7], s[28:29], 0, v[132:133]
	v_lshl_add_u64 v[4:5], s[28:29], 0, v[128:129]
	v_lshl_add_u64 v[0:1], s[34:35], 0, v[134:135]
	s_cselect_b64 s[6:7], -1, 0
	s_cmp_lg_u32 s5, 1
	v_lshl_add_u64 v[2:3], s[34:35], 0, v[130:131]
	s_cbranch_scc1 .LBB0_1607
	s_barrier

.LBB0_1616:
	s_add_i32 s101, s30, 1
	s_cmp_eq_u32 s100, s101
	s_cbranch_scc1 .Lgu1_fast
	s_mov_b32 s100, s101
	v_mov_b32_e32 v153, v154
	s_mov_b64 s[28:29], s[0:1]
	s_load_dwordx2 s[34:35], s[28:29], 0x138
	s_waitcnt lgkmcnt(0)
	s_add_u32 s28, s34, 0xfe00000
	s_addc_u32 s29, s35, 0
	s_lshl_b32 s15, s30, 8
	s_add_i32 s15, s15, s50
	v_and_or_b32 v146, v153, 15, s15
	v_ashrrev_i32_e32 v147, 31, v146
	v_lshlrev_b64 v[144:145], 6, v[146:147]
	v_lshl_add_u64 v[144:145], s[28:29], 0, v[144:145]
	global_load_dwordx4 v[156:159], v[144:145], off
	global_load_dwordx4 v[160:163], v[144:145], off offset:32
	global_load_dwordx4 v[164:167], v[144:145], off offset:16
	global_load_dwordx4 v[168:171], v[144:145], off offset:48
	v_lshrrev_b32_e32 v144, 2, v153
	s_lshl_b32 s15, s58, 7
	s_or_b32 s15, s15, s53
	v_and_or_b32 v144, v144, 12, s15
	v_ashrrev_i32_e32 v145, 31, v144
	v_or_b32_e32 v172, 16, v146
	v_lshl_add_u64 v[144:145], v[144:145], 1, s[34:35]
	v_ashrrev_i32_e32 v173, 31, v172
	v_lshl_add_u64 v[144:145], v[144:145], 0, s[12:13]
	v_lshlrev_b64 v[174:175], 6, v[172:173]
	s_andn2_b64 vcc, exec, s[4:5]
	s_waitcnt vmcnt(0)
	v_mov_b32_e32 v176, v156
	v_mov_b32_e32 v177, v160
	v_mov_b32_e32 v160, v157
	v_mov_b32_e32 v156, v158
	v_mov_b32_e32 v157, v162
	v_mov_b32_e32 v162, v159
	v_mov_b32_e32 v158, v164
	v_mov_b32_e32 v159, v168
	v_mov_b32_e32 v168, v165
	v_mov_b32_e32 v164, v166
	v_mov_b32_e32 v165, v170
	v_mov_b32_e32 v170, v167
	v_pk_add_f32 v[160:161], v[176:177], v[160:161]
	v_pk_add_f32 v[156:157], v[156:157], v[162:163]
	v_pk_add_f32 v[158:159], v[158:159], v[168:169]
	v_pk_add_f32 v[162:163], v[164:165], v[170:171]
	v_pk_add_f32 v[156:157], v[160:161], v[156:157]
	v_pk_add_f32 v[158:159], v[158:159], v[162:163]
	v_lshl_add_u64 v[160:161], s[28:29], 0, v[174:175]
	v_pk_add_f32 v[156:157], v[156:157], v[158:159]
	v_mad_i64_i32 v[158:159], s[34:35], v146, s57, v[144:145]
	v_add_f32_e32 v147, v156, v157
	v_fmamk_f32 v147, v147, 0x3a800000, v152
	v_rsq_f32_e32 v156, v147
	s_nop 0
	v_mov_b32_e32 v228, v156
	v_pk_mul_f32 v[124:125], v[124:125], v[156:157] op_sel_hi:[1,0]
	v_pk_mul_f32 v[126:127], v[126:127], v[156:157] op_sel_hi:[1,0]
	v_pk_mul_f32 v[120:121], v[120:121], v[156:157] op_sel_hi:[1,0]
	v_pk_mul_f32 v[122:123], v[122:123], v[156:157] op_sel_hi:[1,0]
	v_pk_mul_f32 v[116:117], v[116:117], v[156:157] op_sel_hi:[1,0]
	v_pk_mul_f32 v[112:113], v[112:113], v[156:157] op_sel_hi:[1,0]
	v_pk_mul_f32 v[118:119], v[118:119], v[156:157] op_sel_hi:[1,0]
	v_pk_mul_f32 v[114:115], v[114:115], v[156:157] op_sel_hi:[1,0]
	v_mul_f32_e32 v147, 0xbfb8aa3b, v124
	v_mul_f32_e32 v153, 0xbfb8aa3b, v125
	v_mul_f32_e32 v156, 0xbfb8aa3b, v126
	v_mul_f32_e32 v157, 0xbfb8aa3b, v127
	v_mul_f32_e32 v162, 0xbfb8aa3b, v116
	v_mul_f32_e32 v163, 0xbfb8aa3b, v117
	v_mul_f32_e32 v164, 0xbfb8aa3b, v118
	v_mul_f32_e32 v165, 0xbfb8aa3b, v119
	v_exp_f32_e32 v147, v147
	v_exp_f32_e32 v153, v153
	v_exp_f32_e32 v156, v156
	v_exp_f32_e32 v157, v157
	v_exp_f32_e32 v162, v162
	v_exp_f32_e32 v163, v163
	v_exp_f32_e32 v164, v164
	v_exp_f32_e32 v165, v165
	v_add_f32_e32 v147, 1.0, v147
	v_add_f32_e32 v153, 1.0, v153
	v_add_f32_e32 v166, 1.0, v156
	v_add_f32_e32 v167, 1.0, v157
	v_add_f32_e32 v168, 1.0, v162
	v_add_f32_e32 v169, 1.0, v163
	v_add_f32_e32 v170, 1.0, v164
	v_add_f32_e32 v171, 1.0, v165
	v_rcp_f32_e32 v156, v147
	v_rcp_f32_e32 v157, v153
	v_rcp_f32_e32 v162, v166
	v_rcp_f32_e32 v163, v167
	v_rcp_f32_e32 v164, v168
	v_rcp_f32_e32 v165, v169
	v_rcp_f32_e32 v166, v170
	v_rcp_f32_e32 v167, v171
	v_pk_mul_f32 v[124:125], v[124:125], v[156:157]
	v_pk_mul_f32 v[126:127], v[126:127], v[162:163]
	v_pk_mul_f32 v[116:117], v[116:117], v[164:165]
	v_pk_mul_f32 v[118:119], v[118:119], v[166:167]
	v_pk_mul_f32 v[120:121], v[120:121], v[124:125]
	v_pk_mul_f32 v[122:123], v[122:123], v[126:127]
	v_pk_mul_f32 v[112:113], v[112:113], v[116:117]
	v_pk_mul_f32 v[114:115], v[114:115], v[118:119]
	v_cvt_pk_bf16_f32 v116, v120, v121
	v_cvt_pk_bf16_f32 v117, v122, v123
	v_cvt_pk_bf16_f32 v112, v112, v113
	v_cvt_pk_bf16_f32 v113, v114, v115
	global_store_dwordx2 v[158:159], v[116:117], off
	global_store_dwordx2 v[158:159], v[112:113], off offset:128
	global_load_dwordx4 v[112:115], v[160:161], off
	s_nop 0
	global_load_dwordx4 v[116:119], v[160:161], off offset:32
	global_load_dwordx4 v[120:123], v[160:161], off offset:16
	global_load_dwordx4 v[124:127], v[160:161], off offset:48
	v_or_b32_e32 v156, 32, v146
	v_ashrrev_i32_e32 v157, 31, v156
	v_lshlrev_b64 v[158:159], 6, v[156:157]
	s_waitcnt vmcnt(3)
	v_mov_b32_e32 v160, v112
	s_waitcnt vmcnt(2)
	v_mov_b32_e32 v161, v116
	v_mov_b32_e32 v116, v113
	v_mov_b32_e32 v112, v114
	v_mov_b32_e32 v113, v118
	v_mov_b32_e32 v118, v115
	s_waitcnt vmcnt(1)
	v_mov_b32_e32 v114, v120
	s_waitcnt vmcnt(0)
	v_mov_b32_e32 v115, v124
	v_mov_b32_e32 v124, v121
	v_mov_b32_e32 v120, v122
	v_mov_b32_e32 v121, v126
	v_mov_b32_e32 v126, v123
	v_pk_add_f32 v[116:117], v[160:161], v[116:117]
	v_pk_add_f32 v[112:113], v[112:113], v[118:119]
	v_pk_add_f32 v[114:115], v[114:115], v[124:125]
	v_pk_add_f32 v[118:119], v[120:121], v[126:127]
	v_pk_add_f32 v[112:113], v[116:117], v[112:113]
	v_pk_add_f32 v[114:115], v[114:115], v[118:119]
	v_lshl_add_u64 v[116:117], s[28:29], 0, v[158:159]
	v_pk_add_f32 v[112:113], v[112:113], v[114:115]
	v_mad_i64_i32 v[114:115], s[34:35], v172, s57, v[144:145]
	v_add_f32_e32 v112, v112, v113
	v_fmamk_f32 v112, v112, 0x3a800000, v152
	v_rsq_f32_e32 v112, v112
	s_nop 0
	v_mov_b32_e32 v229, v112
	v_pk_mul_f32 v[108:109], v[108:109], v[112:113] op_sel_hi:[1,0]
	v_pk_mul_f32 v[110:111], v[110:111], v[112:113] op_sel_hi:[1,0]
	v_pk_mul_f32 v[104:105], v[104:105], v[112:113] op_sel_hi:[1,0]
	v_pk_mul_f32 v[106:107], v[106:107], v[112:113] op_sel_hi:[1,0]
	v_pk_mul_f32 v[100:101], v[100:101], v[112:113] op_sel_hi:[1,0]
	v_pk_mul_f32 v[96:97], v[96:97], v[112:113] op_sel_hi:[1,0]
	v_pk_mul_f32 v[102:103], v[102:103], v[112:113] op_sel_hi:[1,0]
	v_pk_mul_f32 v[98:99], v[98:99], v[112:113] op_sel_hi:[1,0]
	v_mul_f32_e32 v112, 0xbfb8aa3b, v108
	v_mul_f32_e32 v113, 0xbfb8aa3b, v109
	v_mul_f32_e32 v118, 0xbfb8aa3b, v110
	v_mul_f32_e32 v119, 0xbfb8aa3b, v111
	v_mul_f32_e32 v120, 0xbfb8aa3b, v100
	v_mul_f32_e32 v121, 0xbfb8aa3b, v101
	v_mul_f32_e32 v122, 0xbfb8aa3b, v102
	v_mul_f32_e32 v123, 0xbfb8aa3b, v103
	v_exp_f32_e32 v112, v112
	v_exp_f32_e32 v113, v113
	v_exp_f32_e32 v118, v118
	v_exp_f32_e32 v119, v119
	v_exp_f32_e32 v120, v120
	v_exp_f32_e32 v121, v121
	v_exp_f32_e32 v122, v122
	v_exp_f32_e32 v123, v123
	v_add_f32_e32 v112, 1.0, v112
	v_add_f32_e32 v113, 1.0, v113
	v_add_f32_e32 v118, 1.0, v118
	v_add_f32_e32 v119, 1.0, v119
	v_add_f32_e32 v120, 1.0, v120
	v_add_f32_e32 v121, 1.0, v121
	v_add_f32_e32 v122, 1.0, v122
	v_add_f32_e32 v123, 1.0, v123
	v_rcp_f32_e32 v112, v112
	v_rcp_f32_e32 v113, v113
	v_rcp_f32_e32 v118, v118
	v_rcp_f32_e32 v119, v119
	v_rcp_f32_e32 v120, v120
	v_rcp_f32_e32 v121, v121
	v_rcp_f32_e32 v122, v122
	v_rcp_f32_e32 v123, v123
	v_pk_mul_f32 v[108:109], v[108:109], v[112:113]
	v_pk_mul_f32 v[110:111], v[110:111], v[118:119]
	v_pk_mul_f32 v[100:101], v[100:101], v[120:121]
	v_pk_mul_f32 v[102:103], v[102:103], v[122:123]
	v_pk_mul_f32 v[104:105], v[104:105], v[108:109]
	v_pk_mul_f32 v[106:107], v[106:107], v[110:111]
	v_pk_mul_f32 v[96:97], v[96:97], v[100:101]
	v_pk_mul_f32 v[98:99], v[98:99], v[102:103]
	v_cvt_pk_bf16_f32 v100, v104, v105
	v_cvt_pk_bf16_f32 v101, v106, v107
	v_cvt_pk_bf16_f32 v96, v96, v97
	v_cvt_pk_bf16_f32 v97, v98, v99
	global_store_dwordx2 v[114:115], v[100:101], off
	global_store_dwordx2 v[114:115], v[96:97], off offset:128
	global_load_dwordx4 v[96:99], v[116:117], off
	s_nop 0
	global_load_dwordx4 v[100:103], v[116:117], off offset:32
	global_load_dwordx4 v[104:107], v[116:117], off offset:16
	global_load_dwordx4 v[108:111], v[116:117], off offset:48
	v_or_b32_e32 v112, 48, v146
	v_ashrrev_i32_e32 v113, 31, v112
	v_lshlrev_b64 v[114:115], 6, v[112:113]
	s_waitcnt vmcnt(3)
	v_mov_b32_e32 v116, v96
	s_waitcnt vmcnt(2)
	v_mov_b32_e32 v117, v100
	v_mov_b32_e32 v100, v97
	v_mov_b32_e32 v96, v98
	v_mov_b32_e32 v97, v102
	v_mov_b32_e32 v102, v99
	s_waitcnt vmcnt(1)
	v_mov_b32_e32 v98, v104
	s_waitcnt vmcnt(0)
	v_mov_b32_e32 v99, v108
	v_mov_b32_e32 v108, v105
	v_mov_b32_e32 v104, v106
	v_mov_b32_e32 v105, v110
	v_mov_b32_e32 v110, v107
	v_pk_add_f32 v[100:101], v[116:117], v[100:101]
	v_pk_add_f32 v[96:97], v[96:97], v[102:103]
	v_pk_add_f32 v[98:99], v[98:99], v[108:109]
	v_pk_add_f32 v[102:103], v[104:105], v[110:111]
	v_pk_add_f32 v[96:97], v[100:101], v[96:97]
	v_pk_add_f32 v[98:99], v[98:99], v[102:103]
	v_lshl_add_u64 v[100:101], s[28:29], 0, v[114:115]
	v_pk_add_f32 v[96:97], v[96:97], v[98:99]
	v_mad_i64_i32 v[98:99], s[34:35], v156, s57, v[144:145]
	v_add_f32_e32 v96, v96, v97
	v_fmamk_f32 v96, v96, 0x3a800000, v152
	v_rsq_f32_e32 v96, v96
	s_nop 0
	v_mov_b32_e32 v230, v96
	v_pk_mul_f32 v[92:93], v[92:93], v[96:97] op_sel_hi:[1,0]
	v_pk_mul_f32 v[94:95], v[94:95], v[96:97] op_sel_hi:[1,0]
	v_pk_mul_f32 v[88:89], v[88:89], v[96:97] op_sel_hi:[1,0]
	v_pk_mul_f32 v[90:91], v[90:91], v[96:97] op_sel_hi:[1,0]
	v_pk_mul_f32 v[84:85], v[84:85], v[96:97] op_sel_hi:[1,0]
	v_pk_mul_f32 v[80:81], v[80:81], v[96:97] op_sel_hi:[1,0]
	v_pk_mul_f32 v[86:87], v[86:87], v[96:97] op_sel_hi:[1,0]
	v_pk_mul_f32 v[82:83], v[82:83], v[96:97] op_sel_hi:[1,0]
	v_mul_f32_e32 v96, 0xbfb8aa3b, v92
	v_mul_f32_e32 v97, 0xbfb8aa3b, v93
	v_mul_f32_e32 v102, 0xbfb8aa3b, v94
	v_mul_f32_e32 v103, 0xbfb8aa3b, v95
	v_mul_f32_e32 v104, 0xbfb8aa3b, v84
	v_mul_f32_e32 v105, 0xbfb8aa3b, v85
	v_mul_f32_e32 v106, 0xbfb8aa3b, v86
	v_mul_f32_e32 v107, 0xbfb8aa3b, v87
	v_exp_f32_e32 v96, v96
	v_exp_f32_e32 v97, v97
	v_exp_f32_e32 v102, v102
	v_exp_f32_e32 v103, v103
	v_exp_f32_e32 v104, v104
	v_exp_f32_e32 v105, v105
	v_exp_f32_e32 v106, v106
	v_exp_f32_e32 v107, v107
	v_add_f32_e32 v96, 1.0, v96
	v_add_f32_e32 v97, 1.0, v97
	v_add_f32_e32 v102, 1.0, v102
	v_add_f32_e32 v103, 1.0, v103
	v_add_f32_e32 v104, 1.0, v104
	v_add_f32_e32 v105, 1.0, v105
	v_add_f32_e32 v106, 1.0, v106
	v_add_f32_e32 v107, 1.0, v107
	v_rcp_f32_e32 v96, v96
	v_rcp_f32_e32 v97, v97
	v_rcp_f32_e32 v102, v102
	v_rcp_f32_e32 v103, v103
	v_rcp_f32_e32 v104, v104
	v_rcp_f32_e32 v105, v105
	v_rcp_f32_e32 v106, v106
	v_rcp_f32_e32 v107, v107
	v_pk_mul_f32 v[92:93], v[92:93], v[96:97]
	v_pk_mul_f32 v[94:95], v[94:95], v[102:103]
	v_pk_mul_f32 v[84:85], v[84:85], v[104:105]
	v_pk_mul_f32 v[86:87], v[86:87], v[106:107]
	v_pk_mul_f32 v[88:89], v[88:89], v[92:93]
	v_pk_mul_f32 v[90:91], v[90:91], v[94:95]
	v_pk_mul_f32 v[80:81], v[80:81], v[84:85]
	v_pk_mul_f32 v[82:83], v[82:83], v[86:87]
	v_cvt_pk_bf16_f32 v84, v88, v89
	v_cvt_pk_bf16_f32 v85, v90, v91
	v_cvt_pk_bf16_f32 v80, v80, v81
	v_cvt_pk_bf16_f32 v81, v82, v83
	global_store_dwordx2 v[98:99], v[84:85], off
	global_store_dwordx2 v[98:99], v[80:81], off offset:128
	global_load_dwordx4 v[80:83], v[100:101], off
	s_nop 0
	global_load_dwordx4 v[84:87], v[100:101], off offset:32
	global_load_dwordx4 v[88:91], v[100:101], off offset:16
	global_load_dwordx4 v[92:95], v[100:101], off offset:48
	v_add_u32_e32 v96, 0x80, v146
	v_ashrrev_i32_e32 v97, 31, v96
	v_lshlrev_b64 v[98:99], 6, v[96:97]
	s_waitcnt vmcnt(3)
	v_mov_b32_e32 v100, v80
	s_waitcnt vmcnt(2)
	v_mov_b32_e32 v101, v84
	v_mov_b32_e32 v84, v81
	v_mov_b32_e32 v80, v82
	v_mov_b32_e32 v81, v86
	v_mov_b32_e32 v86, v83
	s_waitcnt vmcnt(1)
	v_mov_b32_e32 v82, v88
	s_waitcnt vmcnt(0)
	v_mov_b32_e32 v83, v92
	v_mov_b32_e32 v92, v89
	v_mov_b32_e32 v88, v90
	v_mov_b32_e32 v89, v94
	v_mov_b32_e32 v94, v91
	v_pk_add_f32 v[84:85], v[100:101], v[84:85]
	v_pk_add_f32 v[80:81], v[80:81], v[86:87]
	v_pk_add_f32 v[82:83], v[82:83], v[92:93]
	v_pk_add_f32 v[86:87], v[88:89], v[94:95]
	v_pk_add_f32 v[80:81], v[84:85], v[80:81]
	v_pk_add_f32 v[82:83], v[82:83], v[86:87]
	v_lshl_add_u64 v[84:85], s[28:29], 0, v[98:99]
	v_pk_add_f32 v[80:81], v[80:81], v[82:83]
	v_mad_i64_i32 v[82:83], s[34:35], v112, s57, v[144:145]
	v_add_f32_e32 v80, v80, v81
	v_fmamk_f32 v80, v80, 0x3a800000, v152
	v_rsq_f32_e32 v80, v80
	s_nop 0
	v_mov_b32_e32 v231, v80
	v_pk_mul_f32 v[76:77], v[76:77], v[80:81] op_sel_hi:[1,0]
	v_pk_mul_f32 v[78:79], v[78:79], v[80:81] op_sel_hi:[1,0]
	v_pk_mul_f32 v[72:73], v[72:73], v[80:81] op_sel_hi:[1,0]
	v_pk_mul_f32 v[74:75], v[74:75], v[80:81] op_sel_hi:[1,0]
	v_pk_mul_f32 v[68:69], v[68:69], v[80:81] op_sel_hi:[1,0]
	v_pk_mul_f32 v[64:65], v[64:65], v[80:81] op_sel_hi:[1,0]
	v_pk_mul_f32 v[70:71], v[70:71], v[80:81] op_sel_hi:[1,0]
	v_pk_mul_f32 v[66:67], v[66:67], v[80:81] op_sel_hi:[1,0]
	v_mul_f32_e32 v80, 0xbfb8aa3b, v76
	v_mul_f32_e32 v81, 0xbfb8aa3b, v77
	v_mul_f32_e32 v86, 0xbfb8aa3b, v78
	v_mul_f32_e32 v87, 0xbfb8aa3b, v79
	v_mul_f32_e32 v88, 0xbfb8aa3b, v68
	v_mul_f32_e32 v89, 0xbfb8aa3b, v69
	v_mul_f32_e32 v90, 0xbfb8aa3b, v70
	v_mul_f32_e32 v91, 0xbfb8aa3b, v71
	v_exp_f32_e32 v80, v80
	v_exp_f32_e32 v81, v81
	v_exp_f32_e32 v86, v86
	v_exp_f32_e32 v87, v87
	v_exp_f32_e32 v88, v88
	v_exp_f32_e32 v89, v89
	v_exp_f32_e32 v90, v90
	v_exp_f32_e32 v91, v91
	v_add_f32_e32 v80, 1.0, v80
	v_add_f32_e32 v81, 1.0, v81
	v_add_f32_e32 v86, 1.0, v86
	v_add_f32_e32 v87, 1.0, v87
	v_add_f32_e32 v88, 1.0, v88
	v_add_f32_e32 v89, 1.0, v89
	v_add_f32_e32 v90, 1.0, v90
	v_add_f32_e32 v91, 1.0, v91
	v_rcp_f32_e32 v80, v80
	v_rcp_f32_e32 v81, v81
	v_rcp_f32_e32 v86, v86
	v_rcp_f32_e32 v87, v87
	v_rcp_f32_e32 v88, v88
	v_rcp_f32_e32 v89, v89
	v_rcp_f32_e32 v90, v90
	v_rcp_f32_e32 v91, v91
	v_pk_mul_f32 v[76:77], v[76:77], v[80:81]
	v_pk_mul_f32 v[78:79], v[78:79], v[86:87]
	v_pk_mul_f32 v[68:69], v[68:69], v[88:89]
	v_pk_mul_f32 v[70:71], v[70:71], v[90:91]
	v_pk_mul_f32 v[72:73], v[72:73], v[76:77]
	v_pk_mul_f32 v[74:75], v[74:75], v[78:79]
	v_pk_mul_f32 v[64:65], v[64:65], v[68:69]
	v_pk_mul_f32 v[66:67], v[66:67], v[70:71]
	v_cvt_pk_bf16_f32 v68, v72, v73
	v_cvt_pk_bf16_f32 v69, v74, v75
	v_cvt_pk_bf16_f32 v64, v64, v65
	v_cvt_pk_bf16_f32 v65, v66, v67
	global_store_dwordx2 v[82:83], v[68:69], off
	global_store_dwordx2 v[82:83], v[64:65], off offset:128
	global_load_dwordx4 v[64:67], v[84:85], off
	s_nop 0
	global_load_dwordx4 v[68:71], v[84:85], off offset:32
	global_load_dwordx4 v[72:75], v[84:85], off offset:16
	global_load_dwordx4 v[76:79], v[84:85], off offset:48
	v_add_u32_e32 v80, 0x90, v146
	v_ashrrev_i32_e32 v81, 31, v80
	v_lshlrev_b64 v[82:83], 6, v[80:81]
	s_waitcnt vmcnt(3)
	v_mov_b32_e32 v84, v64
	s_waitcnt vmcnt(2)
	v_mov_b32_e32 v85, v68
	v_mov_b32_e32 v68, v65
	v_mov_b32_e32 v64, v66
	v_mov_b32_e32 v65, v70
	v_mov_b32_e32 v70, v67
	s_waitcnt vmcnt(1)
	v_mov_b32_e32 v66, v72
	s_waitcnt vmcnt(0)
	v_mov_b32_e32 v67, v76
	v_mov_b32_e32 v76, v73
	v_mov_b32_e32 v72, v74
	v_mov_b32_e32 v73, v78
	v_mov_b32_e32 v78, v75
	v_pk_add_f32 v[68:69], v[84:85], v[68:69]
	v_pk_add_f32 v[64:65], v[64:65], v[70:71]
	v_pk_add_f32 v[66:67], v[66:67], v[76:77]
	v_pk_add_f32 v[70:71], v[72:73], v[78:79]
	v_pk_add_f32 v[64:65], v[68:69], v[64:65]
	v_pk_add_f32 v[66:67], v[66:67], v[70:71]
	v_lshl_add_u64 v[68:69], s[28:29], 0, v[82:83]
	v_pk_add_f32 v[64:65], v[64:65], v[66:67]
	v_mad_i64_i32 v[66:67], s[34:35], v96, s57, v[144:145]
	v_add_f32_e32 v64, v64, v65
	v_fmamk_f32 v64, v64, 0x3a800000, v152
	v_rsq_f32_e32 v64, v64
	s_nop 0
	v_mov_b32_e32 v232, v64
	v_pk_mul_f32 v[60:61], v[60:61], v[64:65] op_sel_hi:[1,0]
	v_pk_mul_f32 v[62:63], v[62:63], v[64:65] op_sel_hi:[1,0]
	v_pk_mul_f32 v[56:57], v[56:57], v[64:65] op_sel_hi:[1,0]
	v_pk_mul_f32 v[58:59], v[58:59], v[64:65] op_sel_hi:[1,0]
	v_pk_mul_f32 v[52:53], v[52:53], v[64:65] op_sel_hi:[1,0]
	v_pk_mul_f32 v[48:49], v[48:49], v[64:65] op_sel_hi:[1,0]
	v_pk_mul_f32 v[54:55], v[54:55], v[64:65] op_sel_hi:[1,0]
	v_pk_mul_f32 v[50:51], v[50:51], v[64:65] op_sel_hi:[1,0]
	v_mul_f32_e32 v64, 0xbfb8aa3b, v60
	v_mul_f32_e32 v65, 0xbfb8aa3b, v61
	v_mul_f32_e32 v70, 0xbfb8aa3b, v62
	v_mul_f32_e32 v71, 0xbfb8aa3b, v63
	v_mul_f32_e32 v72, 0xbfb8aa3b, v52
	v_mul_f32_e32 v73, 0xbfb8aa3b, v53
	v_mul_f32_e32 v74, 0xbfb8aa3b, v54
	v_mul_f32_e32 v75, 0xbfb8aa3b, v55
	v_exp_f32_e32 v64, v64
	v_exp_f32_e32 v65, v65
	v_exp_f32_e32 v70, v70
	v_exp_f32_e32 v71, v71
	v_exp_f32_e32 v72, v72
	v_exp_f32_e32 v73, v73
	v_exp_f32_e32 v74, v74
	v_exp_f32_e32 v75, v75
	v_add_f32_e32 v64, 1.0, v64
	v_add_f32_e32 v65, 1.0, v65
	v_add_f32_e32 v70, 1.0, v70
	v_add_f32_e32 v71, 1.0, v71
	v_add_f32_e32 v72, 1.0, v72
	v_add_f32_e32 v73, 1.0, v73
	v_add_f32_e32 v74, 1.0, v74
	v_add_f32_e32 v75, 1.0, v75
	v_rcp_f32_e32 v64, v64
	v_rcp_f32_e32 v65, v65
	v_rcp_f32_e32 v70, v70
	v_rcp_f32_e32 v71, v71
	v_rcp_f32_e32 v72, v72
	v_rcp_f32_e32 v73, v73
	v_rcp_f32_e32 v74, v74
	v_rcp_f32_e32 v75, v75
	v_pk_mul_f32 v[60:61], v[60:61], v[64:65]
	v_pk_mul_f32 v[62:63], v[62:63], v[70:71]
	v_pk_mul_f32 v[52:53], v[52:53], v[72:73]
	v_pk_mul_f32 v[54:55], v[54:55], v[74:75]
	v_pk_mul_f32 v[56:57], v[56:57], v[60:61]
	v_pk_mul_f32 v[58:59], v[58:59], v[62:63]
	v_pk_mul_f32 v[48:49], v[48:49], v[52:53]
	v_pk_mul_f32 v[50:51], v[50:51], v[54:55]
	v_cvt_pk_bf16_f32 v52, v56, v57
	v_cvt_pk_bf16_f32 v53, v58, v59
	v_cvt_pk_bf16_f32 v48, v48, v49
	v_cvt_pk_bf16_f32 v49, v50, v51
	global_store_dwordx2 v[66:67], v[52:53], off
	global_store_dwordx2 v[66:67], v[48:49], off offset:128
	global_load_dwordx4 v[48:51], v[68:69], off
	s_nop 0
	global_load_dwordx4 v[52:55], v[68:69], off offset:32
	global_load_dwordx4 v[56:59], v[68:69], off offset:16
	global_load_dwordx4 v[60:63], v[68:69], off offset:48
	v_add_u32_e32 v64, 0xa0, v146
	v_ashrrev_i32_e32 v65, 31, v64
	v_lshlrev_b64 v[66:67], 6, v[64:65]
	s_waitcnt vmcnt(3)
	v_mov_b32_e32 v68, v48
	s_waitcnt vmcnt(2)
	v_mov_b32_e32 v69, v52
	v_mov_b32_e32 v52, v49
	v_mov_b32_e32 v48, v50
	v_mov_b32_e32 v49, v54
	v_mov_b32_e32 v54, v51
	s_waitcnt vmcnt(1)
	v_mov_b32_e32 v50, v56
	s_waitcnt vmcnt(0)
	v_mov_b32_e32 v51, v60
	v_mov_b32_e32 v60, v57
	v_mov_b32_e32 v56, v58
	v_mov_b32_e32 v57, v62
	v_mov_b32_e32 v62, v59
	v_pk_add_f32 v[52:53], v[68:69], v[52:53]
	v_pk_add_f32 v[48:49], v[48:49], v[54:55]
	v_pk_add_f32 v[50:51], v[50:51], v[60:61]
	v_pk_add_f32 v[54:55], v[56:57], v[62:63]
	v_pk_add_f32 v[48:49], v[52:53], v[48:49]
	v_pk_add_f32 v[50:51], v[50:51], v[54:55]
	v_lshl_add_u64 v[52:53], s[28:29], 0, v[66:67]
	v_pk_add_f32 v[48:49], v[48:49], v[50:51]
	v_mad_i64_i32 v[50:51], s[34:35], v80, s57, v[144:145]
	v_add_f32_e32 v48, v48, v49
	v_fmamk_f32 v48, v48, 0x3a800000, v152
	v_rsq_f32_e32 v48, v48
	s_nop 0
	v_mov_b32_e32 v233, v48
	v_pk_mul_f32 v[44:45], v[44:45], v[48:49] op_sel_hi:[1,0]
	v_pk_mul_f32 v[46:47], v[46:47], v[48:49] op_sel_hi:[1,0]
	v_pk_mul_f32 v[40:41], v[40:41], v[48:49] op_sel_hi:[1,0]
	v_pk_mul_f32 v[42:43], v[42:43], v[48:49] op_sel_hi:[1,0]
	v_pk_mul_f32 v[36:37], v[36:37], v[48:49] op_sel_hi:[1,0]
	v_pk_mul_f32 v[32:33], v[32:33], v[48:49] op_sel_hi:[1,0]
	v_pk_mul_f32 v[38:39], v[38:39], v[48:49] op_sel_hi:[1,0]
	v_pk_mul_f32 v[34:35], v[34:35], v[48:49] op_sel_hi:[1,0]
	v_mul_f32_e32 v48, 0xbfb8aa3b, v44
	v_mul_f32_e32 v49, 0xbfb8aa3b, v45
	v_mul_f32_e32 v54, 0xbfb8aa3b, v46
	v_mul_f32_e32 v55, 0xbfb8aa3b, v47
	v_mul_f32_e32 v56, 0xbfb8aa3b, v36
	v_mul_f32_e32 v57, 0xbfb8aa3b, v37
	v_mul_f32_e32 v58, 0xbfb8aa3b, v38
	v_mul_f32_e32 v59, 0xbfb8aa3b, v39
	v_exp_f32_e32 v48, v48
	v_exp_f32_e32 v49, v49
	v_exp_f32_e32 v54, v54
	v_exp_f32_e32 v55, v55
	v_exp_f32_e32 v56, v56
	v_exp_f32_e32 v57, v57
	v_exp_f32_e32 v58, v58
	v_exp_f32_e32 v59, v59
	v_add_f32_e32 v48, 1.0, v48
	v_add_f32_e32 v49, 1.0, v49
	v_add_f32_e32 v54, 1.0, v54
	v_add_f32_e32 v55, 1.0, v55
	v_add_f32_e32 v56, 1.0, v56
	v_add_f32_e32 v57, 1.0, v57
	v_add_f32_e32 v58, 1.0, v58
	v_add_f32_e32 v59, 1.0, v59
	v_rcp_f32_e32 v48, v48
	v_rcp_f32_e32 v49, v49
	v_rcp_f32_e32 v54, v54
	v_rcp_f32_e32 v55, v55
	v_rcp_f32_e32 v56, v56
	v_rcp_f32_e32 v57, v57
	v_rcp_f32_e32 v58, v58
	v_rcp_f32_e32 v59, v59
	v_pk_mul_f32 v[44:45], v[44:45], v[48:49]
	v_pk_mul_f32 v[46:47], v[46:47], v[54:55]
	v_pk_mul_f32 v[36:37], v[36:37], v[56:57]
	v_pk_mul_f32 v[38:39], v[38:39], v[58:59]
	v_pk_mul_f32 v[40:41], v[40:41], v[44:45]
	v_pk_mul_f32 v[42:43], v[42:43], v[46:47]
	v_pk_mul_f32 v[32:33], v[32:33], v[36:37]
	v_pk_mul_f32 v[34:35], v[34:35], v[38:39]
	v_cvt_pk_bf16_f32 v36, v40, v41
	v_cvt_pk_bf16_f32 v37, v42, v43
	v_cvt_pk_bf16_f32 v32, v32, v33
	v_cvt_pk_bf16_f32 v33, v34, v35
	global_store_dwordx2 v[50:51], v[36:37], off
	global_store_dwordx2 v[50:51], v[32:33], off offset:128
	global_load_dwordx4 v[32:35], v[52:53], off
	s_nop 0
	global_load_dwordx4 v[36:39], v[52:53], off offset:32
	global_load_dwordx4 v[40:43], v[52:53], off offset:16
	global_load_dwordx4 v[44:47], v[52:53], off offset:48
	v_add_u32_e32 v48, 0xb0, v146
	v_ashrrev_i32_e32 v49, 31, v48
	v_lshlrev_b64 v[50:51], 6, v[48:49]
	s_waitcnt vmcnt(3)
	v_mov_b32_e32 v52, v32
	s_waitcnt vmcnt(2)
	v_mov_b32_e32 v53, v36
	v_mov_b32_e32 v36, v33
	v_mov_b32_e32 v32, v34
	v_mov_b32_e32 v33, v38
	v_mov_b32_e32 v38, v35
	s_waitcnt vmcnt(1)
	v_mov_b32_e32 v34, v40
	s_waitcnt vmcnt(0)
	v_mov_b32_e32 v35, v44
	v_mov_b32_e32 v44, v41
	v_mov_b32_e32 v40, v42
	v_mov_b32_e32 v41, v46
	v_mov_b32_e32 v46, v43
	v_pk_add_f32 v[36:37], v[52:53], v[36:37]
	v_pk_add_f32 v[32:33], v[32:33], v[38:39]
	v_pk_add_f32 v[34:35], v[34:35], v[44:45]
	v_pk_add_f32 v[38:39], v[40:41], v[46:47]
	v_pk_add_f32 v[32:33], v[36:37], v[32:33]
	v_pk_add_f32 v[34:35], v[34:35], v[38:39]
	v_lshl_add_u64 v[36:37], s[28:29], 0, v[50:51]
	v_pk_add_f32 v[32:33], v[32:33], v[34:35]
	v_mad_i64_i32 v[34:35], s[34:35], v64, s57, v[144:145]
	v_add_f32_e32 v32, v32, v33
	v_fmamk_f32 v32, v32, 0x3a800000, v152
	v_rsq_f32_e32 v32, v32
	s_nop 0
	v_mov_b32_e32 v234, v32
	v_pk_mul_f32 v[28:29], v[28:29], v[32:33] op_sel_hi:[1,0]
	v_pk_mul_f32 v[30:31], v[30:31], v[32:33] op_sel_hi:[1,0]
	v_pk_mul_f32 v[24:25], v[24:25], v[32:33] op_sel_hi:[1,0]
	v_pk_mul_f32 v[26:27], v[26:27], v[32:33] op_sel_hi:[1,0]
	v_pk_mul_f32 v[20:21], v[20:21], v[32:33] op_sel_hi:[1,0]
	v_pk_mul_f32 v[16:17], v[16:17], v[32:33] op_sel_hi:[1,0]
	v_pk_mul_f32 v[22:23], v[22:23], v[32:33] op_sel_hi:[1,0]
	v_pk_mul_f32 v[18:19], v[18:19], v[32:33] op_sel_hi:[1,0]
	v_mul_f32_e32 v32, 0xbfb8aa3b, v28
	v_mul_f32_e32 v33, 0xbfb8aa3b, v29
	v_mul_f32_e32 v38, 0xbfb8aa3b, v30
	v_mul_f32_e32 v39, 0xbfb8aa3b, v31
	v_mul_f32_e32 v40, 0xbfb8aa3b, v20
	v_mul_f32_e32 v41, 0xbfb8aa3b, v21
	v_mul_f32_e32 v42, 0xbfb8aa3b, v22
	v_mul_f32_e32 v43, 0xbfb8aa3b, v23
	v_exp_f32_e32 v32, v32
	v_exp_f32_e32 v33, v33
	v_exp_f32_e32 v38, v38
	v_exp_f32_e32 v39, v39
	v_exp_f32_e32 v40, v40
	v_exp_f32_e32 v41, v41
	v_exp_f32_e32 v42, v42
	v_exp_f32_e32 v43, v43
	v_add_f32_e32 v32, 1.0, v32
	v_add_f32_e32 v33, 1.0, v33
	v_add_f32_e32 v38, 1.0, v38
	v_add_f32_e32 v39, 1.0, v39
	v_add_f32_e32 v40, 1.0, v40
	v_add_f32_e32 v41, 1.0, v41
	v_add_f32_e32 v42, 1.0, v42
	v_add_f32_e32 v43, 1.0, v43
	v_rcp_f32_e32 v32, v32
	v_rcp_f32_e32 v33, v33
	v_rcp_f32_e32 v38, v38
	v_rcp_f32_e32 v39, v39
	v_rcp_f32_e32 v40, v40
	v_rcp_f32_e32 v41, v41
	v_rcp_f32_e32 v42, v42
	v_rcp_f32_e32 v43, v43
	v_pk_mul_f32 v[28:29], v[28:29], v[32:33]
	v_pk_mul_f32 v[30:31], v[30:31], v[38:39]
	v_pk_mul_f32 v[20:21], v[20:21], v[40:41]
	v_pk_mul_f32 v[22:23], v[22:23], v[42:43]
	v_pk_mul_f32 v[24:25], v[24:25], v[28:29]
	v_pk_mul_f32 v[26:27], v[26:27], v[30:31]
	v_pk_mul_f32 v[16:17], v[16:17], v[20:21]
	v_pk_mul_f32 v[18:19], v[18:19], v[22:23]
	v_cvt_pk_bf16_f32 v20, v24, v25
	v_cvt_pk_bf16_f32 v21, v26, v27
	v_cvt_pk_bf16_f32 v16, v16, v17
	v_cvt_pk_bf16_f32 v17, v18, v19
	global_store_dwordx2 v[34:35], v[20:21], off
	global_store_dwordx2 v[34:35], v[16:17], off offset:128
	global_load_dwordx4 v[16:19], v[36:37], off
	s_nop 0
	global_load_dwordx4 v[20:23], v[36:37], off offset:32
	global_load_dwordx4 v[24:27], v[36:37], off offset:16
	global_load_dwordx4 v[28:31], v[36:37], off offset:48
	s_waitcnt vmcnt(3)
	v_mov_b32_e32 v32, v16
	s_waitcnt vmcnt(2)
	v_mov_b32_e32 v33, v20
	v_mov_b32_e32 v20, v17
	v_mov_b32_e32 v16, v18
	v_mov_b32_e32 v17, v22
	v_mov_b32_e32 v22, v19
	s_waitcnt vmcnt(1)
	v_mov_b32_e32 v18, v24
	s_waitcnt vmcnt(0)
	v_mov_b32_e32 v19, v28
	v_mov_b32_e32 v28, v25
	v_mov_b32_e32 v24, v26
	v_mov_b32_e32 v25, v30
	v_mov_b32_e32 v30, v27
	v_pk_add_f32 v[20:21], v[32:33], v[20:21]
	v_pk_add_f32 v[16:17], v[16:17], v[22:23]
	v_pk_add_f32 v[18:19], v[18:19], v[28:29]
	v_pk_add_f32 v[22:23], v[24:25], v[30:31]
	v_pk_add_f32 v[16:17], v[20:21], v[16:17]
	v_pk_add_f32 v[18:19], v[18:19], v[22:23]
	s_nop 0
	v_pk_add_f32 v[16:17], v[16:17], v[18:19]
	v_mad_i64_i32 v[18:19], s[4:5], v48, s57, v[144:145]
	v_add_f32_e32 v16, v16, v17
	v_fmamk_f32 v16, v16, 0x3a800000, v152
	v_rsq_f32_e32 v16, v16
	s_mov_b64 s[4:5], -1
	v_mov_b32_e32 v235, v16
	v_pk_mul_f32 v[12:13], v[12:13], v[16:17] op_sel_hi:[1,0]
	v_pk_mul_f32 v[14:15], v[14:15], v[16:17] op_sel_hi:[1,0]
	v_pk_mul_f32 v[8:9], v[8:9], v[16:17] op_sel_hi:[1,0]
	v_pk_mul_f32 v[10:11], v[10:11], v[16:17] op_sel_hi:[1,0]
	v_pk_mul_f32 v[4:5], v[4:5], v[16:17] op_sel_hi:[1,0]
	v_pk_mul_f32 v[0:1], v[0:1], v[16:17] op_sel_hi:[1,0]
	v_pk_mul_f32 v[6:7], v[6:7], v[16:17] op_sel_hi:[1,0]
	v_pk_mul_f32 v[2:3], v[2:3], v[16:17] op_sel_hi:[1,0]
	v_mul_f32_e32 v16, 0xbfb8aa3b, v12
	v_mul_f32_e32 v17, 0xbfb8aa3b, v13
	v_mul_f32_e32 v20, 0xbfb8aa3b, v14
	v_mul_f32_e32 v21, 0xbfb8aa3b, v15
	v_mul_f32_e32 v22, 0xbfb8aa3b, v4
	v_mul_f32_e32 v23, 0xbfb8aa3b, v5
	v_mul_f32_e32 v24, 0xbfb8aa3b, v6
	v_mul_f32_e32 v25, 0xbfb8aa3b, v7
	v_exp_f32_e32 v16, v16
	v_exp_f32_e32 v17, v17
	v_exp_f32_e32 v20, v20
	v_exp_f32_e32 v21, v21
	v_exp_f32_e32 v22, v22
	v_exp_f32_e32 v23, v23
	v_exp_f32_e32 v24, v24
	v_exp_f32_e32 v25, v25
	v_add_f32_e32 v16, 1.0, v16
	v_add_f32_e32 v17, 1.0, v17
	v_add_f32_e32 v20, 1.0, v20
	v_add_f32_e32 v21, 1.0, v21
	v_add_f32_e32 v22, 1.0, v22
	v_add_f32_e32 v23, 1.0, v23
	v_add_f32_e32 v24, 1.0, v24
	v_add_f32_e32 v25, 1.0, v25
	v_rcp_f32_e32 v16, v16
	v_rcp_f32_e32 v17, v17
	v_rcp_f32_e32 v20, v20
	v_rcp_f32_e32 v21, v21
	v_rcp_f32_e32 v22, v22
	v_rcp_f32_e32 v23, v23
	v_rcp_f32_e32 v24, v24
	v_rcp_f32_e32 v25, v25
	v_pk_mul_f32 v[12:13], v[12:13], v[16:17]
	v_pk_mul_f32 v[14:15], v[14:15], v[20:21]
	v_pk_mul_f32 v[4:5], v[4:5], v[22:23]
	v_pk_mul_f32 v[6:7], v[6:7], v[24:25]
	v_pk_mul_f32 v[8:9], v[8:9], v[12:13]
	v_pk_mul_f32 v[10:11], v[10:11], v[14:15]
	v_pk_mul_f32 v[0:1], v[0:1], v[4:5]
	v_pk_mul_f32 v[2:3], v[2:3], v[6:7]
	v_cvt_pk_bf16_f32 v4, v8, v9
	v_cvt_pk_bf16_f32 v5, v10, v11
	v_cvt_pk_bf16_f32 v0, v0, v1
	v_cvt_pk_bf16_f32 v1, v2, v3
	global_store_dwordx2 v[18:19], v[4:5], off
	global_store_dwordx2 v[18:19], v[0:1], off offset:128
	s_cbranch_vccnz .LBB0_1609

.Lgu1_fast:
	s_andn2_b64 vcc, exec, s[4:5]
	s_load_dwordx2 s[34:35], s[0:1], 0x138
	s_mov_b32 s94, 0x16000
	s_mov_b32 s95, 0
	s_mov_b32 s96, 0x6e000
	s_mov_b32 s97, 0
	s_lshl_b32 s15, s30, 8
	s_add_i32 s15, s15, s50
	v_and_or_b32 v146, v154, 15, s15
	v_lshrrev_b32_e32 v144, 2, v154
	s_lshl_b32 s15, s58, 7
	s_or_b32 s15, s15, s53
	v_and_or_b32 v144, v144, 12, s15
	v_ashrrev_i32_e32 v145, 31, v144
	s_waitcnt lgkmcnt(0)
	v_lshl_add_u64 v[144:145], v[144:145], 1, s[34:35]
	v_lshl_add_u64 v[144:145], v[144:145], 0, s[12:13]
	v_mad_i64_i32 v[144:145], s[34:35], v146, s57, v[144:145]
	v_pk_mul_f32 v[124:125], v[124:125], v[228:229] op_sel_hi:[1,0]
	v_pk_mul_f32 v[126:127], v[126:127], v[228:229] op_sel_hi:[1,0]
	v_pk_mul_f32 v[120:121], v[120:121], v[228:229] op_sel_hi:[1,0]
	v_pk_mul_f32 v[122:123], v[122:123], v[228:229] op_sel_hi:[1,0]
	v_pk_mul_f32 v[116:117], v[116:117], v[228:229] op_sel_hi:[1,0]
	v_pk_mul_f32 v[118:119], v[118:119], v[228:229] op_sel_hi:[1,0]
	v_pk_mul_f32 v[112:113], v[112:113], v[228:229] op_sel_hi:[1,0]
	v_pk_mul_f32 v[114:115], v[114:115], v[228:229] op_sel_hi:[1,0]
	v_mul_f32_e32 v156, 0xbfb8aa3b, v124
	v_mul_f32_e32 v157, 0xbfb8aa3b, v125
	v_mul_f32_e32 v158, 0xbfb8aa3b, v126
	v_mul_f32_e32 v159, 0xbfb8aa3b, v127
	v_mul_f32_e32 v160, 0xbfb8aa3b, v116
	v_mul_f32_e32 v161, 0xbfb8aa3b, v117
	v_mul_f32_e32 v162, 0xbfb8aa3b, v118
	v_mul_f32_e32 v163, 0xbfb8aa3b, v119
	v_exp_f32_e32 v156, v156
	v_exp_f32_e32 v157, v157
	v_exp_f32_e32 v158, v158
	v_exp_f32_e32 v159, v159
	v_exp_f32_e32 v160, v160
	v_exp_f32_e32 v161, v161
	v_exp_f32_e32 v162, v162
	v_exp_f32_e32 v163, v163
	v_add_f32_e32 v156, 1.0, v156
	v_add_f32_e32 v157, 1.0, v157
	v_add_f32_e32 v158, 1.0, v158
	v_add_f32_e32 v159, 1.0, v159
	v_add_f32_e32 v160, 1.0, v160
	v_add_f32_e32 v161, 1.0, v161
	v_add_f32_e32 v162, 1.0, v162
	v_add_f32_e32 v163, 1.0, v163
	v_rcp_f32_e32 v156, v156
	v_rcp_f32_e32 v157, v157
	v_rcp_f32_e32 v158, v158
	v_rcp_f32_e32 v159, v159
	v_rcp_f32_e32 v160, v160
	v_rcp_f32_e32 v161, v161
	v_rcp_f32_e32 v162, v162
	v_rcp_f32_e32 v163, v163
	v_pk_mul_f32 v[124:125], v[124:125], v[156:157]
	v_pk_mul_f32 v[126:127], v[126:127], v[158:159]
	v_pk_mul_f32 v[116:117], v[116:117], v[160:161]
	v_pk_mul_f32 v[118:119], v[118:119], v[162:163]
	v_pk_mul_f32 v[120:121], v[120:121], v[124:125]
	v_pk_mul_f32 v[122:123], v[122:123], v[126:127]
	v_pk_mul_f32 v[112:113], v[112:113], v[116:117]
	v_pk_mul_f32 v[114:115], v[114:115], v[118:119]
	v_cvt_pk_bf16_f32 v156, v120, v121
	v_cvt_pk_bf16_f32 v157, v122, v123
	v_cvt_pk_bf16_f32 v158, v112, v113
	v_cvt_pk_bf16_f32 v159, v114, v115
	global_store_dwordx2 v[144:145], v[156:157], off
	global_store_dwordx2 v[144:145], v[158:159], off offset:128
	v_lshl_add_u64 v[144:145], v[144:145], 0, s[94:95]
	v_pk_mul_f32 v[108:109], v[108:109], v[228:229] op_sel:[0,1] op_sel_hi:[1,1]
	v_pk_mul_f32 v[110:111], v[110:111], v[228:229] op_sel:[0,1] op_sel_hi:[1,1]
	v_pk_mul_f32 v[104:105], v[104:105], v[228:229] op_sel:[0,1] op_sel_hi:[1,1]
	v_pk_mul_f32 v[106:107], v[106:107], v[228:229] op_sel:[0,1] op_sel_hi:[1,1]
	v_pk_mul_f32 v[100:101], v[100:101], v[228:229] op_sel:[0,1] op_sel_hi:[1,1]
	v_pk_mul_f32 v[102:103], v[102:103], v[228:229] op_sel:[0,1] op_sel_hi:[1,1]
	v_pk_mul_f32 v[96:97], v[96:97], v[228:229] op_sel:[0,1] op_sel_hi:[1,1]
	v_pk_mul_f32 v[98:99], v[98:99], v[228:229] op_sel:[0,1] op_sel_hi:[1,1]
	v_mul_f32_e32 v156, 0xbfb8aa3b, v108
	v_mul_f32_e32 v157, 0xbfb8aa3b, v109
	v_mul_f32_e32 v158, 0xbfb8aa3b, v110
	v_mul_f32_e32 v159, 0xbfb8aa3b, v111
	v_mul_f32_e32 v160, 0xbfb8aa3b, v100
	v_mul_f32_e32 v161, 0xbfb8aa3b, v101
	v_mul_f32_e32 v162, 0xbfb8aa3b, v102
	v_mul_f32_e32 v163, 0xbfb8aa3b, v103
	v_exp_f32_e32 v156, v156
	v_exp_f32_e32 v157, v157
	v_exp_f32_e32 v158, v158
	v_exp_f32_e32 v159, v159
	v_exp_f32_e32 v160, v160
	v_exp_f32_e32 v161, v161
	v_exp_f32_e32 v162, v162
	v_exp_f32_e32 v163, v163
	v_add_f32_e32 v156, 1.0, v156
	v_add_f32_e32 v157, 1.0, v157
	v_add_f32_e32 v158, 1.0, v158
	v_add_f32_e32 v159, 1.0, v159
	v_add_f32_e32 v160, 1.0, v160
	v_add_f32_e32 v161, 1.0, v161
	v_add_f32_e32 v162, 1.0, v162
	v_add_f32_e32 v163, 1.0, v163
	v_rcp_f32_e32 v156, v156
	v_rcp_f32_e32 v157, v157
	v_rcp_f32_e32 v158, v158
	v_rcp_f32_e32 v159, v159
	v_rcp_f32_e32 v160, v160
	v_rcp_f32_e32 v161, v161
	v_rcp_f32_e32 v162, v162
	v_rcp_f32_e32 v163, v163
	v_pk_mul_f32 v[108:109], v[108:109], v[156:157]
	v_pk_mul_f32 v[110:111], v[110:111], v[158:159]
	v_pk_mul_f32 v[100:101], v[100:101], v[160:161]
	v_pk_mul_f32 v[102:103], v[102:103], v[162:163]
	v_pk_mul_f32 v[104:105], v[104:105], v[108:109]
	v_pk_mul_f32 v[106:107], v[106:107], v[110:111]
	v_pk_mul_f32 v[96:97], v[96:97], v[100:101]
	v_pk_mul_f32 v[98:99], v[98:99], v[102:103]
	v_cvt_pk_bf16_f32 v156, v104, v105
	v_cvt_pk_bf16_f32 v157, v106, v107
	v_cvt_pk_bf16_f32 v158, v96, v97
	v_cvt_pk_bf16_f32 v159, v98, v99
	global_store_dwordx2 v[144:145], v[156:157], off
	global_store_dwordx2 v[144:145], v[158:159], off offset:128
	v_lshl_add_u64 v[144:145], v[144:145], 0, s[94:95]
	v_pk_mul_f32 v[92:93], v[92:93], v[230:231] op_sel_hi:[1,0]
	v_pk_mul_f32 v[94:95], v[94:95], v[230:231] op_sel_hi:[1,0]
	v_pk_mul_f32 v[88:89], v[88:89], v[230:231] op_sel_hi:[1,0]
	v_pk_mul_f32 v[90:91], v[90:91], v[230:231] op_sel_hi:[1,0]
	v_pk_mul_f32 v[84:85], v[84:85], v[230:231] op_sel_hi:[1,0]
	v_pk_mul_f32 v[86:87], v[86:87], v[230:231] op_sel_hi:[1,0]
	v_pk_mul_f32 v[80:81], v[80:81], v[230:231] op_sel_hi:[1,0]
	v_pk_mul_f32 v[82:83], v[82:83], v[230:231] op_sel_hi:[1,0]
	v_mul_f32_e32 v156, 0xbfb8aa3b, v92
	v_mul_f32_e32 v157, 0xbfb8aa3b, v93
	v_mul_f32_e32 v158, 0xbfb8aa3b, v94
	v_mul_f32_e32 v159, 0xbfb8aa3b, v95
	v_mul_f32_e32 v160, 0xbfb8aa3b, v84
	v_mul_f32_e32 v161, 0xbfb8aa3b, v85
	v_mul_f32_e32 v162, 0xbfb8aa3b, v86
	v_mul_f32_e32 v163, 0xbfb8aa3b, v87
	v_exp_f32_e32 v156, v156
	v_exp_f32_e32 v157, v157
	v_exp_f32_e32 v158, v158
	v_exp_f32_e32 v159, v159
	v_exp_f32_e32 v160, v160
	v_exp_f32_e32 v161, v161
	v_exp_f32_e32 v162, v162
	v_exp_f32_e32 v163, v163
	v_add_f32_e32 v156, 1.0, v156
	v_add_f32_e32 v157, 1.0, v157
	v_add_f32_e32 v158, 1.0, v158
	v_add_f32_e32 v159, 1.0, v159
	v_add_f32_e32 v160, 1.0, v160
	v_add_f32_e32 v161, 1.0, v161
	v_add_f32_e32 v162, 1.0, v162
	v_add_f32_e32 v163, 1.0, v163
	v_rcp_f32_e32 v156, v156
	v_rcp_f32_e32 v157, v157
	v_rcp_f32_e32 v158, v158
	v_rcp_f32_e32 v159, v159
	v_rcp_f32_e32 v160, v160
	v_rcp_f32_e32 v161, v161
	v_rcp_f32_e32 v162, v162
	v_rcp_f32_e32 v163, v163
	v_pk_mul_f32 v[92:93], v[92:93], v[156:157]
	v_pk_mul_f32 v[94:95], v[94:95], v[158:159]
	v_pk_mul_f32 v[84:85], v[84:85], v[160:161]
	v_pk_mul_f32 v[86:87], v[86:87], v[162:163]
	v_pk_mul_f32 v[88:89], v[88:89], v[92:93]
	v_pk_mul_f32 v[90:91], v[90:91], v[94:95]
	v_pk_mul_f32 v[80:81], v[80:81], v[84:85]
	v_pk_mul_f32 v[82:83], v[82:83], v[86:87]
	v_cvt_pk_bf16_f32 v156, v88, v89
	v_cvt_pk_bf16_f32 v157, v90, v91
	v_cvt_pk_bf16_f32 v158, v80, v81
	v_cvt_pk_bf16_f32 v159, v82, v83
	global_store_dwordx2 v[144:145], v[156:157], off
	global_store_dwordx2 v[144:145], v[158:159], off offset:128
	v_lshl_add_u64 v[144:145], v[144:145], 0, s[94:95]
	v_pk_mul_f32 v[76:77], v[76:77], v[230:231] op_sel:[0,1] op_sel_hi:[1,1]
	v_pk_mul_f32 v[78:79], v[78:79], v[230:231] op_sel:[0,1] op_sel_hi:[1,1]
	v_pk_mul_f32 v[72:73], v[72:73], v[230:231] op_sel:[0,1] op_sel_hi:[1,1]
	v_pk_mul_f32 v[74:75], v[74:75], v[230:231] op_sel:[0,1] op_sel_hi:[1,1]
	v_pk_mul_f32 v[68:69], v[68:69], v[230:231] op_sel:[0,1] op_sel_hi:[1,1]
	v_pk_mul_f32 v[70:71], v[70:71], v[230:231] op_sel:[0,1] op_sel_hi:[1,1]
	v_pk_mul_f32 v[64:65], v[64:65], v[230:231] op_sel:[0,1] op_sel_hi:[1,1]
	v_pk_mul_f32 v[66:67], v[66:67], v[230:231] op_sel:[0,1] op_sel_hi:[1,1]
	v_mul_f32_e32 v156, 0xbfb8aa3b, v76
	v_mul_f32_e32 v157, 0xbfb8aa3b, v77
	v_mul_f32_e32 v158, 0xbfb8aa3b, v78
	v_mul_f32_e32 v159, 0xbfb8aa3b, v79
	v_mul_f32_e32 v160, 0xbfb8aa3b, v68
	v_mul_f32_e32 v161, 0xbfb8aa3b, v69
	v_mul_f32_e32 v162, 0xbfb8aa3b, v70
	v_mul_f32_e32 v163, 0xbfb8aa3b, v71
	v_exp_f32_e32 v156, v156
	v_exp_f32_e32 v157, v157
	v_exp_f32_e32 v158, v158
	v_exp_f32_e32 v159, v159
	v_exp_f32_e32 v160, v160
	v_exp_f32_e32 v161, v161
	v_exp_f32_e32 v162, v162
	v_exp_f32_e32 v163, v163
	v_add_f32_e32 v156, 1.0, v156
	v_add_f32_e32 v157, 1.0, v157
	v_add_f32_e32 v158, 1.0, v158
	v_add_f32_e32 v159, 1.0, v159
	v_add_f32_e32 v160, 1.0, v160
	v_add_f32_e32 v161, 1.0, v161
	v_add_f32_e32 v162, 1.0, v162
	v_add_f32_e32 v163, 1.0, v163
	v_rcp_f32_e32 v156, v156
	v_rcp_f32_e32 v157, v157
	v_rcp_f32_e32 v158, v158
	v_rcp_f32_e32 v159, v159
	v_rcp_f32_e32 v160, v160
	v_rcp_f32_e32 v161, v161
	v_rcp_f32_e32 v162, v162
	v_rcp_f32_e32 v163, v163
	v_pk_mul_f32 v[76:77], v[76:77], v[156:157]
	v_pk_mul_f32 v[78:79], v[78:79], v[158:159]
	v_pk_mul_f32 v[68:69], v[68:69], v[160:161]
	v_pk_mul_f32 v[70:71], v[70:71], v[162:163]
	v_pk_mul_f32 v[72:73], v[72:73], v[76:77]
	v_pk_mul_f32 v[74:75], v[74:75], v[78:79]
	v_pk_mul_f32 v[64:65], v[64:65], v[68:69]
	v_pk_mul_f32 v[66:67], v[66:67], v[70:71]
	v_cvt_pk_bf16_f32 v156, v72, v73
	v_cvt_pk_bf16_f32 v157, v74, v75
	v_cvt_pk_bf16_f32 v158, v64, v65
	v_cvt_pk_bf16_f32 v159, v66, v67
	global_store_dwordx2 v[144:145], v[156:157], off
	global_store_dwordx2 v[144:145], v[158:159], off offset:128
	v_lshl_add_u64 v[144:145], v[144:145], 0, s[96:97]
	v_pk_mul_f32 v[60:61], v[60:61], v[232:233] op_sel_hi:[1,0]
	v_pk_mul_f32 v[62:63], v[62:63], v[232:233] op_sel_hi:[1,0]
	v_pk_mul_f32 v[56:57], v[56:57], v[232:233] op_sel_hi:[1,0]
	v_pk_mul_f32 v[58:59], v[58:59], v[232:233] op_sel_hi:[1,0]
	v_pk_mul_f32 v[52:53], v[52:53], v[232:233] op_sel_hi:[1,0]
	v_pk_mul_f32 v[54:55], v[54:55], v[232:233] op_sel_hi:[1,0]
	v_pk_mul_f32 v[48:49], v[48:49], v[232:233] op_sel_hi:[1,0]
	v_pk_mul_f32 v[50:51], v[50:51], v[232:233] op_sel_hi:[1,0]
	v_mul_f32_e32 v156, 0xbfb8aa3b, v60
	v_mul_f32_e32 v157, 0xbfb8aa3b, v61
	v_mul_f32_e32 v158, 0xbfb8aa3b, v62
	v_mul_f32_e32 v159, 0xbfb8aa3b, v63
	v_mul_f32_e32 v160, 0xbfb8aa3b, v52
	v_mul_f32_e32 v161, 0xbfb8aa3b, v53
	v_mul_f32_e32 v162, 0xbfb8aa3b, v54
	v_mul_f32_e32 v163, 0xbfb8aa3b, v55
	v_exp_f32_e32 v156, v156
	v_exp_f32_e32 v157, v157
	v_exp_f32_e32 v158, v158
	v_exp_f32_e32 v159, v159
	v_exp_f32_e32 v160, v160
	v_exp_f32_e32 v161, v161
	v_exp_f32_e32 v162, v162
	v_exp_f32_e32 v163, v163
	v_add_f32_e32 v156, 1.0, v156
	v_add_f32_e32 v157, 1.0, v157
	v_add_f32_e32 v158, 1.0, v158
	v_add_f32_e32 v159, 1.0, v159
	v_add_f32_e32 v160, 1.0, v160
	v_add_f32_e32 v161, 1.0, v161
	v_add_f32_e32 v162, 1.0, v162
	v_add_f32_e32 v163, 1.0, v163
	v_rcp_f32_e32 v156, v156
	v_rcp_f32_e32 v157, v157
	v_rcp_f32_e32 v158, v158
	v_rcp_f32_e32 v159, v159
	v_rcp_f32_e32 v160, v160
	v_rcp_f32_e32 v161, v161
	v_rcp_f32_e32 v162, v162
	v_rcp_f32_e32 v163, v163
	v_pk_mul_f32 v[60:61], v[60:61], v[156:157]
	v_pk_mul_f32 v[62:63], v[62:63], v[158:159]
	v_pk_mul_f32 v[52:53], v[52:53], v[160:161]
	v_pk_mul_f32 v[54:55], v[54:55], v[162:163]
	v_pk_mul_f32 v[56:57], v[56:57], v[60:61]
	v_pk_mul_f32 v[58:59], v[58:59], v[62:63]
	v_pk_mul_f32 v[48:49], v[48:49], v[52:53]
	v_pk_mul_f32 v[50:51], v[50:51], v[54:55]
	v_cvt_pk_bf16_f32 v156, v56, v57
	v_cvt_pk_bf16_f32 v157, v58, v59
	v_cvt_pk_bf16_f32 v158, v48, v49
	v_cvt_pk_bf16_f32 v159, v50, v51
	global_store_dwordx2 v[144:145], v[156:157], off
	global_store_dwordx2 v[144:145], v[158:159], off offset:128
	v_lshl_add_u64 v[144:145], v[144:145], 0, s[94:95]
	v_pk_mul_f32 v[44:45], v[44:45], v[232:233] op_sel:[0,1] op_sel_hi:[1,1]
	v_pk_mul_f32 v[46:47], v[46:47], v[232:233] op_sel:[0,1] op_sel_hi:[1,1]
	v_pk_mul_f32 v[40:41], v[40:41], v[232:233] op_sel:[0,1] op_sel_hi:[1,1]
	v_pk_mul_f32 v[42:43], v[42:43], v[232:233] op_sel:[0,1] op_sel_hi:[1,1]
	v_pk_mul_f32 v[36:37], v[36:37], v[232:233] op_sel:[0,1] op_sel_hi:[1,1]
	v_pk_mul_f32 v[38:39], v[38:39], v[232:233] op_sel:[0,1] op_sel_hi:[1,1]
	v_pk_mul_f32 v[32:33], v[32:33], v[232:233] op_sel:[0,1] op_sel_hi:[1,1]
	v_pk_mul_f32 v[34:35], v[34:35], v[232:233] op_sel:[0,1] op_sel_hi:[1,1]
	v_mul_f32_e32 v156, 0xbfb8aa3b, v44
	v_mul_f32_e32 v157, 0xbfb8aa3b, v45
	v_mul_f32_e32 v158, 0xbfb8aa3b, v46
	v_mul_f32_e32 v159, 0xbfb8aa3b, v47
	v_mul_f32_e32 v160, 0xbfb8aa3b, v36
	v_mul_f32_e32 v161, 0xbfb8aa3b, v37
	v_mul_f32_e32 v162, 0xbfb8aa3b, v38
	v_mul_f32_e32 v163, 0xbfb8aa3b, v39
	v_exp_f32_e32 v156, v156
	v_exp_f32_e32 v157, v157
	v_exp_f32_e32 v158, v158
	v_exp_f32_e32 v159, v159
	v_exp_f32_e32 v160, v160
	v_exp_f32_e32 v161, v161
	v_exp_f32_e32 v162, v162
	v_exp_f32_e32 v163, v163
	v_add_f32_e32 v156, 1.0, v156
	v_add_f32_e32 v157, 1.0, v157
	v_add_f32_e32 v158, 1.0, v158
	v_add_f32_e32 v159, 1.0, v159
	v_add_f32_e32 v160, 1.0, v160
	v_add_f32_e32 v161, 1.0, v161
	v_add_f32_e32 v162, 1.0, v162
	v_add_f32_e32 v163, 1.0, v163
	v_rcp_f32_e32 v156, v156
	v_rcp_f32_e32 v157, v157
	v_rcp_f32_e32 v158, v158
	v_rcp_f32_e32 v159, v159
	v_rcp_f32_e32 v160, v160
	v_rcp_f32_e32 v161, v161
	v_rcp_f32_e32 v162, v162
	v_rcp_f32_e32 v163, v163
	v_pk_mul_f32 v[44:45], v[44:45], v[156:157]
	v_pk_mul_f32 v[46:47], v[46:47], v[158:159]
	v_pk_mul_f32 v[36:37], v[36:37], v[160:161]
	v_pk_mul_f32 v[38:39], v[38:39], v[162:163]
	v_pk_mul_f32 v[40:41], v[40:41], v[44:45]
	v_pk_mul_f32 v[42:43], v[42:43], v[46:47]
	v_pk_mul_f32 v[32:33], v[32:33], v[36:37]
	v_pk_mul_f32 v[34:35], v[34:35], v[38:39]
	v_cvt_pk_bf16_f32 v156, v40, v41
	v_cvt_pk_bf16_f32 v157, v42, v43
	v_cvt_pk_bf16_f32 v158, v32, v33
	v_cvt_pk_bf16_f32 v159, v34, v35
	global_store_dwordx2 v[144:145], v[156:157], off
	global_store_dwordx2 v[144:145], v[158:159], off offset:128
	v_lshl_add_u64 v[144:145], v[144:145], 0, s[94:95]
	v_pk_mul_f32 v[28:29], v[28:29], v[234:235] op_sel_hi:[1,0]
	v_pk_mul_f32 v[30:31], v[30:31], v[234:235] op_sel_hi:[1,0]
	v_pk_mul_f32 v[24:25], v[24:25], v[234:235] op_sel_hi:[1,0]
	v_pk_mul_f32 v[26:27], v[26:27], v[234:235] op_sel_hi:[1,0]
	v_pk_mul_f32 v[20:21], v[20:21], v[234:235] op_sel_hi:[1,0]
	v_pk_mul_f32 v[22:23], v[22:23], v[234:235] op_sel_hi:[1,0]
	v_pk_mul_f32 v[16:17], v[16:17], v[234:235] op_sel_hi:[1,0]
	v_pk_mul_f32 v[18:19], v[18:19], v[234:235] op_sel_hi:[1,0]
	v_mul_f32_e32 v156, 0xbfb8aa3b, v28
	v_mul_f32_e32 v157, 0xbfb8aa3b, v29
	v_mul_f32_e32 v158, 0xbfb8aa3b, v30
	v_mul_f32_e32 v159, 0xbfb8aa3b, v31
	v_mul_f32_e32 v160, 0xbfb8aa3b, v20
	v_mul_f32_e32 v161, 0xbfb8aa3b, v21
	v_mul_f32_e32 v162, 0xbfb8aa3b, v22
	v_mul_f32_e32 v163, 0xbfb8aa3b, v23
	v_exp_f32_e32 v156, v156
	v_exp_f32_e32 v157, v157
	v_exp_f32_e32 v158, v158
	v_exp_f32_e32 v159, v159
	v_exp_f32_e32 v160, v160
	v_exp_f32_e32 v161, v161
	v_exp_f32_e32 v162, v162
	v_exp_f32_e32 v163, v163
	v_add_f32_e32 v156, 1.0, v156
	v_add_f32_e32 v157, 1.0, v157
	v_add_f32_e32 v158, 1.0, v158
	v_add_f32_e32 v159, 1.0, v159
	v_add_f32_e32 v160, 1.0, v160
	v_add_f32_e32 v161, 1.0, v161
	v_add_f32_e32 v162, 1.0, v162
	v_add_f32_e32 v163, 1.0, v163
	v_rcp_f32_e32 v156, v156
	v_rcp_f32_e32 v157, v157
	v_rcp_f32_e32 v158, v158
	v_rcp_f32_e32 v159, v159
	v_rcp_f32_e32 v160, v160
	v_rcp_f32_e32 v161, v161
	v_rcp_f32_e32 v162, v162
	v_rcp_f32_e32 v163, v163
	v_pk_mul_f32 v[28:29], v[28:29], v[156:157]
	v_pk_mul_f32 v[30:31], v[30:31], v[158:159]
	v_pk_mul_f32 v[20:21], v[20:21], v[160:161]
	v_pk_mul_f32 v[22:23], v[22:23], v[162:163]
	v_pk_mul_f32 v[24:25], v[24:25], v[28:29]
	v_pk_mul_f32 v[26:27], v[26:27], v[30:31]
	v_pk_mul_f32 v[16:17], v[16:17], v[20:21]
	v_pk_mul_f32 v[18:19], v[18:19], v[22:23]
	v_cvt_pk_bf16_f32 v156, v24, v25
	v_cvt_pk_bf16_f32 v157, v26, v27
	v_cvt_pk_bf16_f32 v158, v16, v17
	v_cvt_pk_bf16_f32 v159, v18, v19
	global_store_dwordx2 v[144:145], v[156:157], off
	global_store_dwordx2 v[144:145], v[158:159], off offset:128
	v_lshl_add_u64 v[144:145], v[144:145], 0, s[94:95]
	v_pk_mul_f32 v[12:13], v[12:13], v[234:235] op_sel:[0,1] op_sel_hi:[1,1]
	v_pk_mul_f32 v[14:15], v[14:15], v[234:235] op_sel:[0,1] op_sel_hi:[1,1]
	v_pk_mul_f32 v[8:9], v[8:9], v[234:235] op_sel:[0,1] op_sel_hi:[1,1]
	v_pk_mul_f32 v[10:11], v[10:11], v[234:235] op_sel:[0,1] op_sel_hi:[1,1]
	v_pk_mul_f32 v[4:5], v[4:5], v[234:235] op_sel:[0,1] op_sel_hi:[1,1]
	v_pk_mul_f32 v[6:7], v[6:7], v[234:235] op_sel:[0,1] op_sel_hi:[1,1]
	v_pk_mul_f32 v[0:1], v[0:1], v[234:235] op_sel:[0,1] op_sel_hi:[1,1]
	v_pk_mul_f32 v[2:3], v[2:3], v[234:235] op_sel:[0,1] op_sel_hi:[1,1]
	v_mul_f32_e32 v156, 0xbfb8aa3b, v12
	v_mul_f32_e32 v157, 0xbfb8aa3b, v13
	v_mul_f32_e32 v158, 0xbfb8aa3b, v14
	v_mul_f32_e32 v159, 0xbfb8aa3b, v15
	v_mul_f32_e32 v160, 0xbfb8aa3b, v4
	v_mul_f32_e32 v161, 0xbfb8aa3b, v5
	v_mul_f32_e32 v162, 0xbfb8aa3b, v6
	v_mul_f32_e32 v163, 0xbfb8aa3b, v7
	v_exp_f32_e32 v156, v156
	v_exp_f32_e32 v157, v157
	v_exp_f32_e32 v158, v158
	v_exp_f32_e32 v159, v159
	v_exp_f32_e32 v160, v160
	v_exp_f32_e32 v161, v161
	v_exp_f32_e32 v162, v162
	v_exp_f32_e32 v163, v163
	v_add_f32_e32 v156, 1.0, v156
	v_add_f32_e32 v157, 1.0, v157
	v_add_f32_e32 v158, 1.0, v158
	v_add_f32_e32 v159, 1.0, v159
	v_add_f32_e32 v160, 1.0, v160
	v_add_f32_e32 v161, 1.0, v161
	v_add_f32_e32 v162, 1.0, v162
	v_add_f32_e32 v163, 1.0, v163
	v_rcp_f32_e32 v156, v156
	v_rcp_f32_e32 v157, v157
	v_rcp_f32_e32 v158, v158
	v_rcp_f32_e32 v159, v159
	v_rcp_f32_e32 v160, v160
	v_rcp_f32_e32 v161, v161
	v_rcp_f32_e32 v162, v162
	v_rcp_f32_e32 v163, v163
	v_pk_mul_f32 v[12:13], v[12:13], v[156:157]
	v_pk_mul_f32 v[14:15], v[14:15], v[158:159]
	v_pk_mul_f32 v[4:5], v[4:5], v[160:161]
	v_pk_mul_f32 v[6:7], v[6:7], v[162:163]
	v_pk_mul_f32 v[8:9], v[8:9], v[12:13]
	v_pk_mul_f32 v[10:11], v[10:11], v[14:15]
	v_pk_mul_f32 v[0:1], v[0:1], v[4:5]
	v_pk_mul_f32 v[2:3], v[2:3], v[6:7]
	v_cvt_pk_bf16_f32 v156, v8, v9
	v_cvt_pk_bf16_f32 v157, v10, v11
	v_cvt_pk_bf16_f32 v158, v0, v1
	v_cvt_pk_bf16_f32 v159, v2, v3
	global_store_dwordx2 v[144:145], v[156:157], off
	global_store_dwordx2 v[144:145], v[158:159], off offset:128
	s_mov_b64 s[4:5], -1
	s_cbranch_vccnz .LBB0_1609
	s_branch .Lgu1_tail

	.amdhsa_kernel _Z9trunk_fwd6Params
		.amdhsa_group_segment_fixed_size 0
		.amdhsa_private_segment_fixed_size 0
		.amdhsa_kernarg_size 576
		.amdhsa_user_sgpr_count 2
		.amdhsa_user_sgpr_dispatch_ptr 0
		.amdhsa_user_sgpr_queue_ptr 0
		.amdhsa_user_sgpr_kernarg_segment_ptr 1
		.amdhsa_user_sgpr_dispatch_id 0
		.amdhsa_user_sgpr_kernarg_preload_length 0
		.amdhsa_user_sgpr_kernarg_preload_offset 0
		.amdhsa_user_sgpr_private_segment_size 0
		.amdhsa_uses_dynamic_stack 0
		.amdhsa_enable_private_segment 0
		.amdhsa_system_sgpr_workgroup_id_x 1
		.amdhsa_system_sgpr_workgroup_id_y 0
		.amdhsa_system_sgpr_workgroup_id_z 0
		.amdhsa_system_sgpr_workgroup_info 0
		.amdhsa_system_vgpr_workitem_id 2
		.amdhsa_next_free_vgpr 256
		.amdhsa_next_free_sgpr 102
		.amdhsa_accum_offset 256
		.amdhsa_reserve_vcc 1
		.amdhsa_float_round_mode_32 0
		.amdhsa_float_round_mode_16_64 0
		.amdhsa_float_denorm_mode_32 3
		.amdhsa_float_denorm_mode_16_64 3
		.amdhsa_dx10_clamp 1
		.amdhsa_ieee_mode 1
		.amdhsa_fp16_overflow 0
		.amdhsa_tg_split 0
		.amdhsa_exception_fp_ieee_invalid_op 0
		.amdhsa_exception_fp_denorm_src 0
		.amdhsa_exception_fp_ieee_div_zero 0
		.amdhsa_exception_fp_ieee_overflow 0
		.amdhsa_exception_fp_ieee_underflow 0
		.amdhsa_exception_fp_ieee_inexact 0
		.amdhsa_exception_int_div_zero 0
	.end_amdhsa_kernel

amdhsa.kernels:
  - .agpr_count:     0
    .args:
      - .offset:         0
        .size:           320
        .value_kind:     by_value
      - .offset:         320
        .size:           4
        .value_kind:     hidden_block_count_x
      - .offset:         324
        .size:           4
        .value_kind:     hidden_block_count_y
      - .offset:         328
        .size:           4
        .value_kind:     hidden_block_count_z
      - .offset:         332
        .size:           2
        .value_kind:     hidden_group_size_x
      - .offset:         334
        .size:           2
        .value_kind:     hidden_group_size_y
      - .offset:         336
        .size:           2
        .value_kind:     hidden_group_size_z
      - .offset:         338
        .size:           2
        .value_kind:     hidden_remainder_x
      - .offset:         340
        .size:           2
        .value_kind:     hidden_remainder_y
      - .offset:         342
        .size:           2
        .value_kind:     hidden_remainder_z
      - .offset:         360
        .size:           8
        .value_kind:     hidden_global_offset_x
      - .offset:         368
        .size:           8
        .value_kind:     hidden_global_offset_y
      - .offset:         376
        .size:           8
        .value_kind:     hidden_global_offset_z
      - .offset:         384
        .size:           2
        .value_kind:     hidden_grid_dims
      - .offset:         408
        .size:           8
        .value_kind:     hidden_multigrid_sync_arg
      - .offset:         440
        .size:           4
        .value_kind:     hidden_dynamic_lds_size
    .group_segment_fixed_size: 0
    .kernarg_segment_align: 8
    .kernarg_segment_size: 576
    .language:       OpenCL C
    .language_version:
      - 2
      - 0
    .max_flat_workgroup_size: 512
    .name:           _Z9trunk_fwd6Params
    .private_segment_fixed_size: 0
    .sgpr_count:     108
    .sgpr_spill_count: 0
    .symbol:         _Z9trunk_fwd6Params.kd
    .uniform_work_group_size: 1
    .uses_dynamic_stack: false
    .vgpr_count:     256
    .vgpr_spill_count: 0
    .wavefront_size: 64
